# NSA rows remapped to 4 tokens x 4 heads per column group (fewer selected tile steps), selected loop with 4-tile rounds and one shared tile body, gMLP LayerNorm statistics with all rows in flight + DPP
# speedup vs baseline: 1.0271x; 1.0271x over previous
; #define LAS __attribute__((address_space(3)))
; __device__ __forceinline__ int opaque_tid() { int t = threadIdx.x; asm volatile("" : "+v"(t)); return t; }
; __device__ __forceinline__ void nsa_unit(LAS unsigned char* lds, const Ctx& P, int l, int b, int hkv, int tb) {
;     ...
;     const int tid = opaque_tid(), wid = tid >> 6, lane = tid & 63, c = lane & 15, i = lane >> 4, g = wid & 3, th = wid >> 2, hq = hkv * 4 + g;
;     const LAS float* lut = (const LAS float*)(lds + NSA_LUT) + g * 1024;
;     const int t0 = tb * 64, qb = tb;
;     int tq[2]; size_t tok[2];
; #pragma unroll
;     for (int sb = 0; sb < 2; ++sb) { tq[sb] = t0 + 32 * th + 16 * sb + c; tok[sb] = (size_t)b * SEQ + tq[sb]; }
;     bf16x8 qf[2][2];
; #pragma unroll
;     for (int sb = 0; sb < 2; ++sb)
; #pragma unroll
;         for (int ks = 0; ks < 2; ++ks) qf[sb][ks] = load_q_scaled(H + tok[sb] * LDH + C_Q + hq * 64 + ks * 32 + 8 * i, 0.125f);
; __global__ void __launch_bounds__(512, 2) fwd_megakernel(Params PK) {
;     ...
;             for (int u = bid; u < 1024; u += G) { const int v = u & 255, k = u >> 8, x = v >> 4, b = (v >> 2) & 3, hkv = v & 3, tb = (k & 1) ? 16 * k + 15 - x : 16 * k + x;
.LBB0_199:
	s_ashr_i32 s4, s6, 4
	s_bfe_u32 s0, s6, 0x40004
	s_and_b32 s5, s4, -16
	s_or_b32 s4, s4, 15
	s_bfe_u32 s61, s6, 0x20002
	s_and_b32 s1, s6, 0x100
	s_sub_i32 s4, s4, s0
	s_or_b32 s0, s5, s0
	s_cmp_eq_u32 s1, 0
	s_cselect_b32 s54, s0, s4
	s_lshl_b32 s0, s61, 16
	s_or_b32 s44, s0, s17
	s_lshl_b64 s[0:1], s[44:45], 1
	v_readlane_b32 s4, v255, 52
	v_mov_b32_e32 v154, v234
	s_add_u32 s0, s4, s0
	v_readlane_b32 s4, v255, 53
	s_addc_u32 s1, s4, s1
	v_ashrrev_i32_e32 v144, 3, v154
	s_lshl_b32 s55, s54, 6
	v_and_b32_e32 v101, 0xfffffff8, v144
	v_and_b32_e32 v97, 15, v154
	v_add_u32_e32 v0, s55, v101
	v_lshrrev_b32_e32 v131, 2, v97
	v_or_b32_e32 v130, v0, v131
	v_ashrrev_i32_e32 v155, 6, v154
	s_lshl_b32 s58, s61, 12
	s_mov_b32 s59, s45
	v_ashrrev_i32_e32 v131, 31, v130
	v_and_b32_e32 v24, 3, v154
	v_lshl_add_u64 v[126:127], v[130:131], 0, s[58:59]
	v_mov_b64_e32 v[10:11], s[10:11]
	v_lshl_or_b32 v96, s60, 2, v24
	v_mad_u64_u32 v[128:129], s[4:5], v126, s42, v[10:11]
	v_mad_i32_i24 v129, v127, s42, v129
	v_lshlrev_b32_e32 v0, 7, v96
	v_or_b32_e32 v98, 4, v130
	v_lshl_add_u64 v[2:3], v[128:129], 0, v[0:1]
	v_and_b32_e32 v18, 48, v154
	v_mov_b32_e32 v19, v1
	v_ashrrev_i32_e32 v99, 31, v98
	v_lshl_add_u64 v[6:7], v[2:3], 0, v[18:19]
	v_lshl_add_u64 v[120:121], v[98:99], 0, s[58:59]
	v_add_co_u32_e32 v2, vcc, s85, v6
	v_mad_u64_u32 v[122:123], s[4:5], v120, s42, v[10:11]
	s_nop 0
	v_addc_co_u32_e32 v3, vcc, 0, v7, vcc
	v_mad_i32_i24 v123, v121, s42, v123
	global_load_dwordx4 v[2:5], v[2:3], off offset:2048
	v_lshl_add_u64 v[10:11], v[122:123], 0, v[0:1]
	v_lshl_add_u64 v[6:7], v[6:7], 0, s[78:79]
	v_lshl_add_u64 v[14:15], v[10:11], 0, v[18:19]
	global_load_dwordx4 v[6:9], v[6:7], off offset:64
	v_add_co_u32_e32 v10, vcc, s85, v14
	v_readlane_b32 s4, v253, 15
	s_nop 0
	v_addc_co_u32_e32 v11, vcc, 0, v15, vcc
	global_load_dwordx4 v[10:13], v[10:11], off offset:2048
	v_lshl_add_u64 v[14:15], v[14:15], 0, s[78:79]
	global_load_dwordx4 v[14:17], v[14:15], off offset:64
	v_and_b32_e32 v99, 63, v154
	s_movk_i32 s18, 0x90
	v_bfe_u32 v103, v154, 4, 2
	v_and_b32_e32 v94, -8, v144
	v_cmp_eq_u32_e64 s[12:13], 3, v103
	v_ashrrev_i32_e32 v95, 31, v94
	v_lshlrev_b32_e32 v153, 12, v24
	v_add_u32_e32 v150, 0, v18
	v_lshlrev_b32_e32 v30, 3, v103
	v_or_b32_e32 v26, 4, v103
	v_or_b32_e32 v27, 8, v103
	v_or_b32_e32 v28, 12, v103
	v_add_u32_e32 v151, 0, v30
	v_mul_lo_u32 v147, v94, s18
	v_mad_u32_u24 v152, v97, s18, v151
	s_mov_b64 s[66:67], 0x86000
	v_or_b32_e32 v32, s71, v96
	s_mov_b32 s44, 0
	v_lshlrev_b32_e32 v102, 6, v96
	v_add_u32_e32 v131, 0, v153
	v_lshl_add_u32 v145, v99, 1, 0
	v_mul_u32_u24_e32 v148, 0x90, v97
	v_lshlrev_b32_e32 v157, 6, v103
	v_lshlrev_b32_e32 v136, 1, v30
	v_lshlrev_b32_e32 v158, 2, v32
	s_waitcnt vmcnt(0)
	v_lshlrev_b32_e32 v0, 16, v2
	v_and_b32_e32 v2, 0xffff0000, v2
	v_mul_f32_e32 v0, 0x3e000000, v0
	v_mul_f32_e32 v2, 0x3e000000, v2
	v_cvt_pk_bf16_f32 v2, v0, v2
	s_waitcnt vmcnt(2)
	v_lshlrev_b32_e32 v0, 16, v9
	v_and_b32_e32 v9, 0xffff0000, v9
	v_mul_f32_e32 v0, 0x3e000000, v0
	v_mul_f32_e32 v9, 0x3e000000, v9
	v_cvt_pk_bf16_f32 v9, v0, v9
	s_waitcnt vmcnt(1)
	v_lshlrev_b32_e32 v0, 16, v10
	v_and_b32_e32 v10, 0xffff0000, v10
	v_mul_f32_e32 v0, 0x3e000000, v0
	v_mul_f32_e32 v10, 0x3e000000, v10
	v_cvt_pk_bf16_f32 v10, v0, v10
	v_lshlrev_b32_e32 v0, 16, v11
	v_and_b32_e32 v11, 0xffff0000, v11
	v_mul_f32_e32 v0, 0x3e000000, v0
	v_mul_f32_e32 v11, 0x3e000000, v11
	v_cvt_pk_bf16_f32 v11, v0, v11
	v_lshlrev_b32_e32 v0, 16, v12
	v_and_b32_e32 v12, 0xffff0000, v12
	v_mul_f32_e32 v0, 0x3e000000, v0
	v_mul_f32_e32 v12, 0x3e000000, v12
	v_cvt_pk_bf16_f32 v12, v0, v12
	v_lshlrev_b32_e32 v0, 16, v13
	v_and_b32_e32 v13, 0xffff0000, v13
	v_mul_f32_e32 v0, 0x3e000000, v0
	v_mul_f32_e32 v13, 0x3e000000, v13
	v_cvt_pk_bf16_f32 v13, v0, v13
	s_waitcnt vmcnt(0)
; __device__ __forceinline__ void nsa_unit(LAS unsigned char* lds, const Ctx& P, int l, int b, int hkv, int tb) {
;     ...
;     for (int sb = 0; sb < 2; ++sb) { tq[sb] = t0 + 32 * th + 16 * sb + c; tok[sb] = (size_t)b * SEQ + tq[sb]; }
;     bf16x8 qf[2][2];
; #pragma unroll
;     for (int sb = 0; sb < 2; ++sb)
; #pragma unroll
;         for (int ks = 0; ks < 2; ++ks) qf[sb][ks] = load_q_scaled(H + tok[sb] * LDH + C_Q + hq * 64 + ks * 32 + 8 * i, 0.125f);
;     f32x4* park = (f32x4*)(P.ws + WS_PARK) + ((size_t)(blockIdx.x * 8 + wid) * 8) * 64 + lane;
;     float alpha; bf16x8 pf, pf1;
;     auto load2 = [&](const bf16_t* ksrc, const bf16_t* vsrc, size_t ld, int p0a, int p0b, bool hasb, int pmax) {
;         TileRegs ra, rb; tile_issue(ra, tid, ksrc, vsrc, ld, p0a, pmax); if (hasb) tile_issue(rb, tid, ksrc, vsrc, ld, p0b, pmax);
;         tile_commit(ra, tid, KV, KV + 4608); if (hasb) tile_commit(rb, tid, KV + 9216, KV + 9216 + 4608); };
; #pragma unroll 1
;     for (int sb = 0; sb < 2; ++sb) {
;         f32x4 o[4], oi[4]; float m = NEGBIG, lsum = 0.f;
; #pragma unroll
;         for (int dt = 0; dt < 4; ++dt) { o[dt] = (f32x4){0.f, 0.f, 0.f, 0.f}; oi[dt] = (f32x4){0.f, 0.f, 0.f, 0.f}; }
;         bf16x8 ovA[2], ovB[2];
; #pragma unroll
;         for (int st = 0; st < 2; ++st)
; #pragma unroll
;             for (int j = 0; j < 8; ++j) { const int nl = 32 * st + (j < 4 ? 4 * i + j : 16 + 4 * i + (j - 4));
;                 float a = 0.f; if ((nl >> 2) == c) a = ((nl & 3) == 3) ? 0.5f : 1.0f; else if ((nl >> 2) == c - 1 && (nl & 3) == 3) a = 0.5f;
;                 const float bb = (c == 0 && nl == 63) ? 0.5f : 0.f;
;                 ovA[st][j] = (short)(__float_as_uint(a) >> 16); ovB[st][j] = (short)(__float_as_uint(bb) >> 16); }
;         const int ntile = ((t0 >> 4) + 2) / 64 + 1;
;         const int tqs = t0 + 32 * th + 16 * sb + c;
;         bf16x8 qs[2];
; #pragma unroll
;         for (int ks = 0; ks < 2; ++ks) qs[ks] = load_q_scaled(H + ((size_t)b * SEQ + tqs) * LDH + C_Q + hq * 64 + ks * 32 + 8 * i, 0.125f);
	v_lshlrev_b32_e32 v0, 16, v14
	v_and_b32_e32 v14, 0xffff0000, v14
	v_mul_f32_e32 v0, 0x3e000000, v0
	v_mul_f32_e32 v14, 0x3e000000, v14
	v_cvt_pk_bf16_f32 v14, v0, v14
	v_lshlrev_b32_e32 v0, 16, v15
	v_and_b32_e32 v15, 0xffff0000, v15
	v_mul_f32_e32 v0, 0x3e000000, v0
	v_mul_f32_e32 v15, 0x3e000000, v15
	v_cvt_pk_bf16_f32 v15, v0, v15
	v_lshlrev_b32_e32 v0, 16, v16
	v_and_b32_e32 v16, 0xffff0000, v16
	v_mul_f32_e32 v0, 0x3e000000, v0
	v_mul_f32_e32 v16, 0x3e000000, v16
	v_cvt_pk_bf16_f32 v16, v0, v16
	v_lshlrev_b32_e32 v0, 16, v17
	v_and_b32_e32 v17, 0xffff0000, v17
	v_lshlrev_b32_e32 v20, 16, v4
	v_and_b32_e32 v4, 0xffff0000, v4
	v_lshlrev_b32_e32 v21, 16, v5
	v_and_b32_e32 v5, 0xffff0000, v5
	v_mul_f32_e32 v0, 0x3e000000, v0
	v_mul_f32_e32 v17, 0x3e000000, v17
	v_mul_f32_e32 v20, 0x3e000000, v20
	v_mul_f32_e32 v4, 0x3e000000, v4
	v_mul_f32_e32 v21, 0x3e000000, v21
	v_mul_f32_e32 v5, 0x3e000000, v5
	v_cvt_pk_bf16_f32 v17, v0, v17
	v_add_u32_e32 v0, s4, v155
	v_readlane_b32 s4, v255, 54
	v_cvt_pk_bf16_f32 v4, v20, v4
	v_cvt_pk_bf16_f32 v5, v21, v5
	v_lshlrev_b64 v[20:21], 13, v[0:1]
	v_readlane_b32 s5, v255, 55
	v_lshlrev_b32_e32 v0, 4, v99
	v_lshlrev_b32_e32 v25, 16, v8
	v_lshl_add_u64 v[20:21], s[4:5], 0, v[20:21]
	v_and_b32_e32 v8, 0xffff0000, v8
	v_lshl_add_u64 v[124:125], v[20:21], 0, v[0:1]
	v_lshlrev_b32_e32 v0, 3, v154
	v_lshlrev_b32_e32 v22, 16, v6
	v_and_b32_e32 v6, 0xffff0000, v6
	v_lshlrev_b32_e32 v23, 16, v7
	v_and_b32_e32 v7, 0xffff0000, v7
	v_mul_f32_e32 v25, 0x3e000000, v25
	v_mul_f32_e32 v8, 0x3e000000, v8
	v_and_b32_e32 v100, 56, v0
	v_lshlrev_b32_e32 v19, 16, v3
	v_and_b32_e32 v3, 0xffff0000, v3
	v_mul_f32_e32 v22, 0x3e000000, v22
	v_mul_f32_e32 v6, 0x3e000000, v6
	v_mul_f32_e32 v23, 0x3e000000, v23
	v_mul_f32_e32 v7, 0x3e000000, v7
	v_cvt_pk_bf16_f32 v8, v25, v8
	s_lshl_b32 s4, s54, 2
	s_ashr_i32 s5, s54, 31
	v_lshlrev_b32_e32 v0, 1, v100
	v_mul_lo_u32 v25, v144, s18
	v_mul_f32_e32 v19, 0x3e000000, v19
	v_mul_f32_e32 v3, 0x3e000000, v3
	v_cvt_pk_bf16_f32 v6, v22, v6
	v_cvt_pk_bf16_f32 v7, v23, v7
	s_or_b32 s16, s4, 2
	s_lshr_b32 s5, s5, 26
	v_lshl_add_u64 v[22:23], s[0:1], 0, v[0:1]
	v_add3_u32 v146, 0, v25, v0
	v_or_b32_e32 v0, 48, v99
	v_cvt_pk_bf16_f32 v3, v19, v3
	v_subrev_co_u32_e32 v19, vcc, 1, v97
	s_add_i32 s5, s16, s5
	v_mul_u32_u24_e32 v149, 0x90, v0
	v_lshl_add_u32 v0, v24, 6, v101
	s_ashr_i32 s17, s5, 6
	v_lshrrev_b32_e32 v156, 2, v97
	v_or_b32_e32 v156, v0, v156
	s_and_b64 vcc, vcc, s[12:13]
	v_lshlrev_b32_e32 v0, 7, v144
	v_lshl_add_u64 v[20:21], v[94:95], 1, s[0:1]
	s_cmpk_gt_i32 s16, 0xffc0
	v_lshl_add_u64 v[104:105], v[22:23], 0, v[0:1]
	v_lshlrev_b32_e32 v0, 7, v99
	s_cselect_b64 s[8:9], -1, 0
	s_addk_i32 s4, 0x41
	v_lshl_add_u64 v[24:25], v[20:21], 0, v[0:1]
	v_add_u32_e32 v0, 64, v144
	s_cmpk_gt_u32 s4, 0x7e
	s_mov_b64 s[4:5], 0x80000
	v_cmp_gt_u32_e64 s[14:15], s84, v0
	v_lshlrev_b32_e32 v0, 7, v0
	v_cndmask_b32_e32 v18, 0, v252, vcc
	v_lshl_add_u64 v[106:107], v[24:25], 0, s[4:5]
	v_lshl_add_u64 v[108:109], v[22:23], 0, v[0:1]
	s_mov_b64 s[4:5], 0x82000
	v_mov_b32_e32 v0, 0x5040100
	s_cselect_b64 s[30:31], -1, 0
	v_lshl_add_u64 v[110:111], v[24:25], 0, s[4:5]
	v_perm_b32 v21, v18, 0, v0
	s_pack_ll_b32_b16 s4, 0, 0
	s_cmpk_gt_i32 s16, 0x7f
	v_add_u32_e32 v0, 0x80, v144
	v_cmp_eq_u32_e64 s[0:1], v103, v19
	v_cmp_eq_u32_e64 s[20:21], v26, v19
	v_cmp_eq_u32_e64 s[24:25], v27, v19
	v_cmp_eq_u32_e64 s[26:27], v28, v19
	v_mov_b32_e32 v18, s4
	v_mov_b32_e32 v19, s4
	v_mov_b32_e32 v20, s4
	s_cselect_b64 s[4:5], -1, 0
	s_cmp_gt_u32 s17, 2
	v_cmp_gt_u32_e64 s[16:17], s84, v0
	v_lshlrev_b32_e32 v0, 7, v0
	v_lshl_add_u64 v[112:113], v[22:23], 0, v[0:1]
	s_mov_b64 s[18:19], 0x84000
	v_add_u32_e32 v0, 0xc0, v144
	v_lshl_add_u64 v[114:115], v[24:25], 0, s[18:19]
	v_cmp_gt_u32_e64 s[18:19], s84, v0
	v_lshlrev_b32_e32 v0, 7, v0
	v_cmp_eq_u32_e32 vcc, v103, v97
	s_cselect_b64 s[28:29], -1, 0
	v_lshl_add_u64 v[116:117], v[22:23], 0, v[0:1]
	v_cndmask_b32_e32 v0, 0, v238, vcc
	s_or_b64 vcc, vcc, s[0:1]
	v_cndmask_b32_e32 v22, 0, v252, vcc
	v_cmp_eq_u32_e32 vcc, v26, v97
	v_lshl_add_u64 v[134:135], v[24:25], 0, s[66:67]
	s_mov_b32 s0, 0x5040100
	v_cndmask_b32_e32 v24, 0, v238, vcc
	s_or_b64 vcc, vcc, s[20:21]
	v_cndmask_b32_e32 v23, 0, v252, vcc
	v_cmp_eq_u32_e32 vcc, v27, v97
	v_cmp_gt_u32_e64 s[12:13], s84, v144
	v_perm_b32 v25, v23, v24, s0
	v_cndmask_b32_e32 v26, 0, v238, vcc
	s_or_b64 vcc, vcc, s[24:25]
	v_cndmask_b32_e32 v27, 0, v252, vcc
	v_cmp_eq_u32_e32 vcc, v28, v97
	v_perm_b32 v23, v22, v0, s0
	v_perm_b32 v24, v24, v24, s0
	v_cndmask_b32_e32 v28, 0, v238, vcc
	s_or_b64 vcc, vcc, s[26:27]
	v_cndmask_b32_e32 v29, 0, v252, vcc
	v_perm_b32 v22, v0, v0, s0
	v_perm_b32 v29, v29, v28, s0
	v_perm_b32 v27, v27, v26, s0
	v_perm_b32 v28, v28, v28, s0
	v_perm_b32 v26, v26, v26, s0
	s_mov_b64 s[24:25], -1
	s_branch .LBB0_203

; #define LAS __attribute__((address_space(3)))
; __device__ __forceinline__ float bf2f(bf16_t v) { return __uint_as_float(((unsigned)v) << 16); }
; __device__ __forceinline__ float sigmoidf_(float x) { return __builtin_amdgcn_rcpf(1.0f + __expf(-x)); }
; __device__ __forceinline__ void nsa_unit(LAS unsigned char* lds, const Ctx& P, int l, int b, int hkv, int tb) {
;     ...
;         const float inv = 1.0f / fmaxf(lsum, 1e-30f);
;         const float g0 = sigmoidf_(bf2f(H[((size_t)b * SEQ + tqs) * LDH + C_GL + hq]) + P.in[21][l * 48 + hq]) * inv;
; #pragma unroll
;         for (int dt = 0; dt < 4; ++dt) { park[(sb * 4 + dt) * 64] = o[dt] * g0;
;             *(LAS f32x4*)(impb + (g * 64 + 32 * th + 16 * sb + c) * 64 + 16 * dt + 4 * i) = oi[dt] * inv; }
.Lcm_rotd_9:
	s_waitcnt lgkmcnt(0)
	s_barrier
	v_max_f32_e32 v86, v138, v138
	v_max_f32_e32 v86, 0xda24260, v86
	v_div_scale_f32 v87, s[0:1], v86, v86, 1.0
	v_rcp_f32_e32 v88, v87
	s_nop 0
	v_fma_f32 v89, -v87, v88, 1.0
	v_fmac_f32_e32 v88, v89, v88
	v_div_scale_f32 v89, vcc, 1.0, v86, 1.0
	v_mul_f32_e32 v91, v89, v88
	v_fma_f32 v92, -v87, v91, v89
	v_fmac_f32_e32 v91, v92, v88
	v_fma_f32 v87, -v87, v91, v89
	v_div_fmas_f32 v87, v87, v88, v91
	v_div_fixup_f32 v68, v87, v86, 1.0
	v_lshlrev_b32_e32 v64, 16, v108
	v_add_f32_e32 v64, v110, v64
	v_mul_f32_e32 v64, 0xbfb8aa3b, v64
	v_exp_f32_e32 v64, v64
	s_nop 0
	v_add_f32_e32 v64, 1.0, v64
	v_rcp_f32_e32 v64, v64
	s_nop 0
	v_mul_f32_e32 v70, v68, v64
	v_pk_mul_f32 v[30:31], v[30:31], v[70:71] op_sel_hi:[1,0]
	v_pk_mul_f32 v[32:33], v[32:33], v[70:71] op_sel_hi:[1,0]
	global_store_dwordx4 v[124:125], v[30:33], off
	v_pk_mul_f32 v[34:35], v[34:35], v[70:71] op_sel_hi:[1,0]
	v_pk_mul_f32 v[36:37], v[36:37], v[70:71] op_sel_hi:[1,0]
	global_store_dwordx4 v[124:125], v[34:37], off offset:1024
	v_pk_mul_f32 v[38:39], v[38:39], v[70:71] op_sel_hi:[1,0]
	v_pk_mul_f32 v[40:41], v[40:41], v[70:71] op_sel_hi:[1,0]
	global_store_dwordx4 v[124:125], v[38:41], off offset:2048
	v_pk_mul_f32 v[42:43], v[42:43], v[70:71] op_sel_hi:[1,0]
	v_pk_mul_f32 v[44:45], v[44:45], v[70:71] op_sel_hi:[1,0]
	global_store_dwordx4 v[124:125], v[42:45], off offset:3072
	v_mov_b32_e32 v74, v156
	v_lshl_add_u32 v74, v74, 8, v150
	v_pk_mul_f32 v[46:47], v[46:47], v[68:69] op_sel_hi:[1,0]
	v_pk_mul_f32 v[48:49], v[48:49], v[68:69] op_sel_hi:[1,0]
	ds_write_b128 v74, v[46:49] offset:53248
	v_pk_mul_f32 v[50:51], v[50:51], v[68:69] op_sel_hi:[1,0]
	v_pk_mul_f32 v[52:53], v[52:53], v[68:69] op_sel_hi:[1,0]
	ds_write_b128 v74, v[50:53] offset:53312
	v_pk_mul_f32 v[54:55], v[54:55], v[68:69] op_sel_hi:[1,0]
	v_pk_mul_f32 v[56:57], v[56:57], v[68:69] op_sel_hi:[1,0]
	ds_write_b128 v74, v[54:57] offset:53376
	v_pk_mul_f32 v[58:59], v[58:59], v[68:69] op_sel_hi:[1,0]
	v_pk_mul_f32 v[60:61], v[60:61], v[68:69] op_sel_hi:[1,0]
	ds_write_b128 v74, v[58:61] offset:53440
	v_max_f32_e32 v86, v196, v196
	v_max_f32_e32 v86, 0xda24260, v86
	v_div_scale_f32 v87, s[0:1], v86, v86, 1.0
	v_rcp_f32_e32 v88, v87
	s_nop 0
	v_fma_f32 v89, -v87, v88, 1.0
	v_fmac_f32_e32 v88, v89, v88
	v_div_scale_f32 v89, vcc, 1.0, v86, 1.0
	v_mul_f32_e32 v91, v89, v88
	v_fma_f32 v92, -v87, v91, v89
	v_fmac_f32_e32 v91, v92, v88
	v_fma_f32 v87, -v87, v91, v89
	v_div_fmas_f32 v87, v87, v88, v91
	v_div_fixup_f32 v68, v87, v86, 1.0
	v_lshlrev_b32_e32 v64, 16, v109
	v_add_f32_e32 v64, v110, v64
	v_mul_f32_e32 v64, 0xbfb8aa3b, v64
	v_exp_f32_e32 v64, v64
	s_nop 0
	v_add_f32_e32 v64, 1.0, v64
	v_rcp_f32_e32 v64, v64
	s_nop 0
	v_mul_f32_e32 v70, v68, v64
	v_add_co_u32_e32 v72, vcc, 0x1000, v124
	s_nop 1
	v_addc_co_u32_e32 v73, vcc, 0, v125, vcc
	v_pk_mul_f32 v[174:175], v[174:175], v[70:71] op_sel_hi:[1,0]
	v_pk_mul_f32 v[176:177], v[176:177], v[70:71] op_sel_hi:[1,0]
	global_store_dwordx4 v[72:73], v[174:177], off
	v_pk_mul_f32 v[178:179], v[178:179], v[70:71] op_sel_hi:[1,0]
	v_pk_mul_f32 v[180:181], v[180:181], v[70:71] op_sel_hi:[1,0]
	global_store_dwordx4 v[72:73], v[178:181], off offset:1024
	v_pk_mul_f32 v[182:183], v[182:183], v[70:71] op_sel_hi:[1,0]
	v_pk_mul_f32 v[184:185], v[184:185], v[70:71] op_sel_hi:[1,0]
	global_store_dwordx4 v[72:73], v[182:185], off offset:2048
	v_pk_mul_f32 v[186:187], v[186:187], v[70:71] op_sel_hi:[1,0]
	v_pk_mul_f32 v[188:189], v[188:189], v[70:71] op_sel_hi:[1,0]
	global_store_dwordx4 v[72:73], v[186:189], off offset:3072
	v_or_b32_e32 v74, 4, v156
	v_lshl_add_u32 v74, v74, 8, v150
	v_pk_mul_f32 v[18:19], v[18:19], v[68:69] op_sel_hi:[1,0]
	v_pk_mul_f32 v[20:21], v[20:21], v[68:69] op_sel_hi:[1,0]
	ds_write_b128 v74, v[18:21] offset:53248
	v_pk_mul_f32 v[22:23], v[22:23], v[68:69] op_sel_hi:[1,0]
	v_pk_mul_f32 v[24:25], v[24:25], v[68:69] op_sel_hi:[1,0]
	ds_write_b128 v74, v[22:25] offset:53312
	v_pk_mul_f32 v[26:27], v[26:27], v[68:69] op_sel_hi:[1,0]
	v_pk_mul_f32 v[28:29], v[28:29], v[68:69] op_sel_hi:[1,0]
	ds_write_b128 v74, v[26:29] offset:53376
	v_pk_mul_f32 v[104:105], v[104:105], v[68:69] op_sel_hi:[1,0]
	v_pk_mul_f32 v[106:107], v[106:107], v[68:69] op_sel_hi:[1,0]
	ds_write_b128 v74, v[104:107] offset:53440
	v_lshlrev_b32_e32 v0, 1, v102
	v_lshlrev_b32_e32 v132, 1, v96
	s_branch .LBB0_361

; __device__ __forceinline__ void nsa_unit(LAS unsigned char* lds, const Ctx& P, int l, int b, int hkv, int tb) {
;     ...
;         unsigned long long ms[2]; unsigned long long U = 0ull;
; #pragma unroll
;         for (int sb = 0; sb < 2; ++sb) ms[sb] = sels[32 * th + 16 * sb + c];
;         for (int t = 0; t < 64; ++t) U |= sels[t];
;         f32x4 o[2][4]; float m[2], lsum[2];
; #pragma unroll
;         for (int sb = 0; sb < 2; ++sb) { m[sb] = NEGBIG; lsum[sb] = 0.f;
; #pragma unroll
;             for (int dt = 0; dt < 4; ++dt) o[sb][dt] = (f32x4){0.f, 0.f, 0.f, 0.f}; }
;         const bf16_t* kb = H + (size_t)b * SEQ * LDH + C_KS + hkv * 64; const bf16_t* vb = H + (size_t)b * SEQ * LDH + C_VS + hkv * 64;
;         U &= ((2ull << qb) - 1ull);
;         unsigned long long Ur = ((unsigned long long)(unsigned)__builtin_amdgcn_readfirstlane((int)(U >> 32)) << 32) | (unsigned)__builtin_amdgcn_readfirstlane((int)U);
.LBB0_402:
	s_or_b64 exec, exec, s[0:1]
	s_add_i32 s4, 0, 0x1d000
	v_readlane_b32 s0, v254, 54
	v_mov_b32_e32 v18, s4
	s_waitcnt lgkmcnt(0)
	v_mov_b32_e32 v22, s0
	s_barrier
	ds_read_b128 v[18:21], v18
	ds_read_b128 v[22:25], v22
	v_readlane_b32 s0, v254, 55
	s_mul_i32 s61, s61, 0x5600000
	s_add_u32 s16, s10, s61
	v_mov_b32_e32 v26, s0
	v_readlane_b32 s0, v254, 56
	s_waitcnt lgkmcnt(1)
	v_or_b32_e32 v18, v20, v18
	v_or_b32_e32 v19, v21, v19
	v_mov_b32_e32 v30, s0
	ds_read_b128 v[26:29], v26
	ds_read_b128 v[30:33], v30
	v_readlane_b32 s0, v254, 57
	s_waitcnt lgkmcnt(2)
	v_or_b32_e32 v18, v18, v22
	v_or_b32_e32 v19, v19, v23
	v_mov_b32_e32 v34, s0
	v_readlane_b32 s0, v254, 58
	v_or_b32_e32 v18, v18, v24
	v_or_b32_e32 v19, v19, v25
	v_mov_b32_e32 v38, s0
	ds_read_b128 v[34:37], v34
	ds_read_b128 v[38:41], v38
	s_waitcnt lgkmcnt(3)
	v_or_b32_e32 v18, v18, v26
	v_or_b32_e32 v19, v19, v27
	v_readlane_b32 s0, v254, 59
	v_or_b32_e32 v18, v18, v28
	v_or_b32_e32 v19, v19, v29
	v_mov_b32_e32 v42, s0
	v_readlane_b32 s0, v254, 60
	s_waitcnt lgkmcnt(2)
	v_or_b32_e32 v18, v18, v30
	v_or_b32_e32 v19, v19, v31
	v_mov_b32_e32 v46, s0
	v_or_b32_e32 v18, v18, v32
	v_or_b32_e32 v19, v19, v33
	ds_read_b128 v[42:45], v42
	ds_read_b128 v[46:49], v46
	s_waitcnt lgkmcnt(3)
	v_or_b32_e32 v18, v18, v34
	v_or_b32_e32 v19, v19, v35
	v_readlane_b32 s0, v254, 61
	v_or_b32_e32 v18, v18, v36
	v_or_b32_e32 v19, v19, v37
	v_mov_b32_e32 v50, s0
	v_readlane_b32 s0, v254, 62
	s_waitcnt lgkmcnt(2)
	v_or_b32_e32 v18, v18, v38
	v_or_b32_e32 v19, v19, v39
	v_mov_b32_e32 v54, s0
	v_or_b32_e32 v18, v18, v40
	v_or_b32_e32 v19, v19, v41
	ds_read_b128 v[50:53], v50
	ds_read_b128 v[54:57], v54
	s_waitcnt lgkmcnt(3)
	v_or_b32_e32 v18, v18, v42
	v_or_b32_e32 v19, v19, v43
	v_readlane_b32 s0, v254, 63
	v_or_b32_e32 v18, v18, v44
	v_or_b32_e32 v19, v19, v45
	v_mov_b32_e32 v58, s0
	v_readlane_b32 s0, v255, 0
	s_waitcnt lgkmcnt(2)
	v_or_b32_e32 v18, v18, v46
	v_or_b32_e32 v19, v19, v47
	v_mov_b32_e32 v62, s0
	v_or_b32_e32 v18, v18, v48
	v_or_b32_e32 v19, v19, v49
	ds_read_b128 v[58:61], v58
	ds_read_b128 v[62:65], v62
	s_waitcnt lgkmcnt(3)
	v_or_b32_e32 v18, v18, v50
	v_or_b32_e32 v19, v19, v51
	v_readlane_b32 s0, v255, 1
	v_or_b32_e32 v18, v18, v52
	v_or_b32_e32 v19, v19, v53
	v_mov_b32_e32 v66, s0
	v_readlane_b32 s0, v255, 2
	s_waitcnt lgkmcnt(2)
	v_or_b32_e32 v18, v18, v54
	v_or_b32_e32 v19, v19, v55
	v_mov_b32_e32 v70, s0
	v_or_b32_e32 v18, v18, v56
	v_or_b32_e32 v19, v19, v57
	ds_read_b128 v[66:69], v66
	ds_read_b128 v[70:73], v70
	s_waitcnt lgkmcnt(3)
	v_or_b32_e32 v18, v18, v58
	v_or_b32_e32 v19, v19, v59
	v_readlane_b32 s0, v255, 3
	v_or_b32_e32 v18, v18, v60
	v_or_b32_e32 v19, v19, v61
	v_mov_b32_e32 v74, s0
	v_readlane_b32 s0, v255, 4
	s_waitcnt lgkmcnt(2)
	v_or_b32_e32 v18, v18, v62
	v_or_b32_e32 v19, v19, v63
	v_mov_b32_e32 v78, s0
	v_or_b32_e32 v18, v18, v64
	v_or_b32_e32 v19, v19, v65
	ds_read_b128 v[74:77], v74
	ds_read_b128 v[78:81], v78
	s_waitcnt lgkmcnt(3)
	v_or_b32_e32 v18, v18, v66
	v_or_b32_e32 v19, v19, v67
	v_readlane_b32 s0, v255, 5
	v_or_b32_e32 v18, v18, v68
	v_or_b32_e32 v19, v19, v69
	v_mov_b32_e32 v82, s0
	v_readlane_b32 s0, v255, 6
	s_waitcnt lgkmcnt(2)
	v_or_b32_e32 v18, v18, v70
	v_or_b32_e32 v19, v19, v71
	v_mov_b32_e32 v86, s0
	v_or_b32_e32 v18, v18, v72
	v_or_b32_e32 v19, v19, v73
	ds_read_b128 v[82:85], v82
	ds_read_b128 v[86:89], v86
	s_waitcnt lgkmcnt(3)
	v_or_b32_e32 v18, v18, v74
	v_or_b32_e32 v19, v19, v75
	v_or_b32_e32 v18, v18, v76
	v_or_b32_e32 v19, v19, v77
	v_readlane_b32 s0, v255, 7
	s_waitcnt lgkmcnt(2)
	v_or_b32_e32 v18, v18, v78
	v_or_b32_e32 v19, v19, v79
	v_mov_b32_e32 v90, s0
	v_readlane_b32 s0, v255, 8
	v_or_b32_e32 v18, v18, v80
	v_or_b32_e32 v19, v19, v81
	v_mov_b32_e32 v102, s0
	ds_read_b128 v[90:93], v90
	ds_read_b128 v[104:107], v102
	s_waitcnt lgkmcnt(3)
	v_or_b32_e32 v18, v18, v82
	v_or_b32_e32 v19, v19, v83
	v_readlane_b32 s0, v255, 9
	v_or_b32_e32 v18, v18, v84
	v_or_b32_e32 v19, v19, v85
	v_mov_b32_e32 v102, s0
	v_readlane_b32 s0, v255, 10
	s_waitcnt lgkmcnt(2)
	v_or_b32_e32 v18, v18, v86
	v_or_b32_e32 v19, v19, v87
	v_mov_b32_e32 v112, s0
	v_or_b32_e32 v18, v18, v88
	v_or_b32_e32 v19, v19, v89
	ds_read_b128 v[108:111], v102
	ds_read_b128 v[112:115], v112
	s_waitcnt lgkmcnt(3)
	v_or_b32_e32 v18, v18, v90
	v_or_b32_e32 v19, v19, v91
	v_or_b32_e32 v18, v18, v92
	v_or_b32_e32 v19, v19, v93
	v_readlane_b32 s0, v255, 11
	s_waitcnt lgkmcnt(2)
	v_or_b32_e32 v18, v18, v104
	v_or_b32_e32 v19, v19, v105
	v_mov_b32_e32 v102, s0
	v_readlane_b32 s0, v255, 12
	v_or_b32_e32 v18, v18, v106
	v_or_b32_e32 v19, v19, v107
	v_mov_b32_e32 v116, s0
	ds_read_b128 v[134:137], v102
	ds_read_b128 v[156:159], v116
	s_waitcnt lgkmcnt(3)
	v_or_b32_e32 v18, v18, v108
	v_or_b32_e32 v19, v19, v109
	v_or_b32_e32 v18, v18, v110
	v_or_b32_e32 v19, v19, v111
	v_readlane_b32 s0, v255, 13
	s_waitcnt lgkmcnt(2)
	v_or_b32_e32 v18, v18, v112
	v_or_b32_e32 v19, v19, v113
	v_mov_b32_e32 v102, s0
	v_readlane_b32 s0, v255, 14
	v_or_b32_e32 v18, v18, v114
	v_or_b32_e32 v19, v19, v115
	v_mov_b32_e32 v116, s0
	ds_read_b128 v[160:163], v102
	ds_read_b128 v[170:173], v116
	s_waitcnt lgkmcnt(3)
	v_or_b32_e32 v18, v18, v134
	v_or_b32_e32 v19, v19, v135
	v_or_b32_e32 v18, v18, v136
	v_or_b32_e32 v19, v19, v137
	v_readlane_b32 s0, v255, 15
	s_waitcnt lgkmcnt(2)
	v_or_b32_e32 v18, v18, v156
	v_or_b32_e32 v19, v19, v157
	v_mov_b32_e32 v102, s0
	v_readlane_b32 s0, v255, 16
	v_or_b32_e32 v18, v18, v158
	v_or_b32_e32 v19, v19, v159
	v_mov_b32_e32 v116, s0
	ds_read_b128 v[174:177], v102
	ds_read_b128 v[178:181], v116
	s_waitcnt lgkmcnt(3)
; __device__ __forceinline__ void nsa_unit(LAS unsigned char* lds, const Ctx& P, int l, int b, int hkv, int tb) {
;     ...
;         unsigned long long ms[2]; unsigned long long U = 0ull;
; #pragma unroll
;         for (int sb = 0; sb < 2; ++sb) ms[sb] = sels[32 * th + 16 * sb + c];
;         for (int t = 0; t < 64; ++t) U |= sels[t];
;         f32x4 o[2][4]; float m[2], lsum[2];
; #pragma unroll
;         for (int sb = 0; sb < 2; ++sb) { m[sb] = NEGBIG; lsum[sb] = 0.f;
; #pragma unroll
;             for (int dt = 0; dt < 4; ++dt) o[sb][dt] = (f32x4){0.f, 0.f, 0.f, 0.f}; }
;         const bf16_t* kb = H + (size_t)b * SEQ * LDH + C_KS + hkv * 64; const bf16_t* vb = H + (size_t)b * SEQ * LDH + C_VS + hkv * 64;
;         U &= ((2ull << qb) - 1ull);
;         unsigned long long Ur = ((unsigned long long)(unsigned)__builtin_amdgcn_readfirstlane((int)(U >> 32)) << 32) | (unsigned)__builtin_amdgcn_readfirstlane((int)U);
;         const float cfar = lut[790];
	v_or_b32_e32 v18, v18, v160
	v_or_b32_e32 v19, v19, v161
	v_or_b32_e32 v18, v18, v162
	v_or_b32_e32 v19, v19, v163
	v_readlane_b32 s0, v255, 17
	s_waitcnt lgkmcnt(2)
	v_or_b32_e32 v18, v18, v170
	v_or_b32_e32 v19, v19, v171
	v_mov_b32_e32 v102, s0
	v_readlane_b32 s0, v255, 18
	v_or_b32_e32 v18, v18, v172
	v_or_b32_e32 v19, v19, v173
	v_mov_b32_e32 v116, s0
	ds_read_b128 v[182:185], v102
	ds_read_b128 v[186:189], v116
	s_waitcnt lgkmcnt(3)
	v_or_b32_e32 v18, v18, v174
	v_or_b32_e32 v19, v19, v175
	v_or_b32_e32 v18, v18, v176
	v_or_b32_e32 v19, v19, v177
	v_readlane_b32 s0, v255, 19
	s_waitcnt lgkmcnt(2)
	v_or_b32_e32 v18, v18, v178
	v_or_b32_e32 v19, v19, v179
	v_mov_b32_e32 v102, s0
	v_readlane_b32 s0, v255, 20
	v_or_b32_e32 v18, v18, v180
	v_or_b32_e32 v19, v19, v181
	v_mov_b32_e32 v116, s0
	ds_read_b128 v[190:193], v102
	ds_read_b128 v[194:197], v116
	s_waitcnt lgkmcnt(3)
	v_or_b32_e32 v18, v18, v182
	v_or_b32_e32 v19, v19, v183
	v_or_b32_e32 v18, v18, v184
	v_or_b32_e32 v19, v19, v185
	s_waitcnt lgkmcnt(2)
	v_or_b32_e32 v18, v18, v186
	v_or_b32_e32 v19, v19, v187
	v_or_b32_e32 v18, v18, v188
	v_or_b32_e32 v19, v19, v189
	s_waitcnt lgkmcnt(1)
	v_or_b32_e32 v18, v18, v190
	v_or_b32_e32 v19, v19, v191
	v_or_b32_e32 v18, v18, v192
	v_or_b32_e32 v19, v19, v193
	s_waitcnt lgkmcnt(0)
	v_or_b32_e32 v18, v18, v194
	v_or_b32_e32 v19, v19, v195
	v_or_b32_e32 v18, v18, v196
	v_or_b32_e32 v19, v19, v197
	v_and_b32_e32 v18, s24, v18
	v_and_b32_e32 v19, s25, v19
	s_addc_u32 s17, s11, 0
	s_lshl_b32 s18, s60, 6
	v_readfirstlane_b32 s1, v19
	v_readfirstlane_b32 s0, v18
	v_lshlrev_b32_e32 v139, 2, v103
	s_cmp_eq_u64 s[0:1], 0
	v_lshlrev_b32_e32 v86, 1, v100
	s_cbranch_scc1 .LBB0_596
	v_and_b32_e32 v18, 0xffffffc0, v154
	v_and_b32_e32 v19, 12, v97
	v_lshlrev_b32_e32 v19, 1, v19
	v_add3_u32 v18, s4, v18, v19
	s_lshl_b32 s4, s18, 1
	s_add_u32 s4, s16, s4
	s_addc_u32 s5, s17, 0
	v_mov_b32_e32 v87, v1
	v_lshl_add_u64 v[22:23], s[4:5], 0, v[86:87]
	s_mov_b64 s[8:9], 0x3400
	ds_read2_b64 v[18:21], v18 offset1:4
	ds_read_b32 v92, v131 offset:3160
	v_lshl_add_u64 v[88:89], v[22:23], 0, s[8:9]
	v_lshl_add_u64 v[22:23], v[94:95], 1, s[4:5]
	s_mov_b64 s[4:5], 0x3600
	v_lshl_add_u64 v[90:91], v[22:23], 0, s[4:5]
	v_lshrrev_b32_e32 v22, 1, v154
	v_and_b32_e32 v22, 24, v22
	v_mov_b32_e32 v30, v1
	v_mov_b32_e32 v31, v1
	v_mov_b32_e32 v32, v1
	v_mov_b32_e32 v33, v1
	v_add_u32_e32 v87, 0, v22
	v_mov_b64_e32 v[36:37], v[32:33]
	v_mov_b64_e32 v[26:27], v[30:31]
	v_mov_b64_e32 v[22:23], v[30:31]
	v_mov_b64_e32 v[52:53], v[32:33]
	v_mov_b64_e32 v[48:49], v[32:33]
	v_mov_b64_e32 v[44:45], v[32:33]
	v_mov_b64_e32 v[40:41], v[32:33]
	s_sub_i32 s19, s55, 63
	v_mov_b32_e32 v105, 0
	v_mov_b32_e32 v93, 0xf149f2ca
	v_mov_b64_e32 v[34:35], v[30:31]
	v_mov_b64_e32 v[28:29], v[32:33]
	v_mov_b64_e32 v[24:25], v[32:33]
	v_mov_b64_e32 v[50:51], v[30:31]
	v_mov_b64_e32 v[46:47], v[30:31]
	v_mov_b64_e32 v[42:43], v[30:31]
	v_mov_b64_e32 v[38:39], v[30:31]
	v_mov_b32_e32 v100, 0xf149f2ca
	v_mov_b32_e32 v106, 0
	s_branch .LBB0_407
; __device__ __forceinline__ void tile_issue(TileRegs& r, const int tid, const bf16_t* ksrc, const bf16_t* vsrc, size_t ld, int p0, int pmax) {
;     const int kkey = tid >> 3, kseg = tid & 7, pk = p0 + kkey; const int vkey = tid & 63, vseg = tid >> 6, pv = p0 + vkey;
;     r.k = (u32x4){0u, 0u, 0u, 0u}; r.v = (u32x4){0u, 0u, 0u, 0u};
;     if (pk >= 0 && pk <= pmax) r.k = *(const u32x4*)(ksrc + (size_t)pk * ld + kseg * 8);
;     if (pv >= 0 && pv <= pmax) r.v = *(const u32x4*)(vsrc + (size_t)pv * ld + vseg * 8); }
; __device__ __forceinline__ void nsa_unit(LAS unsigned char* lds, const Ctx& P, int l, int b, int hkv, int tb) {
;     ...
;         while (Ur != 0ull) {
;             const int ja = __builtin_ctzll(Ur); Ur &= Ur - 1ull; const bool hasb = Ur != 0ull; int jb = 0; if (hasb) { jb = __builtin_ctzll(Ur); Ur &= Ur - 1ull; }
;             __syncthreads();
;             load2(kb, vb, LDH, ja * 64, jb * 64, hasb, SEQ - 1);
;             __syncthreads();
.LBB0_407:
	v_add_u32_e32 v102, v150, v148
	v_lshrrev_b32_e32 v78, 2, v97
	v_lshl_add_u32 v78, v103, 2, v78
	v_mul_u32_u24_e32 v78, 0x90, v78
	v_and_b32_e32 v79, 3, v97
	v_lshl_add_u32 v104, v79, 3, v78
	v_add_u32_e32 v192, 0xc000, v146
	s_mov_b64 s[14:15], s[0:1]
	s_mov_b32 s13, 0
	s_ff1_i32_b64 s0, s[14:15]
	s_add_u32 s4, s14, -1
	s_addc_u32 s5, s15, -1
	s_and_b64 s[14:15], s[14:15], s[4:5]
	s_mov_b32 s13, 1
	s_lshl_b32 s4, s0, 6
	v_add_u32_e32 v54, s4, v144
	v_mul_lo_u32 v54, v54, s75
	v_mov_b32_e32 v55, v1
	v_lshl_add_u64 v[54:55], v[54:55], 1, v[88:89]
	global_load_dwordx4 v[230:233], v[54:55], off
	global_load_dwordx4 v[114:117], v[54:55], off offset:512
	s_cmp_eq_u64 s[14:15], 0
	s_cbranch_scc1 .Lsl3_xd_1
	s_ff1_i32_b64 s1, s[14:15]
	s_add_u32 s4, s14, -1
	s_addc_u32 s5, s15, -1
	s_and_b64 s[14:15], s[14:15], s[4:5]
	s_mov_b32 s13, 2
	s_lshl_b32 s4, s1, 6
	v_add_u32_e32 v54, s4, v144
	v_mul_lo_u32 v54, v54, s75
	v_mov_b32_e32 v55, v1
	v_lshl_add_u64 v[54:55], v[54:55], 1, v[88:89]
	global_load_dwordx4 v[134:137], v[54:55], off
	global_load_dwordx4 v[156:159], v[54:55], off offset:512
	s_cmp_eq_u64 s[14:15], 0
	s_cbranch_scc1 .Lsl3_xd_1
	s_ff1_i32_b64 s31, s[14:15]
	s_add_u32 s4, s14, -1
	s_addc_u32 s5, s15, -1
	s_and_b64 s[14:15], s[14:15], s[4:5]
	s_mov_b32 s13, 3
	s_lshl_b32 s4, s31, 6
	v_add_u32_e32 v54, s4, v144
	v_mul_lo_u32 v54, v54, s75
	v_mov_b32_e32 v55, v1
	v_lshl_add_u64 v[54:55], v[54:55], 1, v[88:89]
	global_load_dwordx4 v[174:177], v[54:55], off
	global_load_dwordx4 v[178:181], v[54:55], off offset:512
	s_cmp_eq_u64 s[14:15], 0
	s_cbranch_scc1 .Lsl3_xd_1
	s_ff1_i32_b64 s32, s[14:15]
	s_add_u32 s4, s14, -1
	s_addc_u32 s5, s15, -1
	s_and_b64 s[14:15], s[14:15], s[4:5]
	s_mov_b32 s13, 4
	s_lshl_b32 s4, s32, 6
	v_add_u32_e32 v54, s4, v144
	v_mul_lo_u32 v54, v54, s75
	v_mov_b32_e32 v55, v1
	v_lshl_add_u64 v[54:55], v[54:55], 1, v[88:89]
	global_load_dwordx4 v[182:185], v[54:55], off
	global_load_dwordx4 v[186:189], v[54:55], off offset:512
.Lsl3_xd_1:
.Lsl3_top:
	s_mov_b32 s26, s0
	s_mov_b32 s27, s1
	s_mov_b32 s28, s31
	s_mov_b32 s29, s32
	s_mov_b32 s30, s13
	s_waitcnt lgkmcnt(0)
	s_barrier
	s_waitcnt vmcnt(0)
	ds_write_b128 v146, v[230:233] offset:16384
	ds_write_b128 v146, v[114:117] offset:25600
	s_cmp_lt_u32 s30, 2
	s_cbranch_scc1 .Lsl3_wd_2
	ds_write_b128 v146, v[134:137] offset:34816
	ds_write_b128 v146, v[156:159] offset:44032
	s_cmp_lt_u32 s30, 3
	s_cbranch_scc1 .Lsl3_wd_2
	ds_write_b128 v192, v[174:177] offset:4096
	ds_write_b128 v192, v[178:181] offset:13312
	s_cmp_lt_u32 s30, 4
	s_cbranch_scc1 .Lsl3_wd_2
	ds_write_b128 v192, v[182:185] offset:22528
	ds_write_b128 v192, v[186:189] offset:31744
.Lsl3_wd_2:
	s_waitcnt lgkmcnt(0)
	s_barrier
	s_cmp_eq_u64 s[14:15], 0
	s_cbranch_scc1 .Lsl3_nonext_3
	s_mov_b32 s13, 0
	s_ff1_i32_b64 s0, s[14:15]
	s_add_u32 s4, s14, -1
	s_addc_u32 s5, s15, -1
	s_and_b64 s[14:15], s[14:15], s[4:5]
	s_mov_b32 s13, 1
	s_lshl_b32 s4, s0, 6
	v_add_u32_e32 v54, s4, v144
	v_mul_lo_u32 v54, v54, s75
	v_mov_b32_e32 v55, v1
	v_lshl_add_u64 v[54:55], v[54:55], 1, v[88:89]
	global_load_dwordx4 v[230:233], v[54:55], off
	global_load_dwordx4 v[114:117], v[54:55], off offset:512
	s_cmp_eq_u64 s[14:15], 0
	s_cbranch_scc1 .Lsl3_xd_5
	s_ff1_i32_b64 s1, s[14:15]
	s_add_u32 s4, s14, -1
	s_addc_u32 s5, s15, -1
	s_and_b64 s[14:15], s[14:15], s[4:5]
	s_mov_b32 s13, 2
	s_lshl_b32 s4, s1, 6
	v_add_u32_e32 v54, s4, v144
	v_mul_lo_u32 v54, v54, s75
	v_mov_b32_e32 v55, v1
	v_lshl_add_u64 v[54:55], v[54:55], 1, v[88:89]
	global_load_dwordx4 v[134:137], v[54:55], off
	global_load_dwordx4 v[156:159], v[54:55], off offset:512
	s_cmp_eq_u64 s[14:15], 0
	s_cbranch_scc1 .Lsl3_xd_5
	s_ff1_i32_b64 s31, s[14:15]
	s_add_u32 s4, s14, -1
	s_addc_u32 s5, s15, -1
	s_and_b64 s[14:15], s[14:15], s[4:5]
	s_mov_b32 s13, 3
	s_lshl_b32 s4, s31, 6
	v_add_u32_e32 v54, s4, v144
	v_mul_lo_u32 v54, v54, s75
	v_mov_b32_e32 v55, v1
	v_lshl_add_u64 v[54:55], v[54:55], 1, v[88:89]
	global_load_dwordx4 v[174:177], v[54:55], off
	global_load_dwordx4 v[178:181], v[54:55], off offset:512
	s_cmp_eq_u64 s[14:15], 0
	s_cbranch_scc1 .Lsl3_xd_5
	s_ff1_i32_b64 s32, s[14:15]
	s_add_u32 s4, s14, -1
	s_addc_u32 s5, s15, -1
	s_and_b64 s[14:15], s[14:15], s[4:5]
	s_mov_b32 s13, 4
	s_lshl_b32 s4, s32, 6
	v_add_u32_e32 v54, s4, v144
	v_mul_lo_u32 v54, v54, s75
	v_mov_b32_e32 v55, v1
	v_lshl_add_u64 v[54:55], v[54:55], 1, v[88:89]
	global_load_dwordx4 v[182:185], v[54:55], off
	global_load_dwordx4 v[186:189], v[54:55], off offset:512

; template <int D, class SF>
; __device__ __forceinline__ void attn_step(const bf16x8 (&qf)[D / 32], const LAS bf16_t* Ks, const LAS bf16_t* Vt, f32x4 (&o)[D / 16], float& m, float& lsum, float& alpha_out, bf16x8& pf0_out, bf16x8& pf1_out, const int lane, SF sf) {
;     constexpr int KSTR = D + 8;
;     const int c = lane & 15, i = lane >> 4;
;     f32x4 s[4];
; #pragma unroll
;     for (int t = 0; t < 4; ++t) s[t] = (f32x4){0.f, 0.f, 0.f, 0.f};
; #pragma unroll
;     for (int ks = 0; ks < D / 32; ++ks) {
; #pragma unroll
;         for (int t = 0; t < 4; ++t) { const bf16x8 kf = *(const LAS bf16x8*)(Ks + (16 * t + c) * KSTR + ks * 32 + 8 * i); s[t] = mfma16(kf, qf[ks], s[t]); }
;     }
;     float v[16];
; #pragma unroll
;     for (int t = 0; t < 4; ++t)
; #pragma unroll
;         for (int r = 0; r < 4; ++r) v[4 * t + r] = sf(16 * t + 4 * i + r, s[t][r]);
;     float mx = fmaxf(fmaxf(fmaxf(v[0], v[1]), fmaxf(v[2], v[3])), fmaxf(fmaxf(v[4], v[5]), fmaxf(v[6], v[7])));
;     mx = fmaxf(mx, fmaxf(fmaxf(fmaxf(v[8], v[9]), fmaxf(v[10], v[11])), fmaxf(fmaxf(v[12], v[13]), fmaxf(v[14], v[15]))));
;     mx = rows_max(mx);
;     const float mnew = fmaxf(m, mx);
;     const float mc = fmaxf(mnew, -1e20f);
;     const float alpha = __builtin_amdgcn_exp2f(fmaxf(m, -1e20f) - mc);
;     float p[16], rs = 0.f;
; #pragma unroll
;     for (int r = 0; r < 16; ++r) { p[r] = __builtin_amdgcn_exp2f(v[r] - mc); rs += p[r]; }
;     rs = rows_sum(rs);
;     lsum = lsum * alpha + rs; m = mnew;
;     union { u32x4 u; bf16x8 b; } pk0, pk1;
; __device__ __forceinline__ void nsa_unit(LAS unsigned char* lds, const Ctx& P, int l, int b, int hkv, int tb) {
;     ...
; #pragma unroll
;             for (int sl = 0; sl < 2; ++sl) if (sl == 0 || hasb) {
;                 const int j = sl ? jb : ja; const LAS bf16_t* Ks = KV + sl * 9216; const LAS bf16_t* Vt = Ks + 4608;
;                 const bool far = t0 - (64 * j + 63) >= 790;
; #pragma unroll
;                 for (int sb = 0; sb < 2; ++sb) { const bool selj = (ms[sb] >> j) & 1ull; const int tqs = tq[sb];
;                     if (far) {
;                         if (__builtin_amdgcn_ballot_w64(selj) == 0ull) continue;
;                         attn_step<64>(qf[sb], Ks, Vt, o[sb], m[sb], lsum[sb], alpha, pf, pf1, lane,
;                             [&](int, float s) { return selj ? s * LOG2E + cfar : NEGBIG; });
.Lsl3_cont_4:
	s_mov_b32 s40, 0
.Lsl3_slot_6:
	s_cmp_eq_u32 s40, 1
	s_cselect_b32 s20, s27, s26
	s_cmp_eq_u32 s40, 2
	s_cselect_b32 s20, s28, s20
	s_cmp_eq_u32 s40, 3
	s_cselect_b32 s20, s29, s20
	s_lshl_b32 s21, s20, 6
	s_mul_i32 s4, s40, 0x4800
	v_add_u32_e32 v190, s4, v102
	v_add_u32_e32 v191, s4, v104
	s_sub_i32 s4, s19, s21
	s_cmp_lt_i32 s4, 0
	s_cbranch_scc1 .Lsl3_diagx_9
	s_cmpk_lt_i32 s4, 0x316
	s_cbranch_scc1 .Lsl3_nearx_8
	v_lshrrev_b64 v[78:79], s20, v[18:19]
	v_and_b32_e32 v78, 1, v78
	v_cmp_eq_u32_e64 s[24:25], 1, v78
	s_cmp_eq_u64 s[24:25], 0
	s_cbranch_scc1 .Lsl3_skf_10
	ds_read_b128 v[198:201], v190 offset:16384
	ds_read_b128 v[206:209], v190 offset:18688
	ds_read_b128 v[202:205], v190 offset:16448
	ds_read_b128 v[210:213], v190 offset:18752
	ds_read_b128 v[214:217], v190 offset:20992
	ds_read_b128 v[222:225], v190 offset:23296
	ds_read_b128 v[218:221], v190 offset:21056
	ds_read_b128 v[226:229], v190 offset:23360
	s_waitcnt lgkmcnt(6)
	v_mfma_f32_16x16x32_bf16 v[54:57], v[198:201], v[2:5], 0
	v_mfma_f32_16x16x32_bf16 v[58:61], v[206:209], v[2:5], 0
	s_waitcnt lgkmcnt(4)
	v_mfma_f32_16x16x32_bf16 v[54:57], v[202:205], v[6:9], v[54:57]
	v_mfma_f32_16x16x32_bf16 v[58:61], v[210:213], v[6:9], v[58:61]
	s_waitcnt lgkmcnt(2)
	v_mfma_f32_16x16x32_bf16 v[62:65], v[214:217], v[2:5], 0
	v_mfma_f32_16x16x32_bf16 v[66:69], v[222:225], v[2:5], 0
	s_waitcnt lgkmcnt(0)
	v_mfma_f32_16x16x32_bf16 v[62:65], v[218:221], v[6:9], v[62:65]
	v_mfma_f32_16x16x32_bf16 v[66:69], v[226:229], v[6:9], v[66:69]
	ds_read_b64_tr_b16 v[198:199], v191 offset:25600
	ds_read_b64_tr_b16 v[200:201], v191 offset:27904
	ds_read_b64_tr_b16 v[202:203], v191 offset:30208
	ds_read_b64_tr_b16 v[204:205], v191 offset:32512
	ds_read_b64_tr_b16 v[206:207], v191 offset:25632
	ds_read_b64_tr_b16 v[208:209], v191 offset:27936
	ds_read_b64_tr_b16 v[210:211], v191 offset:30240
	ds_read_b64_tr_b16 v[212:213], v191 offset:32544
	ds_read_b64_tr_b16 v[214:215], v191 offset:25664
	ds_read_b64_tr_b16 v[216:217], v191 offset:27968
	ds_read_b64_tr_b16 v[218:219], v191 offset:30272
	ds_read_b64_tr_b16 v[220:221], v191 offset:32576
	ds_read_b64_tr_b16 v[222:223], v191 offset:25696
	ds_read_b64_tr_b16 v[224:225], v191 offset:28000
	ds_read_b64_tr_b16 v[226:227], v191 offset:30304
	ds_read_b64_tr_b16 v[228:229], v191 offset:32608
	v_max3_f32 v78, v54, v55, v56
	v_max3_f32 v79, v57, v58, v59
	v_max3_f32 v80, v60, v61, v62
	v_max3_f32 v81, v63, v64, v65
	v_max3_f32 v83, v66, v67, v68
	v_max3_f32 v78, v78, v79, v69
	v_max3_f32 v80, v80, v81, v83
	v_max_f32_e32 v78, v78, v80
	v_mov_b32_e32 v79, v78
	s_nop 1
	v_permlane16_swap_b32_e32 v78, v79
	v_max_f32_e32 v78, v78, v79
	v_mov_b32_e32 v79, v78
	s_nop 1
	v_permlane32_swap_b32_e32 v78, v79
	v_max_f32_e32 v78, v78, v79
	v_fmamk_f32 v78, v78, 0x3fb8aa3b, v92
	v_cndmask_b32_e64 v78, v243, v78, s[24:25]
	v_max_f32_e32 v80, v100, v78
	v_max_f32_e32 v82, 0xe0ad78ec, v100
	v_max_f32_e32 v81, 0xe0ad78ec, v80
	v_sub_f32_e32 v82, v82, v81
	v_mov_b32_e32 v100, v80
	v_exp_f32_e32 v82, v82
	v_sub_f32_e32 v83, v92, v81
	v_cndmask_b32_e64 v83, v243, v83, s[24:25]
	v_fmamk_f32 v54, v54, 0x3fb8aa3b, v83
	v_fmamk_f32 v55, v55, 0x3fb8aa3b, v83
	v_fmamk_f32 v56, v56, 0x3fb8aa3b, v83
	v_fmamk_f32 v57, v57, 0x3fb8aa3b, v83
	v_exp_f32_e32 v54, v54
	v_exp_f32_e32 v55, v55
	v_exp_f32_e32 v56, v56
	v_exp_f32_e32 v57, v57
	v_fmamk_f32 v58, v58, 0x3fb8aa3b, v83
	v_fmamk_f32 v59, v59, 0x3fb8aa3b, v83
	v_fmamk_f32 v60, v60, 0x3fb8aa3b, v83
	v_fmamk_f32 v61, v61, 0x3fb8aa3b, v83
	v_exp_f32_e32 v58, v58
	v_exp_f32_e32 v59, v59
	v_exp_f32_e32 v60, v60
	v_exp_f32_e32 v61, v61
	v_fmamk_f32 v62, v62, 0x3fb8aa3b, v83
	v_fmamk_f32 v63, v63, 0x3fb8aa3b, v83
	v_fmamk_f32 v64, v64, 0x3fb8aa3b, v83
	v_fmamk_f32 v65, v65, 0x3fb8aa3b, v83
	v_exp_f32_e32 v62, v62
	v_exp_f32_e32 v63, v63
	v_exp_f32_e32 v64, v64
	v_exp_f32_e32 v65, v65
	v_fmamk_f32 v66, v66, 0x3fb8aa3b, v83
	v_fmamk_f32 v67, v67, 0x3fb8aa3b, v83
	v_fmamk_f32 v68, v68, 0x3fb8aa3b, v83
	v_fmamk_f32 v69, v69, 0x3fb8aa3b, v83
	v_exp_f32_e32 v66, v66
	v_exp_f32_e32 v67, v67
	v_exp_f32_e32 v68, v68
	v_exp_f32_e32 v69, v69
	s_nop 0
	v_add_f32_e32 v78, v54, v55
	v_add_f32_e32 v79, v56, v57
	v_add_f32_e32 v80, v58, v59
	v_add_f32_e32 v81, v60, v61
	v_add_f32_e32 v78, v78, v62
	v_add_f32_e32 v79, v79, v63
	v_add_f32_e32 v80, v80, v64
	v_add_f32_e32 v81, v81, v65
	v_add_f32_e32 v78, v78, v66
	v_add_f32_e32 v79, v79, v67
	v_add_f32_e32 v80, v80, v68
	v_add_f32_e32 v81, v81, v69
	v_add_f32_e32 v78, v78, v79
	v_add_f32_e32 v80, v80, v81
	v_add_f32_e32 v78, v78, v80
	v_cvt_pk_bf16_f32 v70, v54, v55
	v_cvt_pk_bf16_f32 v71, v56, v57
	v_cvt_pk_bf16_f32 v72, v58, v59
	v_cvt_pk_bf16_f32 v73, v60, v61
	v_cvt_pk_bf16_f32 v74, v62, v63
	v_cvt_pk_bf16_f32 v75, v64, v65
	v_cvt_pk_bf16_f32 v76, v66, v67
	v_cvt_pk_bf16_f32 v77, v68, v69
	v_mov_b32_e32 v79, v78
	s_nop 1
	v_permlane16_swap_b32_e32 v78, v79
	v_add_f32_e32 v78, v78, v79
	v_mov_b32_e32 v79, v78
	s_nop 1
	v_permlane32_swap_b32_e32 v78, v79
	v_add_f32_e32 v78, v78, v79
	v_fma_f32 v106, v106, v82, v78
	v_cmp_neq_f32_e64 s[4:5], 1.0, v82
	s_cmp_eq_u64 s[4:5], 0
	s_cbranch_scc1 .Lsl3_nosc_11
	v_pk_mul_f32 v[38:39], v[38:39], v[82:83] op_sel_hi:[1,0]
	v_pk_mul_f32 v[40:41], v[40:41], v[82:83] op_sel_hi:[1,0]
	v_pk_mul_f32 v[42:43], v[42:43], v[82:83] op_sel_hi:[1,0]
	v_pk_mul_f32 v[44:45], v[44:45], v[82:83] op_sel_hi:[1,0]
	v_pk_mul_f32 v[46:47], v[46:47], v[82:83] op_sel_hi:[1,0]
	v_pk_mul_f32 v[48:49], v[48:49], v[82:83] op_sel_hi:[1,0]
	v_pk_mul_f32 v[50:51], v[50:51], v[82:83] op_sel_hi:[1,0]
	v_pk_mul_f32 v[52:53], v[52:53], v[82:83] op_sel_hi:[1,0]

; template <int D, class SF>
; __device__ __forceinline__ void attn_step(const bf16x8 (&qf)[D / 32], const LAS bf16_t* Ks, const LAS bf16_t* Vt, f32x4 (&o)[D / 16], float& m, float& lsum, float& alpha_out, bf16x8& pf0_out, bf16x8& pf1_out, const int lane, SF sf) {
;     constexpr int KSTR = D + 8;
;     const int c = lane & 15, i = lane >> 4;
;     f32x4 s[4];
; #pragma unroll
;     for (int t = 0; t < 4; ++t) s[t] = (f32x4){0.f, 0.f, 0.f, 0.f};
; #pragma unroll
;     for (int ks = 0; ks < D / 32; ++ks) {
; #pragma unroll
;         for (int t = 0; t < 4; ++t) { const bf16x8 kf = *(const LAS bf16x8*)(Ks + (16 * t + c) * KSTR + ks * 32 + 8 * i); s[t] = mfma16(kf, qf[ks], s[t]); }
;     }
;     float v[16];
; #pragma unroll
;     for (int t = 0; t < 4; ++t)
; #pragma unroll
;         for (int r = 0; r < 4; ++r) v[4 * t + r] = sf(16 * t + 4 * i + r, s[t][r]);
;     float mx = fmaxf(fmaxf(fmaxf(v[0], v[1]), fmaxf(v[2], v[3])), fmaxf(fmaxf(v[4], v[5]), fmaxf(v[6], v[7])));
;     mx = fmaxf(mx, fmaxf(fmaxf(fmaxf(v[8], v[9]), fmaxf(v[10], v[11])), fmaxf(fmaxf(v[12], v[13]), fmaxf(v[14], v[15]))));
;     mx = rows_max(mx);
;     const float mnew = fmaxf(m, mx);
;     const float mc = fmaxf(mnew, -1e20f);
;     const float alpha = __builtin_amdgcn_exp2f(fmaxf(m, -1e20f) - mc);
;     float p[16], rs = 0.f;
; #pragma unroll
;     for (int r = 0; r < 16; ++r) { p[r] = __builtin_amdgcn_exp2f(v[r] - mc); rs += p[r]; }
;     rs = rows_sum(rs);
;     lsum = lsum * alpha + rs; m = mnew;
;     union { u32x4 u; bf16x8 b; } pk0, pk1;
;     pk0.u.x = cvt_pk_bf16(p[0], p[1]); pk0.u.y = cvt_pk_bf16(p[2], p[3]); pk0.u.z = cvt_pk_bf16(p[4], p[5]); pk0.u.w = cvt_pk_bf16(p[6], p[7]);
;     pk1.u.x = cvt_pk_bf16(p[8], p[9]); pk1.u.y = cvt_pk_bf16(p[10], p[11]); pk1.u.z = cvt_pk_bf16(p[12], p[13]); pk1.u.w = cvt_pk_bf16(p[14], p[15]);
; __device__ __forceinline__ void nsa_unit(LAS unsigned char* lds, const Ctx& P, int l, int b, int hkv, int tb) {
;     ...
;                 for (int sb = 0; sb < 2; ++sb) { const bool selj = (ms[sb] >> j) & 1ull; const int tqs = tq[sb];
;                     if (far) {
;                         if (__builtin_amdgcn_ballot_w64(selj) == 0ull) continue;
;                         attn_step<64>(qf[sb], Ks, Vt, o[sb], m[sb], lsum[sb], alpha, pf, pf1, lane,
;                             [&](int, float s) { return selj ? s * LOG2E + cfar : NEGBIG; });
.Lsl3_skf_10:
	v_lshrrev_b64 v[78:79], s20, v[20:21]
	v_and_b32_e32 v78, 1, v78
	v_cmp_eq_u32_e64 s[24:25], 1, v78
	s_cmp_eq_u64 s[24:25], 0
	s_cbranch_scc1 .Lsl3_skf_12
	ds_read_b128 v[198:201], v190 offset:16384
	ds_read_b128 v[206:209], v190 offset:18688
	ds_read_b128 v[202:205], v190 offset:16448
	ds_read_b128 v[210:213], v190 offset:18752
	ds_read_b128 v[214:217], v190 offset:20992
	ds_read_b128 v[222:225], v190 offset:23296
	ds_read_b128 v[218:221], v190 offset:21056
	ds_read_b128 v[226:229], v190 offset:23360
	s_waitcnt lgkmcnt(6)
	v_mfma_f32_16x16x32_bf16 v[54:57], v[198:201], v[10:13], 0
	v_mfma_f32_16x16x32_bf16 v[58:61], v[206:209], v[10:13], 0
	s_waitcnt lgkmcnt(4)
	v_mfma_f32_16x16x32_bf16 v[54:57], v[202:205], v[14:17], v[54:57]
	v_mfma_f32_16x16x32_bf16 v[58:61], v[210:213], v[14:17], v[58:61]
	s_waitcnt lgkmcnt(2)
	v_mfma_f32_16x16x32_bf16 v[62:65], v[214:217], v[10:13], 0
	v_mfma_f32_16x16x32_bf16 v[66:69], v[222:225], v[10:13], 0
	s_waitcnt lgkmcnt(0)
	v_mfma_f32_16x16x32_bf16 v[62:65], v[218:221], v[14:17], v[62:65]
	v_mfma_f32_16x16x32_bf16 v[66:69], v[226:229], v[14:17], v[66:69]
	ds_read_b64_tr_b16 v[198:199], v191 offset:25600
	ds_read_b64_tr_b16 v[200:201], v191 offset:27904
	ds_read_b64_tr_b16 v[202:203], v191 offset:30208
	ds_read_b64_tr_b16 v[204:205], v191 offset:32512
	ds_read_b64_tr_b16 v[206:207], v191 offset:25632
	ds_read_b64_tr_b16 v[208:209], v191 offset:27936
	ds_read_b64_tr_b16 v[210:211], v191 offset:30240
	ds_read_b64_tr_b16 v[212:213], v191 offset:32544
	ds_read_b64_tr_b16 v[214:215], v191 offset:25664
	ds_read_b64_tr_b16 v[216:217], v191 offset:27968
	ds_read_b64_tr_b16 v[218:219], v191 offset:30272
	ds_read_b64_tr_b16 v[220:221], v191 offset:32576
	ds_read_b64_tr_b16 v[222:223], v191 offset:25696
	ds_read_b64_tr_b16 v[224:225], v191 offset:28000
	ds_read_b64_tr_b16 v[226:227], v191 offset:30304
	ds_read_b64_tr_b16 v[228:229], v191 offset:32608
	v_max3_f32 v78, v54, v55, v56
	v_max3_f32 v79, v57, v58, v59
	v_max3_f32 v80, v60, v61, v62
	v_max3_f32 v81, v63, v64, v65
	v_max3_f32 v83, v66, v67, v68
	v_max3_f32 v78, v78, v79, v69
	v_max3_f32 v80, v80, v81, v83
	v_max_f32_e32 v78, v78, v80
	v_mov_b32_e32 v79, v78
	s_nop 1
	v_permlane16_swap_b32_e32 v78, v79
	v_max_f32_e32 v78, v78, v79
	v_mov_b32_e32 v79, v78
	s_nop 1
	v_permlane32_swap_b32_e32 v78, v79
	v_max_f32_e32 v78, v78, v79
	v_fmamk_f32 v78, v78, 0x3fb8aa3b, v92
	v_cndmask_b32_e64 v78, v243, v78, s[24:25]
	v_max_f32_e32 v80, v93, v78
	v_max_f32_e32 v82, 0xe0ad78ec, v93
	v_max_f32_e32 v81, 0xe0ad78ec, v80
	v_sub_f32_e32 v82, v82, v81
	v_mov_b32_e32 v93, v80
	v_exp_f32_e32 v82, v82
	v_sub_f32_e32 v83, v92, v81
	v_cndmask_b32_e64 v83, v243, v83, s[24:25]
	v_fmamk_f32 v54, v54, 0x3fb8aa3b, v83
	v_fmamk_f32 v55, v55, 0x3fb8aa3b, v83
	v_fmamk_f32 v56, v56, 0x3fb8aa3b, v83
	v_fmamk_f32 v57, v57, 0x3fb8aa3b, v83
	v_exp_f32_e32 v54, v54
	v_exp_f32_e32 v55, v55
	v_exp_f32_e32 v56, v56
	v_exp_f32_e32 v57, v57
	v_fmamk_f32 v58, v58, 0x3fb8aa3b, v83
	v_fmamk_f32 v59, v59, 0x3fb8aa3b, v83
	v_fmamk_f32 v60, v60, 0x3fb8aa3b, v83
	v_fmamk_f32 v61, v61, 0x3fb8aa3b, v83
	v_exp_f32_e32 v58, v58
	v_exp_f32_e32 v59, v59
	v_exp_f32_e32 v60, v60
	v_exp_f32_e32 v61, v61
	v_fmamk_f32 v62, v62, 0x3fb8aa3b, v83
	v_fmamk_f32 v63, v63, 0x3fb8aa3b, v83
	v_fmamk_f32 v64, v64, 0x3fb8aa3b, v83
	v_fmamk_f32 v65, v65, 0x3fb8aa3b, v83
	v_exp_f32_e32 v62, v62
	v_exp_f32_e32 v63, v63
	v_exp_f32_e32 v64, v64
	v_exp_f32_e32 v65, v65
	v_fmamk_f32 v66, v66, 0x3fb8aa3b, v83
	v_fmamk_f32 v67, v67, 0x3fb8aa3b, v83
	v_fmamk_f32 v68, v68, 0x3fb8aa3b, v83
	v_fmamk_f32 v69, v69, 0x3fb8aa3b, v83
	v_exp_f32_e32 v66, v66
	v_exp_f32_e32 v67, v67
	v_exp_f32_e32 v68, v68
	v_exp_f32_e32 v69, v69
	s_nop 0
	v_add_f32_e32 v78, v54, v55
	v_add_f32_e32 v79, v56, v57
	v_add_f32_e32 v80, v58, v59
	v_add_f32_e32 v81, v60, v61
	v_add_f32_e32 v78, v78, v62
	v_add_f32_e32 v79, v79, v63
	v_add_f32_e32 v80, v80, v64
	v_add_f32_e32 v81, v81, v65
	v_add_f32_e32 v78, v78, v66
	v_add_f32_e32 v79, v79, v67
	v_add_f32_e32 v80, v80, v68
	v_add_f32_e32 v81, v81, v69
	v_add_f32_e32 v78, v78, v79
	v_add_f32_e32 v80, v80, v81
	v_add_f32_e32 v78, v78, v80
	v_cvt_pk_bf16_f32 v70, v54, v55
	v_cvt_pk_bf16_f32 v71, v56, v57
	v_cvt_pk_bf16_f32 v72, v58, v59
	v_cvt_pk_bf16_f32 v73, v60, v61
	v_cvt_pk_bf16_f32 v74, v62, v63
	v_cvt_pk_bf16_f32 v75, v64, v65
	v_cvt_pk_bf16_f32 v76, v66, v67
	v_cvt_pk_bf16_f32 v77, v68, v69
	v_mov_b32_e32 v79, v78
	s_nop 1
	v_permlane16_swap_b32_e32 v78, v79
	v_add_f32_e32 v78, v78, v79
	v_mov_b32_e32 v79, v78
	s_nop 1
	v_permlane32_swap_b32_e32 v78, v79
	v_add_f32_e32 v78, v78, v79
	v_fma_f32 v105, v105, v82, v78
	v_cmp_neq_f32_e64 s[4:5], 1.0, v82
	s_cmp_eq_u64 s[4:5], 0
	s_cbranch_scc1 .Lsl3_nosc_13
	v_pk_mul_f32 v[22:23], v[22:23], v[82:83] op_sel_hi:[1,0]
	v_pk_mul_f32 v[24:25], v[24:25], v[82:83] op_sel_hi:[1,0]
	v_pk_mul_f32 v[26:27], v[26:27], v[82:83] op_sel_hi:[1,0]
	v_pk_mul_f32 v[28:29], v[28:29], v[82:83] op_sel_hi:[1,0]
	v_pk_mul_f32 v[34:35], v[34:35], v[82:83] op_sel_hi:[1,0]
	v_pk_mul_f32 v[36:37], v[36:37], v[82:83] op_sel_hi:[1,0]
	v_pk_mul_f32 v[30:31], v[30:31], v[82:83] op_sel_hi:[1,0]
	v_pk_mul_f32 v[32:33], v[32:33], v[82:83] op_sel_hi:[1,0]

; template <int D, class SF>
; __device__ __forceinline__ void attn_step(const bf16x8 (&qf)[D / 32], const LAS bf16_t* Ks, const LAS bf16_t* Vt, f32x4 (&o)[D / 16], float& m, float& lsum, float& alpha_out, bf16x8& pf0_out, bf16x8& pf1_out, const int lane, SF sf) {
;     constexpr int KSTR = D + 8;
;     const int c = lane & 15, i = lane >> 4;
;     f32x4 s[4];
; #pragma unroll
;     for (int t = 0; t < 4; ++t) s[t] = (f32x4){0.f, 0.f, 0.f, 0.f};
; #pragma unroll
;     for (int ks = 0; ks < D / 32; ++ks) {
; #pragma unroll
;         for (int t = 0; t < 4; ++t) { const bf16x8 kf = *(const LAS bf16x8*)(Ks + (16 * t + c) * KSTR + ks * 32 + 8 * i); s[t] = mfma16(kf, qf[ks], s[t]); }
;     }
;     float v[16];
; #pragma unroll
;     for (int t = 0; t < 4; ++t)
; #pragma unroll
;         for (int r = 0; r < 4; ++r) v[4 * t + r] = sf(16 * t + 4 * i + r, s[t][r]);
;     float mx = fmaxf(fmaxf(fmaxf(v[0], v[1]), fmaxf(v[2], v[3])), fmaxf(fmaxf(v[4], v[5]), fmaxf(v[6], v[7])));
;     mx = fmaxf(mx, fmaxf(fmaxf(fmaxf(v[8], v[9]), fmaxf(v[10], v[11])), fmaxf(fmaxf(v[12], v[13]), fmaxf(v[14], v[15]))));
;     mx = rows_max(mx);
;     const float mnew = fmaxf(m, mx);
;     const float mc = fmaxf(mnew, -1e20f);
;     const float alpha = __builtin_amdgcn_exp2f(fmaxf(m, -1e20f) - mc);
;     float p[16], rs = 0.f;
; #pragma unroll
;     for (int r = 0; r < 16; ++r) { p[r] = __builtin_amdgcn_exp2f(v[r] - mc); rs += p[r]; }
;     rs = rows_sum(rs);
;     lsum = lsum * alpha + rs; m = mnew;
;     union { u32x4 u; bf16x8 b; } pk0, pk1;
;     pk0.u.x = cvt_pk_bf16(p[0], p[1]); pk0.u.y = cvt_pk_bf16(p[2], p[3]); pk0.u.z = cvt_pk_bf16(p[4], p[5]); pk0.u.w = cvt_pk_bf16(p[6], p[7]);
;     pk1.u.x = cvt_pk_bf16(p[8], p[9]); pk1.u.y = cvt_pk_bf16(p[10], p[11]); pk1.u.z = cvt_pk_bf16(p[12], p[13]); pk1.u.w = cvt_pk_bf16(p[14], p[15]);
;     if (__builtin_amdgcn_ballot_w64(alpha != 1.0f) != 0ull) {
; #pragma unroll
; __device__ __forceinline__ void nsa_unit(LAS unsigned char* lds, const Ctx& P, int l, int b, int hkv, int tb) {
;     ...
;                     } else { const int kp0 = j * 64;
;                         attn_step<64>(qf[sb], Ks, Vt, o[sb], m[sb], lsum[sb], alpha, pf, pf1, lane,
;                             [&](int kk, float s) { const int dist = tqs - (kp0 + kk); return (selj && dist >= 0) ? s * LOG2E + lut[min((unsigned)dist, 1023u)] : NEGBIG; });
.Lsl3_nearx_8:
	v_lshrrev_b64 v[78:79], s20, v[18:19]
	v_and_b32_e32 v78, 1, v78
	v_cmp_eq_u32_e64 s[24:25], 1, v78
	s_cmp_eq_u64 s[24:25], 0
	s_cbranch_scc1 .Lsl3_skn_14
	v_sub_u32_e32 v78, v130, v139
	v_subrev_u32_e32 v78, s21, v78
	v_lshl_add_u32 v79, v78, 2, v131
	v_add_u32_e32 v79, 0xffffff34, v79
	ds_read_b32 v107, v79 offset:204
	ds_read_b32 v108, v79 offset:200
	ds_read_b32 v109, v79 offset:196
	ds_read_b32 v110, v79 offset:192
	ds_read_b32 v111, v79 offset:140
	ds_read_b32 v112, v79 offset:136
	ds_read_b32 v113, v79 offset:132
	ds_read_b32 v133, v79 offset:128
	ds_read_b128 v[198:201], v190 offset:16384
	ds_read_b128 v[206:209], v190 offset:18688
	ds_read_b128 v[202:205], v190 offset:16448
	ds_read_b128 v[210:213], v190 offset:18752
	ds_read_b128 v[214:217], v190 offset:20992
	ds_read_b128 v[222:225], v190 offset:23296
	ds_read_b128 v[218:221], v190 offset:21056
	ds_read_b128 v[226:229], v190 offset:23360
	s_waitcnt lgkmcnt(6)
	v_mfma_f32_16x16x32_bf16 v[54:57], v[198:201], v[2:5], 0
	v_mfma_f32_16x16x32_bf16 v[58:61], v[206:209], v[2:5], 0
	s_waitcnt lgkmcnt(4)
	v_mfma_f32_16x16x32_bf16 v[54:57], v[202:205], v[6:9], v[54:57]
	v_mfma_f32_16x16x32_bf16 v[58:61], v[210:213], v[6:9], v[58:61]
	s_waitcnt lgkmcnt(2)
	v_mfma_f32_16x16x32_bf16 v[62:65], v[214:217], v[2:5], 0
	v_mfma_f32_16x16x32_bf16 v[66:69], v[222:225], v[2:5], 0
	s_waitcnt lgkmcnt(0)
	v_mfma_f32_16x16x32_bf16 v[62:65], v[218:221], v[6:9], v[62:65]
	v_mfma_f32_16x16x32_bf16 v[66:69], v[226:229], v[6:9], v[66:69]
	ds_read_b64_tr_b16 v[198:199], v191 offset:25600
	ds_read_b64_tr_b16 v[200:201], v191 offset:27904
	ds_read_b64_tr_b16 v[202:203], v191 offset:30208
	ds_read_b64_tr_b16 v[204:205], v191 offset:32512
	ds_read_b64_tr_b16 v[206:207], v191 offset:25632
	ds_read_b64_tr_b16 v[208:209], v191 offset:27936
	ds_read_b64_tr_b16 v[210:211], v191 offset:30240
	v_fmamk_f32 v54, v54, 0x3fb8aa3b, v107
	v_fmamk_f32 v55, v55, 0x3fb8aa3b, v108
	v_fmamk_f32 v56, v56, 0x3fb8aa3b, v109
	v_fmamk_f32 v57, v57, 0x3fb8aa3b, v110
	v_fmamk_f32 v58, v58, 0x3fb8aa3b, v111
	v_fmamk_f32 v59, v59, 0x3fb8aa3b, v112
	v_fmamk_f32 v60, v60, 0x3fb8aa3b, v113
	v_fmamk_f32 v61, v61, 0x3fb8aa3b, v133
	ds_read_b32 v107, v79 offset:76
	ds_read_b32 v108, v79 offset:72
	ds_read_b32 v109, v79 offset:68
	ds_read_b32 v110, v79 offset:64
	ds_read_b32 v111, v79 offset:12
	ds_read_b32 v112, v79 offset:8
	ds_read_b32 v113, v79 offset:4
	ds_read_b32 v133, v79 offset:0
	ds_read_b64_tr_b16 v[212:213], v191 offset:32544
	ds_read_b64_tr_b16 v[214:215], v191 offset:25664
	ds_read_b64_tr_b16 v[216:217], v191 offset:27968
	ds_read_b64_tr_b16 v[218:219], v191 offset:30272
	ds_read_b64_tr_b16 v[220:221], v191 offset:32576
	ds_read_b64_tr_b16 v[222:223], v191 offset:25696
	ds_read_b64_tr_b16 v[224:225], v191 offset:28000
	ds_read_b64_tr_b16 v[226:227], v191 offset:30304
	ds_read_b64_tr_b16 v[228:229], v191 offset:32608
	s_waitcnt lgkmcnt(9)
	v_fmamk_f32 v62, v62, 0x3fb8aa3b, v107
	v_fmamk_f32 v63, v63, 0x3fb8aa3b, v108
	v_fmamk_f32 v64, v64, 0x3fb8aa3b, v109
	v_fmamk_f32 v65, v65, 0x3fb8aa3b, v110
	v_fmamk_f32 v66, v66, 0x3fb8aa3b, v111
	v_fmamk_f32 v67, v67, 0x3fb8aa3b, v112
	v_fmamk_f32 v68, v68, 0x3fb8aa3b, v113
	v_fmamk_f32 v69, v69, 0x3fb8aa3b, v133
	v_max3_f32 v84, v54, v55, v56
	v_max3_f32 v79, v57, v58, v59
	v_max3_f32 v80, v60, v61, v62
	v_max3_f32 v81, v63, v64, v65
	v_max3_f32 v83, v66, v67, v68
	v_max3_f32 v84, v84, v79, v69
	v_max3_f32 v80, v80, v81, v83
	v_max_f32_e32 v84, v84, v80
	v_mov_b32_e32 v79, v84
	s_nop 1
	v_permlane16_swap_b32_e32 v84, v79
	v_max_f32_e32 v84, v84, v79
	v_mov_b32_e32 v79, v84
	s_nop 1
	v_permlane32_swap_b32_e32 v84, v79
	v_max_f32_e32 v84, v84, v79
	v_cndmask_b32_e64 v84, v243, v84, s[24:25]
	v_max_f32_e32 v80, v100, v84
	v_max_f32_e32 v82, 0xe0ad78ec, v100
	v_max_f32_e32 v81, 0xe0ad78ec, v80
	v_sub_f32_e32 v82, v82, v81
	v_mov_b32_e32 v100, v80
	v_exp_f32_e32 v82, v82
	v_mov_b32_e32 v83, 0x7149f2ca
	v_cndmask_b32_e64 v83, v83, v81, s[24:25]
	v_sub_f32_e32 v54, v54, v83
	v_sub_f32_e32 v55, v55, v83
	v_sub_f32_e32 v56, v56, v83
	v_sub_f32_e32 v57, v57, v83
	v_exp_f32_e32 v54, v54
	v_exp_f32_e32 v55, v55
	v_exp_f32_e32 v56, v56
	v_exp_f32_e32 v57, v57
	v_sub_f32_e32 v58, v58, v83
	v_sub_f32_e32 v59, v59, v83
	v_sub_f32_e32 v60, v60, v83
	v_sub_f32_e32 v61, v61, v83
	v_exp_f32_e32 v58, v58
	v_exp_f32_e32 v59, v59
	v_exp_f32_e32 v60, v60
	v_exp_f32_e32 v61, v61
	v_sub_f32_e32 v62, v62, v83
	v_sub_f32_e32 v63, v63, v83
	v_sub_f32_e32 v64, v64, v83
	v_sub_f32_e32 v65, v65, v83
	v_exp_f32_e32 v62, v62
	v_exp_f32_e32 v63, v63
	v_exp_f32_e32 v64, v64
	v_exp_f32_e32 v65, v65
	v_sub_f32_e32 v66, v66, v83
	v_sub_f32_e32 v67, v67, v83
	v_sub_f32_e32 v68, v68, v83
	v_sub_f32_e32 v69, v69, v83
	v_exp_f32_e32 v66, v66
	v_exp_f32_e32 v67, v67
	v_exp_f32_e32 v68, v68
	v_exp_f32_e32 v69, v69
	s_nop 0
	v_add_f32_e32 v78, v54, v55
	v_add_f32_e32 v79, v56, v57
	v_add_f32_e32 v80, v58, v59
	v_add_f32_e32 v81, v60, v61
	v_add_f32_e32 v78, v78, v62
	v_add_f32_e32 v79, v79, v63
	v_add_f32_e32 v80, v80, v64
	v_add_f32_e32 v81, v81, v65
	v_add_f32_e32 v78, v78, v66
	v_add_f32_e32 v79, v79, v67
	v_add_f32_e32 v80, v80, v68
	v_add_f32_e32 v81, v81, v69
	v_add_f32_e32 v78, v78, v79
	v_add_f32_e32 v80, v80, v81
	v_add_f32_e32 v78, v78, v80
	v_cvt_pk_bf16_f32 v70, v54, v55
	v_cvt_pk_bf16_f32 v71, v56, v57
	v_cvt_pk_bf16_f32 v72, v58, v59
	v_cvt_pk_bf16_f32 v73, v60, v61
	v_cvt_pk_bf16_f32 v74, v62, v63
	v_cvt_pk_bf16_f32 v75, v64, v65
	v_cvt_pk_bf16_f32 v76, v66, v67
	v_cvt_pk_bf16_f32 v77, v68, v69
	v_mov_b32_e32 v79, v78
	s_nop 1
	v_permlane16_swap_b32_e32 v78, v79
	v_add_f32_e32 v78, v78, v79
	v_mov_b32_e32 v79, v78
	s_nop 1
	v_permlane32_swap_b32_e32 v78, v79
	v_add_f32_e32 v78, v78, v79
	v_fma_f32 v106, v106, v82, v78
	v_cmp_neq_f32_e64 s[4:5], 1.0, v82
	s_cmp_eq_u64 s[4:5], 0
	s_cbranch_scc1 .Lsl3_nosc_15
	v_pk_mul_f32 v[38:39], v[38:39], v[82:83] op_sel_hi:[1,0]
	v_pk_mul_f32 v[40:41], v[40:41], v[82:83] op_sel_hi:[1,0]
	v_pk_mul_f32 v[42:43], v[42:43], v[82:83] op_sel_hi:[1,0]
	v_pk_mul_f32 v[44:45], v[44:45], v[82:83] op_sel_hi:[1,0]
	v_pk_mul_f32 v[46:47], v[46:47], v[82:83] op_sel_hi:[1,0]
	v_pk_mul_f32 v[48:49], v[48:49], v[82:83] op_sel_hi:[1,0]
	v_pk_mul_f32 v[50:51], v[50:51], v[82:83] op_sel_hi:[1,0]
	v_pk_mul_f32 v[52:53], v[52:53], v[82:83] op_sel_hi:[1,0]

; template <int D, class SF>
; __device__ __forceinline__ void attn_step(const bf16x8 (&qf)[D / 32], const LAS bf16_t* Ks, const LAS bf16_t* Vt, f32x4 (&o)[D / 16], float& m, float& lsum, float& alpha_out, bf16x8& pf0_out, bf16x8& pf1_out, const int lane, SF sf) {
;     constexpr int KSTR = D + 8;
;     const int c = lane & 15, i = lane >> 4;
;     f32x4 s[4];
; #pragma unroll
;     for (int t = 0; t < 4; ++t) s[t] = (f32x4){0.f, 0.f, 0.f, 0.f};
; #pragma unroll
;     for (int ks = 0; ks < D / 32; ++ks) {
; #pragma unroll
;         for (int t = 0; t < 4; ++t) { const bf16x8 kf = *(const LAS bf16x8*)(Ks + (16 * t + c) * KSTR + ks * 32 + 8 * i); s[t] = mfma16(kf, qf[ks], s[t]); }
;     }
;     float v[16];
; #pragma unroll
;     for (int t = 0; t < 4; ++t)
; #pragma unroll
;         for (int r = 0; r < 4; ++r) v[4 * t + r] = sf(16 * t + 4 * i + r, s[t][r]);
;     float mx = fmaxf(fmaxf(fmaxf(v[0], v[1]), fmaxf(v[2], v[3])), fmaxf(fmaxf(v[4], v[5]), fmaxf(v[6], v[7])));
;     mx = fmaxf(mx, fmaxf(fmaxf(fmaxf(v[8], v[9]), fmaxf(v[10], v[11])), fmaxf(fmaxf(v[12], v[13]), fmaxf(v[14], v[15]))));
;     mx = rows_max(mx);
;     const float mnew = fmaxf(m, mx);
;     const float mc = fmaxf(mnew, -1e20f);
;     const float alpha = __builtin_amdgcn_exp2f(fmaxf(m, -1e20f) - mc);
;     float p[16], rs = 0.f;
; #pragma unroll
;     for (int r = 0; r < 16; ++r) { p[r] = __builtin_amdgcn_exp2f(v[r] - mc); rs += p[r]; }
;     rs = rows_sum(rs);
;     lsum = lsum * alpha + rs; m = mnew;
;     union { u32x4 u; bf16x8 b; } pk0, pk1;
;     pk0.u.x = cvt_pk_bf16(p[0], p[1]); pk0.u.y = cvt_pk_bf16(p[2], p[3]); pk0.u.z = cvt_pk_bf16(p[4], p[5]); pk0.u.w = cvt_pk_bf16(p[6], p[7]);
;     pk1.u.x = cvt_pk_bf16(p[8], p[9]); pk1.u.y = cvt_pk_bf16(p[10], p[11]); pk1.u.z = cvt_pk_bf16(p[12], p[13]); pk1.u.w = cvt_pk_bf16(p[14], p[15]);
;     if (__builtin_amdgcn_ballot_w64(alpha != 1.0f) != 0ull) {
; #pragma unroll
; __device__ __forceinline__ void nsa_unit(LAS unsigned char* lds, const Ctx& P, int l, int b, int hkv, int tb) {
;     ...
;                     } else { const int kp0 = j * 64;
;                         attn_step<64>(qf[sb], Ks, Vt, o[sb], m[sb], lsum[sb], alpha, pf, pf1, lane,
;                             [&](int kk, float s) { const int dist = tqs - (kp0 + kk); return (selj && dist >= 0) ? s * LOG2E + lut[min((unsigned)dist, 1023u)] : NEGBIG; });
.Lsl3_skn_14:
	v_lshrrev_b64 v[78:79], s20, v[20:21]
	v_and_b32_e32 v78, 1, v78
	v_cmp_eq_u32_e64 s[24:25], 1, v78
	s_cmp_eq_u64 s[24:25], 0
	s_cbranch_scc1 .Lsl3_skn_16
	v_sub_u32_e32 v78, v98, v139
	v_subrev_u32_e32 v78, s21, v78
	v_lshl_add_u32 v79, v78, 2, v131
	v_add_u32_e32 v79, 0xffffff34, v79
	ds_read_b32 v107, v79 offset:204
	ds_read_b32 v108, v79 offset:200
	ds_read_b32 v109, v79 offset:196
	ds_read_b32 v110, v79 offset:192
	ds_read_b32 v111, v79 offset:140
	ds_read_b32 v112, v79 offset:136
	ds_read_b32 v113, v79 offset:132
	ds_read_b32 v133, v79 offset:128
	ds_read_b128 v[198:201], v190 offset:16384
	ds_read_b128 v[206:209], v190 offset:18688
	ds_read_b128 v[202:205], v190 offset:16448
	ds_read_b128 v[210:213], v190 offset:18752
	ds_read_b128 v[214:217], v190 offset:20992
	ds_read_b128 v[222:225], v190 offset:23296
	ds_read_b128 v[218:221], v190 offset:21056
	ds_read_b128 v[226:229], v190 offset:23360
	s_waitcnt lgkmcnt(6)
	v_mfma_f32_16x16x32_bf16 v[54:57], v[198:201], v[10:13], 0
	v_mfma_f32_16x16x32_bf16 v[58:61], v[206:209], v[10:13], 0
	s_waitcnt lgkmcnt(4)
	v_mfma_f32_16x16x32_bf16 v[54:57], v[202:205], v[14:17], v[54:57]
	v_mfma_f32_16x16x32_bf16 v[58:61], v[210:213], v[14:17], v[58:61]
	s_waitcnt lgkmcnt(2)
	v_mfma_f32_16x16x32_bf16 v[62:65], v[214:217], v[10:13], 0
	v_mfma_f32_16x16x32_bf16 v[66:69], v[222:225], v[10:13], 0
	s_waitcnt lgkmcnt(0)
	v_mfma_f32_16x16x32_bf16 v[62:65], v[218:221], v[14:17], v[62:65]
	v_mfma_f32_16x16x32_bf16 v[66:69], v[226:229], v[14:17], v[66:69]
	ds_read_b64_tr_b16 v[198:199], v191 offset:25600
	ds_read_b64_tr_b16 v[200:201], v191 offset:27904
	ds_read_b64_tr_b16 v[202:203], v191 offset:30208
	ds_read_b64_tr_b16 v[204:205], v191 offset:32512
	ds_read_b64_tr_b16 v[206:207], v191 offset:25632
	ds_read_b64_tr_b16 v[208:209], v191 offset:27936
	ds_read_b64_tr_b16 v[210:211], v191 offset:30240
	v_fmamk_f32 v54, v54, 0x3fb8aa3b, v107
	v_fmamk_f32 v55, v55, 0x3fb8aa3b, v108
	v_fmamk_f32 v56, v56, 0x3fb8aa3b, v109
	v_fmamk_f32 v57, v57, 0x3fb8aa3b, v110
	v_fmamk_f32 v58, v58, 0x3fb8aa3b, v111
	v_fmamk_f32 v59, v59, 0x3fb8aa3b, v112
	v_fmamk_f32 v60, v60, 0x3fb8aa3b, v113
	v_fmamk_f32 v61, v61, 0x3fb8aa3b, v133
	ds_read_b32 v107, v79 offset:76
	ds_read_b32 v108, v79 offset:72
	ds_read_b32 v109, v79 offset:68
	ds_read_b32 v110, v79 offset:64
	ds_read_b32 v111, v79 offset:12
	ds_read_b32 v112, v79 offset:8
	ds_read_b32 v113, v79 offset:4
	ds_read_b32 v133, v79 offset:0
	ds_read_b64_tr_b16 v[212:213], v191 offset:32544
	ds_read_b64_tr_b16 v[214:215], v191 offset:25664
	ds_read_b64_tr_b16 v[216:217], v191 offset:27968
	ds_read_b64_tr_b16 v[218:219], v191 offset:30272
	ds_read_b64_tr_b16 v[220:221], v191 offset:32576
	ds_read_b64_tr_b16 v[222:223], v191 offset:25696
	ds_read_b64_tr_b16 v[224:225], v191 offset:28000
	ds_read_b64_tr_b16 v[226:227], v191 offset:30304
	ds_read_b64_tr_b16 v[228:229], v191 offset:32608
	s_waitcnt lgkmcnt(9)
	v_fmamk_f32 v62, v62, 0x3fb8aa3b, v107
	v_fmamk_f32 v63, v63, 0x3fb8aa3b, v108
	v_fmamk_f32 v64, v64, 0x3fb8aa3b, v109
	v_fmamk_f32 v65, v65, 0x3fb8aa3b, v110
	v_fmamk_f32 v66, v66, 0x3fb8aa3b, v111
	v_fmamk_f32 v67, v67, 0x3fb8aa3b, v112
	v_fmamk_f32 v68, v68, 0x3fb8aa3b, v113
	v_fmamk_f32 v69, v69, 0x3fb8aa3b, v133
	v_max3_f32 v84, v54, v55, v56
	v_max3_f32 v79, v57, v58, v59
	v_max3_f32 v80, v60, v61, v62
	v_max3_f32 v81, v63, v64, v65
	v_max3_f32 v83, v66, v67, v68
	v_max3_f32 v84, v84, v79, v69
	v_max3_f32 v80, v80, v81, v83
	v_max_f32_e32 v84, v84, v80
	v_mov_b32_e32 v79, v84
	s_nop 1
	v_permlane16_swap_b32_e32 v84, v79
	v_max_f32_e32 v84, v84, v79
	v_mov_b32_e32 v79, v84
	s_nop 1
	v_permlane32_swap_b32_e32 v84, v79
	v_max_f32_e32 v84, v84, v79
	v_cndmask_b32_e64 v84, v243, v84, s[24:25]
	v_max_f32_e32 v80, v93, v84
	v_max_f32_e32 v82, 0xe0ad78ec, v93
	v_max_f32_e32 v81, 0xe0ad78ec, v80
	v_sub_f32_e32 v82, v82, v81
	v_mov_b32_e32 v93, v80
	v_exp_f32_e32 v82, v82
	v_mov_b32_e32 v83, 0x7149f2ca
	v_cndmask_b32_e64 v83, v83, v81, s[24:25]
	v_sub_f32_e32 v54, v54, v83
	v_sub_f32_e32 v55, v55, v83
	v_sub_f32_e32 v56, v56, v83
	v_sub_f32_e32 v57, v57, v83
	v_exp_f32_e32 v54, v54
	v_exp_f32_e32 v55, v55
	v_exp_f32_e32 v56, v56
	v_exp_f32_e32 v57, v57
	v_sub_f32_e32 v58, v58, v83
	v_sub_f32_e32 v59, v59, v83
	v_sub_f32_e32 v60, v60, v83
	v_sub_f32_e32 v61, v61, v83
	v_exp_f32_e32 v58, v58
	v_exp_f32_e32 v59, v59
	v_exp_f32_e32 v60, v60
	v_exp_f32_e32 v61, v61
	v_sub_f32_e32 v62, v62, v83
	v_sub_f32_e32 v63, v63, v83
	v_sub_f32_e32 v64, v64, v83
	v_sub_f32_e32 v65, v65, v83
	v_exp_f32_e32 v62, v62
	v_exp_f32_e32 v63, v63
	v_exp_f32_e32 v64, v64
	v_exp_f32_e32 v65, v65
	v_sub_f32_e32 v66, v66, v83
	v_sub_f32_e32 v67, v67, v83
	v_sub_f32_e32 v68, v68, v83
	v_sub_f32_e32 v69, v69, v83
	v_exp_f32_e32 v66, v66
	v_exp_f32_e32 v67, v67
	v_exp_f32_e32 v68, v68
	v_exp_f32_e32 v69, v69
	s_nop 0
	v_add_f32_e32 v78, v54, v55
	v_add_f32_e32 v79, v56, v57
	v_add_f32_e32 v80, v58, v59
	v_add_f32_e32 v81, v60, v61
	v_add_f32_e32 v78, v78, v62
	v_add_f32_e32 v79, v79, v63
	v_add_f32_e32 v80, v80, v64
	v_add_f32_e32 v81, v81, v65
	v_add_f32_e32 v78, v78, v66
	v_add_f32_e32 v79, v79, v67
	v_add_f32_e32 v80, v80, v68
	v_add_f32_e32 v81, v81, v69
	v_add_f32_e32 v78, v78, v79
	v_add_f32_e32 v80, v80, v81
	v_add_f32_e32 v78, v78, v80
	v_cvt_pk_bf16_f32 v70, v54, v55
	v_cvt_pk_bf16_f32 v71, v56, v57
	v_cvt_pk_bf16_f32 v72, v58, v59
	v_cvt_pk_bf16_f32 v73, v60, v61
	v_cvt_pk_bf16_f32 v74, v62, v63
	v_cvt_pk_bf16_f32 v75, v64, v65
	v_cvt_pk_bf16_f32 v76, v66, v67
	v_cvt_pk_bf16_f32 v77, v68, v69
	v_mov_b32_e32 v79, v78
	s_nop 1
	v_permlane16_swap_b32_e32 v78, v79
	v_add_f32_e32 v78, v78, v79
	v_mov_b32_e32 v79, v78
	s_nop 1
	v_permlane32_swap_b32_e32 v78, v79
	v_add_f32_e32 v78, v78, v79
	v_fma_f32 v105, v105, v82, v78
	v_cmp_neq_f32_e64 s[4:5], 1.0, v82
	s_cmp_eq_u64 s[4:5], 0
	s_cbranch_scc1 .Lsl3_nosc_17
	v_pk_mul_f32 v[22:23], v[22:23], v[82:83] op_sel_hi:[1,0]
	v_pk_mul_f32 v[24:25], v[24:25], v[82:83] op_sel_hi:[1,0]
	v_pk_mul_f32 v[26:27], v[26:27], v[82:83] op_sel_hi:[1,0]
	v_pk_mul_f32 v[28:29], v[28:29], v[82:83] op_sel_hi:[1,0]
	v_pk_mul_f32 v[34:35], v[34:35], v[82:83] op_sel_hi:[1,0]
	v_pk_mul_f32 v[36:37], v[36:37], v[82:83] op_sel_hi:[1,0]
	v_pk_mul_f32 v[30:31], v[30:31], v[82:83] op_sel_hi:[1,0]
	v_pk_mul_f32 v[32:33], v[32:33], v[82:83] op_sel_hi:[1,0]

; template <int D, class SF>
; __device__ __forceinline__ void attn_step(const bf16x8 (&qf)[D / 32], const LAS bf16_t* Ks, const LAS bf16_t* Vt, f32x4 (&o)[D / 16], float& m, float& lsum, float& alpha_out, bf16x8& pf0_out, bf16x8& pf1_out, const int lane, SF sf) {
;     constexpr int KSTR = D + 8;
;     const int c = lane & 15, i = lane >> 4;
;     f32x4 s[4];
; #pragma unroll
;     for (int t = 0; t < 4; ++t) s[t] = (f32x4){0.f, 0.f, 0.f, 0.f};
; #pragma unroll
;     for (int ks = 0; ks < D / 32; ++ks) {
; #pragma unroll
;         for (int t = 0; t < 4; ++t) { const bf16x8 kf = *(const LAS bf16x8*)(Ks + (16 * t + c) * KSTR + ks * 32 + 8 * i); s[t] = mfma16(kf, qf[ks], s[t]); }
;     }
;     float v[16];
; #pragma unroll
;     for (int t = 0; t < 4; ++t)
; #pragma unroll
;         for (int r = 0; r < 4; ++r) v[4 * t + r] = sf(16 * t + 4 * i + r, s[t][r]);
;     float mx = fmaxf(fmaxf(fmaxf(v[0], v[1]), fmaxf(v[2], v[3])), fmaxf(fmaxf(v[4], v[5]), fmaxf(v[6], v[7])));
;     mx = fmaxf(mx, fmaxf(fmaxf(fmaxf(v[8], v[9]), fmaxf(v[10], v[11])), fmaxf(fmaxf(v[12], v[13]), fmaxf(v[14], v[15]))));
;     mx = rows_max(mx);
;     const float mnew = fmaxf(m, mx);
;     const float mc = fmaxf(mnew, -1e20f);
;     const float alpha = __builtin_amdgcn_exp2f(fmaxf(m, -1e20f) - mc);
;     float p[16], rs = 0.f;
; #pragma unroll
;     for (int r = 0; r < 16; ++r) { p[r] = __builtin_amdgcn_exp2f(v[r] - mc); rs += p[r]; }
;     rs = rows_sum(rs);
;     lsum = lsum * alpha + rs; m = mnew;
;     union { u32x4 u; bf16x8 b; } pk0, pk1;
;     pk0.u.x = cvt_pk_bf16(p[0], p[1]); pk0.u.y = cvt_pk_bf16(p[2], p[3]); pk0.u.z = cvt_pk_bf16(p[4], p[5]); pk0.u.w = cvt_pk_bf16(p[6], p[7]);
;     pk1.u.x = cvt_pk_bf16(p[8], p[9]); pk1.u.y = cvt_pk_bf16(p[10], p[11]); pk1.u.z = cvt_pk_bf16(p[12], p[13]); pk1.u.w = cvt_pk_bf16(p[14], p[15]);
;     if (__builtin_amdgcn_ballot_w64(alpha != 1.0f) != 0ull) {
; #pragma unroll
; __device__ __forceinline__ void nsa_unit(LAS unsigned char* lds, const Ctx& P, int l, int b, int hkv, int tb) {
;     ...
;                     } else { const int kp0 = j * 64;
;                         attn_step<64>(qf[sb], Ks, Vt, o[sb], m[sb], lsum[sb], alpha, pf, pf1, lane,
;                             [&](int kk, float s) { const int dist = tqs - (kp0 + kk); return (selj && dist >= 0) ? s * LOG2E + lut[min((unsigned)dist, 1023u)] : NEGBIG; });
.Lsl3_diagx_9:
	v_lshrrev_b64 v[78:79], s20, v[18:19]
	v_and_b32_e32 v78, 1, v78
	v_cmp_eq_u32_e64 s[24:25], 1, v78
	s_cmp_eq_u64 s[24:25], 0
	s_cbranch_scc1 .Lsl3_skd_18
	v_sub_u32_e32 v78, v130, v139
	v_subrev_u32_e32 v78, s21, v78
	v_subrev_u32_e32 v107, 0, v78
	v_min_u32_e32 v107, 0x3ff, v107
	v_lshl_add_u32 v107, v107, 2, v131
	ds_read_b32 v107, v107
	v_subrev_u32_e32 v108, 1, v78
	v_min_u32_e32 v108, 0x3ff, v108
	v_lshl_add_u32 v108, v108, 2, v131
	ds_read_b32 v108, v108
	v_subrev_u32_e32 v109, 2, v78
	v_min_u32_e32 v109, 0x3ff, v109
	v_lshl_add_u32 v109, v109, 2, v131
	ds_read_b32 v109, v109
	v_subrev_u32_e32 v110, 3, v78
	v_min_u32_e32 v110, 0x3ff, v110
	v_lshl_add_u32 v110, v110, 2, v131
	ds_read_b32 v110, v110
	v_subrev_u32_e32 v111, 16, v78
	v_min_u32_e32 v111, 0x3ff, v111
	v_lshl_add_u32 v111, v111, 2, v131
	ds_read_b32 v111, v111
	v_subrev_u32_e32 v112, 17, v78
	v_min_u32_e32 v112, 0x3ff, v112
	v_lshl_add_u32 v112, v112, 2, v131
	ds_read_b32 v112, v112
	v_subrev_u32_e32 v113, 18, v78
	v_min_u32_e32 v113, 0x3ff, v113
	v_lshl_add_u32 v113, v113, 2, v131
	ds_read_b32 v113, v113
	v_subrev_u32_e32 v133, 19, v78
	v_min_u32_e32 v133, 0x3ff, v133
	v_lshl_add_u32 v133, v133, 2, v131
	ds_read_b32 v133, v133
	ds_read_b128 v[198:201], v190 offset:16384
	ds_read_b128 v[206:209], v190 offset:18688
	ds_read_b128 v[202:205], v190 offset:16448
	ds_read_b128 v[210:213], v190 offset:18752
	ds_read_b128 v[214:217], v190 offset:20992
	ds_read_b128 v[222:225], v190 offset:23296
	ds_read_b128 v[218:221], v190 offset:21056
	ds_read_b128 v[226:229], v190 offset:23360
	s_waitcnt lgkmcnt(6)
	v_mfma_f32_16x16x32_bf16 v[54:57], v[198:201], v[2:5], 0
	v_mfma_f32_16x16x32_bf16 v[58:61], v[206:209], v[2:5], 0
	s_waitcnt lgkmcnt(4)
	v_mfma_f32_16x16x32_bf16 v[54:57], v[202:205], v[6:9], v[54:57]
	v_mfma_f32_16x16x32_bf16 v[58:61], v[210:213], v[6:9], v[58:61]
	s_waitcnt lgkmcnt(2)
	v_mfma_f32_16x16x32_bf16 v[62:65], v[214:217], v[2:5], 0
	v_mfma_f32_16x16x32_bf16 v[66:69], v[222:225], v[2:5], 0
	s_waitcnt lgkmcnt(0)
	v_mfma_f32_16x16x32_bf16 v[62:65], v[218:221], v[6:9], v[62:65]
	v_mfma_f32_16x16x32_bf16 v[66:69], v[226:229], v[6:9], v[66:69]
	ds_read_b64_tr_b16 v[198:199], v191 offset:25600
	ds_read_b64_tr_b16 v[200:201], v191 offset:27904
	ds_read_b64_tr_b16 v[202:203], v191 offset:30208
	ds_read_b64_tr_b16 v[204:205], v191 offset:32512
	ds_read_b64_tr_b16 v[206:207], v191 offset:25632
	ds_read_b64_tr_b16 v[208:209], v191 offset:27936
	ds_read_b64_tr_b16 v[210:211], v191 offset:30240
	v_fmamk_f32 v54, v54, 0x3fb8aa3b, v107
	v_fmamk_f32 v55, v55, 0x3fb8aa3b, v108
	v_fmamk_f32 v56, v56, 0x3fb8aa3b, v109
	v_fmamk_f32 v57, v57, 0x3fb8aa3b, v110
	v_fmamk_f32 v58, v58, 0x3fb8aa3b, v111
	v_fmamk_f32 v59, v59, 0x3fb8aa3b, v112
	v_fmamk_f32 v60, v60, 0x3fb8aa3b, v113
	v_fmamk_f32 v61, v61, 0x3fb8aa3b, v133
	v_cmp_le_i32_e32 vcc, 0, v78
	s_nop 1
	v_cndmask_b32_e32 v54, v243, v54, vcc
	v_cmp_le_i32_e32 vcc, 1, v78
	s_nop 1
	v_cndmask_b32_e32 v55, v243, v55, vcc
	v_cmp_le_i32_e32 vcc, 2, v78
	s_nop 1
	v_cndmask_b32_e32 v56, v243, v56, vcc
	v_cmp_le_i32_e32 vcc, 3, v78
	s_nop 1
	v_cndmask_b32_e32 v57, v243, v57, vcc
	v_cmp_le_i32_e32 vcc, 16, v78
	s_nop 1
	v_cndmask_b32_e32 v58, v243, v58, vcc
	v_cmp_le_i32_e32 vcc, 17, v78
	s_nop 1
	v_cndmask_b32_e32 v59, v243, v59, vcc
	v_cmp_le_i32_e32 vcc, 18, v78
	s_nop 1
	v_cndmask_b32_e32 v60, v243, v60, vcc
	v_cmp_le_i32_e32 vcc, 19, v78
	s_nop 1
	v_cndmask_b32_e32 v61, v243, v61, vcc
	v_subrev_u32_e32 v107, 32, v78
	v_min_u32_e32 v107, 0x3ff, v107
	v_lshl_add_u32 v107, v107, 2, v131
	ds_read_b32 v107, v107
	v_subrev_u32_e32 v108, 33, v78
	v_min_u32_e32 v108, 0x3ff, v108
	v_lshl_add_u32 v108, v108, 2, v131
	ds_read_b32 v108, v108
	v_subrev_u32_e32 v109, 34, v78
	v_min_u32_e32 v109, 0x3ff, v109
	v_lshl_add_u32 v109, v109, 2, v131
	ds_read_b32 v109, v109
	v_subrev_u32_e32 v110, 35, v78
	v_min_u32_e32 v110, 0x3ff, v110
	v_lshl_add_u32 v110, v110, 2, v131
	ds_read_b32 v110, v110
	v_subrev_u32_e32 v111, 48, v78
	v_min_u32_e32 v111, 0x3ff, v111
	v_lshl_add_u32 v111, v111, 2, v131
	ds_read_b32 v111, v111
	v_subrev_u32_e32 v112, 49, v78
	v_min_u32_e32 v112, 0x3ff, v112
	v_lshl_add_u32 v112, v112, 2, v131
	ds_read_b32 v112, v112
	v_subrev_u32_e32 v113, 50, v78
	v_min_u32_e32 v113, 0x3ff, v113
	v_lshl_add_u32 v113, v113, 2, v131
	ds_read_b32 v113, v113
	v_subrev_u32_e32 v133, 51, v78
	v_min_u32_e32 v133, 0x3ff, v133
	v_lshl_add_u32 v133, v133, 2, v131
	ds_read_b32 v133, v133
	ds_read_b64_tr_b16 v[212:213], v191 offset:32544
	ds_read_b64_tr_b16 v[214:215], v191 offset:25664
	ds_read_b64_tr_b16 v[216:217], v191 offset:27968
	ds_read_b64_tr_b16 v[218:219], v191 offset:30272
	ds_read_b64_tr_b16 v[220:221], v191 offset:32576
	ds_read_b64_tr_b16 v[222:223], v191 offset:25696
	ds_read_b64_tr_b16 v[224:225], v191 offset:28000
	ds_read_b64_tr_b16 v[226:227], v191 offset:30304
	ds_read_b64_tr_b16 v[228:229], v191 offset:32608
	s_waitcnt lgkmcnt(9)
; #define LAS __attribute__((address_space(3)))
; template <int D, class SF>
; __device__ __forceinline__ void attn_step(const bf16x8 (&qf)[D / 32], const LAS bf16_t* Ks, const LAS bf16_t* Vt, f32x4 (&o)[D / 16], float& m, float& lsum, float& alpha_out, bf16x8& pf0_out, bf16x8& pf1_out, const int lane, SF sf) {
;     constexpr int KSTR = D + 8;
;     const int c = lane & 15, i = lane >> 4;
;     f32x4 s[4];
; #pragma unroll
;     for (int t = 0; t < 4; ++t) s[t] = (f32x4){0.f, 0.f, 0.f, 0.f};
; #pragma unroll
;     for (int ks = 0; ks < D / 32; ++ks) {
; #pragma unroll
;         for (int t = 0; t < 4; ++t) { const bf16x8 kf = *(const LAS bf16x8*)(Ks + (16 * t + c) * KSTR + ks * 32 + 8 * i); s[t] = mfma16(kf, qf[ks], s[t]); }
;     }
;     float v[16];
; #pragma unroll
;     for (int t = 0; t < 4; ++t)
; #pragma unroll
;         for (int r = 0; r < 4; ++r) v[4 * t + r] = sf(16 * t + 4 * i + r, s[t][r]);
;     float mx = fmaxf(fmaxf(fmaxf(v[0], v[1]), fmaxf(v[2], v[3])), fmaxf(fmaxf(v[4], v[5]), fmaxf(v[6], v[7])));
;     mx = fmaxf(mx, fmaxf(fmaxf(fmaxf(v[8], v[9]), fmaxf(v[10], v[11])), fmaxf(fmaxf(v[12], v[13]), fmaxf(v[14], v[15]))));
;     mx = rows_max(mx);
;     const float mnew = fmaxf(m, mx);
;     const float mc = fmaxf(mnew, -1e20f);
;     const float alpha = __builtin_amdgcn_exp2f(fmaxf(m, -1e20f) - mc);
;     float p[16], rs = 0.f;
; #pragma unroll
;     for (int r = 0; r < 16; ++r) { p[r] = __builtin_amdgcn_exp2f(v[r] - mc); rs += p[r]; }
;     rs = rows_sum(rs);
;     lsum = lsum * alpha + rs; m = mnew;
;     union { u32x4 u; bf16x8 b; } pk0, pk1;
;     pk0.u.x = cvt_pk_bf16(p[0], p[1]); pk0.u.y = cvt_pk_bf16(p[2], p[3]); pk0.u.z = cvt_pk_bf16(p[4], p[5]); pk0.u.w = cvt_pk_bf16(p[6], p[7]);
;     pk1.u.x = cvt_pk_bf16(p[8], p[9]); pk1.u.y = cvt_pk_bf16(p[10], p[11]); pk1.u.z = cvt_pk_bf16(p[12], p[13]); pk1.u.w = cvt_pk_bf16(p[14], p[15]);
;     if (__builtin_amdgcn_ballot_w64(alpha != 1.0f) != 0ull) {
; #pragma unroll
;         for (int dt = 0; dt < D / 16; ++dt) o[dt] *= alpha;
;     }
; #pragma unroll
;     for (int dt = 0; dt < D / 16; ++dt) {
;         const LAS bf16_t* vp = Vt + (16 * dt + c) * 72 + 4 * i;
;         union { u32x4 u; bf16x8 b; } vf0, vf1; const u32x2 a0 = *(const LAS u32x2*)vp, a1 = *(const LAS u32x2*)(vp + 16), b0 = *(const LAS u32x2*)(vp + 32), b1 = *(const LAS u32x2*)(vp + 48);
	v_fmamk_f32 v62, v62, 0x3fb8aa3b, v107
	v_fmamk_f32 v63, v63, 0x3fb8aa3b, v108
	v_fmamk_f32 v64, v64, 0x3fb8aa3b, v109
	v_fmamk_f32 v65, v65, 0x3fb8aa3b, v110
	v_fmamk_f32 v66, v66, 0x3fb8aa3b, v111
	v_fmamk_f32 v67, v67, 0x3fb8aa3b, v112
	v_fmamk_f32 v68, v68, 0x3fb8aa3b, v113
	v_fmamk_f32 v69, v69, 0x3fb8aa3b, v133
	v_cmp_le_i32_e32 vcc, 32, v78
	s_nop 1
	v_cndmask_b32_e32 v62, v243, v62, vcc
	v_cmp_le_i32_e32 vcc, 33, v78
	s_nop 1
	v_cndmask_b32_e32 v63, v243, v63, vcc
	v_cmp_le_i32_e32 vcc, 34, v78
	s_nop 1
	v_cndmask_b32_e32 v64, v243, v64, vcc
	v_cmp_le_i32_e32 vcc, 35, v78
	s_nop 1
	v_cndmask_b32_e32 v65, v243, v65, vcc
	v_cmp_le_i32_e32 vcc, 48, v78
	s_nop 1
	v_cndmask_b32_e32 v66, v243, v66, vcc
	v_cmp_le_i32_e32 vcc, 49, v78
	s_nop 1
	v_cndmask_b32_e32 v67, v243, v67, vcc
	v_cmp_le_i32_e32 vcc, 50, v78
	s_nop 1
	v_cndmask_b32_e32 v68, v243, v68, vcc
	v_cmp_le_i32_e32 vcc, 51, v78
	s_nop 1
	v_cndmask_b32_e32 v69, v243, v69, vcc
	v_max3_f32 v84, v54, v55, v56
	v_max3_f32 v79, v57, v58, v59
	v_max3_f32 v80, v60, v61, v62
	v_max3_f32 v81, v63, v64, v65
	v_max3_f32 v83, v66, v67, v68
	v_max3_f32 v84, v84, v79, v69
	v_max3_f32 v80, v80, v81, v83
	v_max_f32_e32 v84, v84, v80
	v_mov_b32_e32 v79, v84
	s_nop 1
	v_permlane16_swap_b32_e32 v84, v79
	v_max_f32_e32 v84, v84, v79
	v_mov_b32_e32 v79, v84
	s_nop 1
	v_permlane32_swap_b32_e32 v84, v79
	v_max_f32_e32 v84, v84, v79
	v_cndmask_b32_e64 v84, v243, v84, s[24:25]
	v_max_f32_e32 v80, v100, v84
	v_max_f32_e32 v82, 0xe0ad78ec, v100
	v_max_f32_e32 v81, 0xe0ad78ec, v80
	v_sub_f32_e32 v82, v82, v81
	v_mov_b32_e32 v100, v80
	v_exp_f32_e32 v82, v82
	v_mov_b32_e32 v83, 0x7149f2ca
	v_cndmask_b32_e64 v83, v83, v81, s[24:25]
	v_sub_f32_e32 v54, v54, v83
	v_sub_f32_e32 v55, v55, v83
	v_sub_f32_e32 v56, v56, v83
	v_sub_f32_e32 v57, v57, v83
	v_exp_f32_e32 v54, v54
	v_exp_f32_e32 v55, v55
	v_exp_f32_e32 v56, v56
	v_exp_f32_e32 v57, v57
	v_sub_f32_e32 v58, v58, v83
	v_sub_f32_e32 v59, v59, v83
	v_sub_f32_e32 v60, v60, v83
	v_sub_f32_e32 v61, v61, v83
	v_exp_f32_e32 v58, v58
	v_exp_f32_e32 v59, v59
	v_exp_f32_e32 v60, v60
	v_exp_f32_e32 v61, v61
	v_sub_f32_e32 v62, v62, v83
	v_sub_f32_e32 v63, v63, v83
	v_sub_f32_e32 v64, v64, v83
	v_sub_f32_e32 v65, v65, v83
	v_exp_f32_e32 v62, v62
	v_exp_f32_e32 v63, v63
	v_exp_f32_e32 v64, v64
	v_exp_f32_e32 v65, v65
	v_sub_f32_e32 v66, v66, v83
	v_sub_f32_e32 v67, v67, v83
	v_sub_f32_e32 v68, v68, v83
	v_sub_f32_e32 v69, v69, v83
	v_exp_f32_e32 v66, v66
	v_exp_f32_e32 v67, v67
	v_exp_f32_e32 v68, v68
	v_exp_f32_e32 v69, v69
	s_nop 0
	v_add_f32_e32 v78, v54, v55
	v_add_f32_e32 v79, v56, v57
	v_add_f32_e32 v80, v58, v59
	v_add_f32_e32 v81, v60, v61
	v_add_f32_e32 v78, v78, v62
	v_add_f32_e32 v79, v79, v63
	v_add_f32_e32 v80, v80, v64
	v_add_f32_e32 v81, v81, v65
	v_add_f32_e32 v78, v78, v66
	v_add_f32_e32 v79, v79, v67
	v_add_f32_e32 v80, v80, v68
	v_add_f32_e32 v81, v81, v69
	v_add_f32_e32 v78, v78, v79
	v_add_f32_e32 v80, v80, v81
	v_add_f32_e32 v78, v78, v80
	v_cvt_pk_bf16_f32 v70, v54, v55
	v_cvt_pk_bf16_f32 v71, v56, v57
	v_cvt_pk_bf16_f32 v72, v58, v59
	v_cvt_pk_bf16_f32 v73, v60, v61
	v_cvt_pk_bf16_f32 v74, v62, v63
	v_cvt_pk_bf16_f32 v75, v64, v65
	v_cvt_pk_bf16_f32 v76, v66, v67
	v_cvt_pk_bf16_f32 v77, v68, v69
	v_mov_b32_e32 v79, v78
	s_nop 1
	v_permlane16_swap_b32_e32 v78, v79
	v_add_f32_e32 v78, v78, v79
	v_mov_b32_e32 v79, v78
	s_nop 1
	v_permlane32_swap_b32_e32 v78, v79
	v_add_f32_e32 v78, v78, v79
	v_fma_f32 v106, v106, v82, v78
	v_cmp_neq_f32_e64 s[4:5], 1.0, v82
	s_cmp_eq_u64 s[4:5], 0
	s_cbranch_scc1 .Lsl3_nosc_19
	v_pk_mul_f32 v[38:39], v[38:39], v[82:83] op_sel_hi:[1,0]
	v_pk_mul_f32 v[40:41], v[40:41], v[82:83] op_sel_hi:[1,0]
	v_pk_mul_f32 v[42:43], v[42:43], v[82:83] op_sel_hi:[1,0]
	v_pk_mul_f32 v[44:45], v[44:45], v[82:83] op_sel_hi:[1,0]
	v_pk_mul_f32 v[46:47], v[46:47], v[82:83] op_sel_hi:[1,0]
	v_pk_mul_f32 v[48:49], v[48:49], v[82:83] op_sel_hi:[1,0]
	v_pk_mul_f32 v[50:51], v[50:51], v[82:83] op_sel_hi:[1,0]
	v_pk_mul_f32 v[52:53], v[52:53], v[82:83] op_sel_hi:[1,0]

; template <int D, class SF>
; __device__ __forceinline__ void attn_step(const bf16x8 (&qf)[D / 32], const LAS bf16_t* Ks, const LAS bf16_t* Vt, f32x4 (&o)[D / 16], float& m, float& lsum, float& alpha_out, bf16x8& pf0_out, bf16x8& pf1_out, const int lane, SF sf) {
;     constexpr int KSTR = D + 8;
;     const int c = lane & 15, i = lane >> 4;
;     f32x4 s[4];
; #pragma unroll
;     for (int t = 0; t < 4; ++t) s[t] = (f32x4){0.f, 0.f, 0.f, 0.f};
; #pragma unroll
;     for (int ks = 0; ks < D / 32; ++ks) {
; #pragma unroll
;         for (int t = 0; t < 4; ++t) { const bf16x8 kf = *(const LAS bf16x8*)(Ks + (16 * t + c) * KSTR + ks * 32 + 8 * i); s[t] = mfma16(kf, qf[ks], s[t]); }
;     }
;     float v[16];
; #pragma unroll
;     for (int t = 0; t < 4; ++t)
; #pragma unroll
;         for (int r = 0; r < 4; ++r) v[4 * t + r] = sf(16 * t + 4 * i + r, s[t][r]);
;     float mx = fmaxf(fmaxf(fmaxf(v[0], v[1]), fmaxf(v[2], v[3])), fmaxf(fmaxf(v[4], v[5]), fmaxf(v[6], v[7])));
;     mx = fmaxf(mx, fmaxf(fmaxf(fmaxf(v[8], v[9]), fmaxf(v[10], v[11])), fmaxf(fmaxf(v[12], v[13]), fmaxf(v[14], v[15]))));
;     mx = rows_max(mx);
;     const float mnew = fmaxf(m, mx);
;     const float mc = fmaxf(mnew, -1e20f);
;     const float alpha = __builtin_amdgcn_exp2f(fmaxf(m, -1e20f) - mc);
;     float p[16], rs = 0.f;
; #pragma unroll
;     for (int r = 0; r < 16; ++r) { p[r] = __builtin_amdgcn_exp2f(v[r] - mc); rs += p[r]; }
;     rs = rows_sum(rs);
;     lsum = lsum * alpha + rs; m = mnew;
;     union { u32x4 u; bf16x8 b; } pk0, pk1;
;     pk0.u.x = cvt_pk_bf16(p[0], p[1]); pk0.u.y = cvt_pk_bf16(p[2], p[3]); pk0.u.z = cvt_pk_bf16(p[4], p[5]); pk0.u.w = cvt_pk_bf16(p[6], p[7]);
;     pk1.u.x = cvt_pk_bf16(p[8], p[9]); pk1.u.y = cvt_pk_bf16(p[10], p[11]); pk1.u.z = cvt_pk_bf16(p[12], p[13]); pk1.u.w = cvt_pk_bf16(p[14], p[15]);
;     if (__builtin_amdgcn_ballot_w64(alpha != 1.0f) != 0ull) {
; #pragma unroll
; __device__ __forceinline__ void nsa_unit(LAS unsigned char* lds, const Ctx& P, int l, int b, int hkv, int tb) {
;     ...
;                     } else { const int kp0 = j * 64;
;                         attn_step<64>(qf[sb], Ks, Vt, o[sb], m[sb], lsum[sb], alpha, pf, pf1, lane,
;                             [&](int kk, float s) { const int dist = tqs - (kp0 + kk); return (selj && dist >= 0) ? s * LOG2E + lut[min((unsigned)dist, 1023u)] : NEGBIG; });
.Lsl3_skd_18:
	v_lshrrev_b64 v[78:79], s20, v[20:21]
	v_and_b32_e32 v78, 1, v78
	v_cmp_eq_u32_e64 s[24:25], 1, v78
	s_cmp_eq_u64 s[24:25], 0
	s_cbranch_scc1 .Lsl3_skd_20
	v_sub_u32_e32 v78, v98, v139
	v_subrev_u32_e32 v78, s21, v78
	v_subrev_u32_e32 v107, 0, v78
	v_min_u32_e32 v107, 0x3ff, v107
	v_lshl_add_u32 v107, v107, 2, v131
	ds_read_b32 v107, v107
	v_subrev_u32_e32 v108, 1, v78
	v_min_u32_e32 v108, 0x3ff, v108
	v_lshl_add_u32 v108, v108, 2, v131
	ds_read_b32 v108, v108
	v_subrev_u32_e32 v109, 2, v78
	v_min_u32_e32 v109, 0x3ff, v109
	v_lshl_add_u32 v109, v109, 2, v131
	ds_read_b32 v109, v109
	v_subrev_u32_e32 v110, 3, v78
	v_min_u32_e32 v110, 0x3ff, v110
	v_lshl_add_u32 v110, v110, 2, v131
	ds_read_b32 v110, v110
	v_subrev_u32_e32 v111, 16, v78
	v_min_u32_e32 v111, 0x3ff, v111
	v_lshl_add_u32 v111, v111, 2, v131
	ds_read_b32 v111, v111
	v_subrev_u32_e32 v112, 17, v78
	v_min_u32_e32 v112, 0x3ff, v112
	v_lshl_add_u32 v112, v112, 2, v131
	ds_read_b32 v112, v112
	v_subrev_u32_e32 v113, 18, v78
	v_min_u32_e32 v113, 0x3ff, v113
	v_lshl_add_u32 v113, v113, 2, v131
	ds_read_b32 v113, v113
	v_subrev_u32_e32 v133, 19, v78
	v_min_u32_e32 v133, 0x3ff, v133
	v_lshl_add_u32 v133, v133, 2, v131
	ds_read_b32 v133, v133
	ds_read_b128 v[198:201], v190 offset:16384
	ds_read_b128 v[206:209], v190 offset:18688
	ds_read_b128 v[202:205], v190 offset:16448
	ds_read_b128 v[210:213], v190 offset:18752
	ds_read_b128 v[214:217], v190 offset:20992
	ds_read_b128 v[222:225], v190 offset:23296
	ds_read_b128 v[218:221], v190 offset:21056
	ds_read_b128 v[226:229], v190 offset:23360
	s_waitcnt lgkmcnt(6)
	v_mfma_f32_16x16x32_bf16 v[54:57], v[198:201], v[10:13], 0
	v_mfma_f32_16x16x32_bf16 v[58:61], v[206:209], v[10:13], 0
	s_waitcnt lgkmcnt(4)
	v_mfma_f32_16x16x32_bf16 v[54:57], v[202:205], v[14:17], v[54:57]
	v_mfma_f32_16x16x32_bf16 v[58:61], v[210:213], v[14:17], v[58:61]
	s_waitcnt lgkmcnt(2)
	v_mfma_f32_16x16x32_bf16 v[62:65], v[214:217], v[10:13], 0
	v_mfma_f32_16x16x32_bf16 v[66:69], v[222:225], v[10:13], 0
	s_waitcnt lgkmcnt(0)
	v_mfma_f32_16x16x32_bf16 v[62:65], v[218:221], v[14:17], v[62:65]
	v_mfma_f32_16x16x32_bf16 v[66:69], v[226:229], v[14:17], v[66:69]
	ds_read_b64_tr_b16 v[198:199], v191 offset:25600
	ds_read_b64_tr_b16 v[200:201], v191 offset:27904
	ds_read_b64_tr_b16 v[202:203], v191 offset:30208
	ds_read_b64_tr_b16 v[204:205], v191 offset:32512
	ds_read_b64_tr_b16 v[206:207], v191 offset:25632
	ds_read_b64_tr_b16 v[208:209], v191 offset:27936
	ds_read_b64_tr_b16 v[210:211], v191 offset:30240
	v_fmamk_f32 v54, v54, 0x3fb8aa3b, v107
	v_fmamk_f32 v55, v55, 0x3fb8aa3b, v108
	v_fmamk_f32 v56, v56, 0x3fb8aa3b, v109
	v_fmamk_f32 v57, v57, 0x3fb8aa3b, v110
	v_fmamk_f32 v58, v58, 0x3fb8aa3b, v111
	v_fmamk_f32 v59, v59, 0x3fb8aa3b, v112
	v_fmamk_f32 v60, v60, 0x3fb8aa3b, v113
	v_fmamk_f32 v61, v61, 0x3fb8aa3b, v133
	v_cmp_le_i32_e32 vcc, 0, v78
	s_nop 1
	v_cndmask_b32_e32 v54, v243, v54, vcc
	v_cmp_le_i32_e32 vcc, 1, v78
	s_nop 1
	v_cndmask_b32_e32 v55, v243, v55, vcc
	v_cmp_le_i32_e32 vcc, 2, v78
	s_nop 1
	v_cndmask_b32_e32 v56, v243, v56, vcc
	v_cmp_le_i32_e32 vcc, 3, v78
	s_nop 1
	v_cndmask_b32_e32 v57, v243, v57, vcc
	v_cmp_le_i32_e32 vcc, 16, v78
	s_nop 1
	v_cndmask_b32_e32 v58, v243, v58, vcc
	v_cmp_le_i32_e32 vcc, 17, v78
	s_nop 1
	v_cndmask_b32_e32 v59, v243, v59, vcc
	v_cmp_le_i32_e32 vcc, 18, v78
	s_nop 1
	v_cndmask_b32_e32 v60, v243, v60, vcc
	v_cmp_le_i32_e32 vcc, 19, v78
	s_nop 1
	v_cndmask_b32_e32 v61, v243, v61, vcc
	v_subrev_u32_e32 v107, 32, v78
	v_min_u32_e32 v107, 0x3ff, v107
	v_lshl_add_u32 v107, v107, 2, v131
	ds_read_b32 v107, v107
	v_subrev_u32_e32 v108, 33, v78
	v_min_u32_e32 v108, 0x3ff, v108
	v_lshl_add_u32 v108, v108, 2, v131
	ds_read_b32 v108, v108
	v_subrev_u32_e32 v109, 34, v78
	v_min_u32_e32 v109, 0x3ff, v109
	v_lshl_add_u32 v109, v109, 2, v131
	ds_read_b32 v109, v109
	v_subrev_u32_e32 v110, 35, v78
	v_min_u32_e32 v110, 0x3ff, v110
	v_lshl_add_u32 v110, v110, 2, v131
	ds_read_b32 v110, v110
	v_subrev_u32_e32 v111, 48, v78
	v_min_u32_e32 v111, 0x3ff, v111
	v_lshl_add_u32 v111, v111, 2, v131
	ds_read_b32 v111, v111
	v_subrev_u32_e32 v112, 49, v78
	v_min_u32_e32 v112, 0x3ff, v112
	v_lshl_add_u32 v112, v112, 2, v131
	ds_read_b32 v112, v112
	v_subrev_u32_e32 v113, 50, v78
	v_min_u32_e32 v113, 0x3ff, v113
	v_lshl_add_u32 v113, v113, 2, v131
	ds_read_b32 v113, v113
	v_subrev_u32_e32 v133, 51, v78
	v_min_u32_e32 v133, 0x3ff, v133
	v_lshl_add_u32 v133, v133, 2, v131
	ds_read_b32 v133, v133
	ds_read_b64_tr_b16 v[212:213], v191 offset:32544
	ds_read_b64_tr_b16 v[214:215], v191 offset:25664
	ds_read_b64_tr_b16 v[216:217], v191 offset:27968
	ds_read_b64_tr_b16 v[218:219], v191 offset:30272
	ds_read_b64_tr_b16 v[220:221], v191 offset:32576
	ds_read_b64_tr_b16 v[222:223], v191 offset:25696
	ds_read_b64_tr_b16 v[224:225], v191 offset:28000
	ds_read_b64_tr_b16 v[226:227], v191 offset:30304
	ds_read_b64_tr_b16 v[228:229], v191 offset:32608
	s_waitcnt lgkmcnt(9)
; #define LAS __attribute__((address_space(3)))
; template <int D, class SF>
; __device__ __forceinline__ void attn_step(const bf16x8 (&qf)[D / 32], const LAS bf16_t* Ks, const LAS bf16_t* Vt, f32x4 (&o)[D / 16], float& m, float& lsum, float& alpha_out, bf16x8& pf0_out, bf16x8& pf1_out, const int lane, SF sf) {
;     constexpr int KSTR = D + 8;
;     const int c = lane & 15, i = lane >> 4;
;     f32x4 s[4];
; #pragma unroll
;     for (int t = 0; t < 4; ++t) s[t] = (f32x4){0.f, 0.f, 0.f, 0.f};
; #pragma unroll
;     for (int ks = 0; ks < D / 32; ++ks) {
; #pragma unroll
;         for (int t = 0; t < 4; ++t) { const bf16x8 kf = *(const LAS bf16x8*)(Ks + (16 * t + c) * KSTR + ks * 32 + 8 * i); s[t] = mfma16(kf, qf[ks], s[t]); }
;     }
;     float v[16];
; #pragma unroll
;     for (int t = 0; t < 4; ++t)
; #pragma unroll
;         for (int r = 0; r < 4; ++r) v[4 * t + r] = sf(16 * t + 4 * i + r, s[t][r]);
;     float mx = fmaxf(fmaxf(fmaxf(v[0], v[1]), fmaxf(v[2], v[3])), fmaxf(fmaxf(v[4], v[5]), fmaxf(v[6], v[7])));
;     mx = fmaxf(mx, fmaxf(fmaxf(fmaxf(v[8], v[9]), fmaxf(v[10], v[11])), fmaxf(fmaxf(v[12], v[13]), fmaxf(v[14], v[15]))));
;     mx = rows_max(mx);
;     const float mnew = fmaxf(m, mx);
;     const float mc = fmaxf(mnew, -1e20f);
;     const float alpha = __builtin_amdgcn_exp2f(fmaxf(m, -1e20f) - mc);
;     float p[16], rs = 0.f;
; #pragma unroll
;     for (int r = 0; r < 16; ++r) { p[r] = __builtin_amdgcn_exp2f(v[r] - mc); rs += p[r]; }
;     rs = rows_sum(rs);
;     lsum = lsum * alpha + rs; m = mnew;
;     union { u32x4 u; bf16x8 b; } pk0, pk1;
;     pk0.u.x = cvt_pk_bf16(p[0], p[1]); pk0.u.y = cvt_pk_bf16(p[2], p[3]); pk0.u.z = cvt_pk_bf16(p[4], p[5]); pk0.u.w = cvt_pk_bf16(p[6], p[7]);
;     pk1.u.x = cvt_pk_bf16(p[8], p[9]); pk1.u.y = cvt_pk_bf16(p[10], p[11]); pk1.u.z = cvt_pk_bf16(p[12], p[13]); pk1.u.w = cvt_pk_bf16(p[14], p[15]);
;     if (__builtin_amdgcn_ballot_w64(alpha != 1.0f) != 0ull) {
; #pragma unroll
;         for (int dt = 0; dt < D / 16; ++dt) o[dt] *= alpha;
;     }
; #pragma unroll
;     for (int dt = 0; dt < D / 16; ++dt) {
;         const LAS bf16_t* vp = Vt + (16 * dt + c) * 72 + 4 * i;
;         union { u32x4 u; bf16x8 b; } vf0, vf1; const u32x2 a0 = *(const LAS u32x2*)vp, a1 = *(const LAS u32x2*)(vp + 16), b0 = *(const LAS u32x2*)(vp + 32), b1 = *(const LAS u32x2*)(vp + 48);
	v_fmamk_f32 v62, v62, 0x3fb8aa3b, v107
	v_fmamk_f32 v63, v63, 0x3fb8aa3b, v108
	v_fmamk_f32 v64, v64, 0x3fb8aa3b, v109
	v_fmamk_f32 v65, v65, 0x3fb8aa3b, v110
	v_fmamk_f32 v66, v66, 0x3fb8aa3b, v111
	v_fmamk_f32 v67, v67, 0x3fb8aa3b, v112
	v_fmamk_f32 v68, v68, 0x3fb8aa3b, v113
	v_fmamk_f32 v69, v69, 0x3fb8aa3b, v133
	v_cmp_le_i32_e32 vcc, 32, v78
	s_nop 1
	v_cndmask_b32_e32 v62, v243, v62, vcc
	v_cmp_le_i32_e32 vcc, 33, v78
	s_nop 1
	v_cndmask_b32_e32 v63, v243, v63, vcc
	v_cmp_le_i32_e32 vcc, 34, v78
	s_nop 1
	v_cndmask_b32_e32 v64, v243, v64, vcc
	v_cmp_le_i32_e32 vcc, 35, v78
	s_nop 1
	v_cndmask_b32_e32 v65, v243, v65, vcc
	v_cmp_le_i32_e32 vcc, 48, v78
	s_nop 1
	v_cndmask_b32_e32 v66, v243, v66, vcc
	v_cmp_le_i32_e32 vcc, 49, v78
	s_nop 1
	v_cndmask_b32_e32 v67, v243, v67, vcc
	v_cmp_le_i32_e32 vcc, 50, v78
	s_nop 1
	v_cndmask_b32_e32 v68, v243, v68, vcc
	v_cmp_le_i32_e32 vcc, 51, v78
	s_nop 1
	v_cndmask_b32_e32 v69, v243, v69, vcc
	v_max3_f32 v84, v54, v55, v56
	v_max3_f32 v79, v57, v58, v59
	v_max3_f32 v80, v60, v61, v62
	v_max3_f32 v81, v63, v64, v65
	v_max3_f32 v83, v66, v67, v68
	v_max3_f32 v84, v84, v79, v69
	v_max3_f32 v80, v80, v81, v83
	v_max_f32_e32 v84, v84, v80
	v_mov_b32_e32 v79, v84
	s_nop 1
	v_permlane16_swap_b32_e32 v84, v79
	v_max_f32_e32 v84, v84, v79
	v_mov_b32_e32 v79, v84
	s_nop 1
	v_permlane32_swap_b32_e32 v84, v79
	v_max_f32_e32 v84, v84, v79
	v_cndmask_b32_e64 v84, v243, v84, s[24:25]
	v_max_f32_e32 v80, v93, v84
	v_max_f32_e32 v82, 0xe0ad78ec, v93
	v_max_f32_e32 v81, 0xe0ad78ec, v80
	v_sub_f32_e32 v82, v82, v81
	v_mov_b32_e32 v93, v80
	v_exp_f32_e32 v82, v82
	v_mov_b32_e32 v83, 0x7149f2ca
	v_cndmask_b32_e64 v83, v83, v81, s[24:25]
	v_sub_f32_e32 v54, v54, v83
	v_sub_f32_e32 v55, v55, v83
	v_sub_f32_e32 v56, v56, v83
	v_sub_f32_e32 v57, v57, v83
	v_exp_f32_e32 v54, v54
	v_exp_f32_e32 v55, v55
	v_exp_f32_e32 v56, v56
	v_exp_f32_e32 v57, v57
	v_sub_f32_e32 v58, v58, v83
	v_sub_f32_e32 v59, v59, v83
	v_sub_f32_e32 v60, v60, v83
	v_sub_f32_e32 v61, v61, v83
	v_exp_f32_e32 v58, v58
	v_exp_f32_e32 v59, v59
	v_exp_f32_e32 v60, v60
	v_exp_f32_e32 v61, v61
	v_sub_f32_e32 v62, v62, v83
	v_sub_f32_e32 v63, v63, v83
	v_sub_f32_e32 v64, v64, v83
	v_sub_f32_e32 v65, v65, v83
	v_exp_f32_e32 v62, v62
	v_exp_f32_e32 v63, v63
	v_exp_f32_e32 v64, v64
	v_exp_f32_e32 v65, v65
	v_sub_f32_e32 v66, v66, v83
	v_sub_f32_e32 v67, v67, v83
	v_sub_f32_e32 v68, v68, v83
	v_sub_f32_e32 v69, v69, v83
	v_exp_f32_e32 v66, v66
	v_exp_f32_e32 v67, v67
	v_exp_f32_e32 v68, v68
	v_exp_f32_e32 v69, v69
	s_nop 0
	v_add_f32_e32 v78, v54, v55
	v_add_f32_e32 v79, v56, v57
	v_add_f32_e32 v80, v58, v59
	v_add_f32_e32 v81, v60, v61
	v_add_f32_e32 v78, v78, v62
	v_add_f32_e32 v79, v79, v63
	v_add_f32_e32 v80, v80, v64
	v_add_f32_e32 v81, v81, v65
	v_add_f32_e32 v78, v78, v66
	v_add_f32_e32 v79, v79, v67
	v_add_f32_e32 v80, v80, v68
	v_add_f32_e32 v81, v81, v69
	v_add_f32_e32 v78, v78, v79
	v_add_f32_e32 v80, v80, v81
	v_add_f32_e32 v78, v78, v80
	v_cvt_pk_bf16_f32 v70, v54, v55
	v_cvt_pk_bf16_f32 v71, v56, v57
	v_cvt_pk_bf16_f32 v72, v58, v59
	v_cvt_pk_bf16_f32 v73, v60, v61
	v_cvt_pk_bf16_f32 v74, v62, v63
	v_cvt_pk_bf16_f32 v75, v64, v65
	v_cvt_pk_bf16_f32 v76, v66, v67
	v_cvt_pk_bf16_f32 v77, v68, v69
	v_mov_b32_e32 v79, v78
	s_nop 1
	v_permlane16_swap_b32_e32 v78, v79
	v_add_f32_e32 v78, v78, v79
	v_mov_b32_e32 v79, v78
	s_nop 1
	v_permlane32_swap_b32_e32 v78, v79
	v_add_f32_e32 v78, v78, v79
	v_fma_f32 v105, v105, v82, v78
	v_cmp_neq_f32_e64 s[4:5], 1.0, v82
	s_cmp_eq_u64 s[4:5], 0
	s_cbranch_scc1 .Lsl3_nosc_21
	v_pk_mul_f32 v[22:23], v[22:23], v[82:83] op_sel_hi:[1,0]
	v_pk_mul_f32 v[24:25], v[24:25], v[82:83] op_sel_hi:[1,0]
	v_pk_mul_f32 v[26:27], v[26:27], v[82:83] op_sel_hi:[1,0]
	v_pk_mul_f32 v[28:29], v[28:29], v[82:83] op_sel_hi:[1,0]
	v_pk_mul_f32 v[34:35], v[34:35], v[82:83] op_sel_hi:[1,0]
	v_pk_mul_f32 v[36:37], v[36:37], v[82:83] op_sel_hi:[1,0]
	v_pk_mul_f32 v[30:31], v[30:31], v[82:83] op_sel_hi:[1,0]
	v_pk_mul_f32 v[32:33], v[32:33], v[82:83] op_sel_hi:[1,0]

; #define LAS __attribute__((address_space(3)))
; __device__ __forceinline__ void nsa_unit(LAS unsigned char* lds, const Ctx& P, int l, int b, int hkv, int tb) {
;     ...
;         while (Ur != 0ull) {
;             const int ja = __builtin_ctzll(Ur); Ur &= Ur - 1ull; const bool hasb = Ur != 0ull; int jb = 0; if (hasb) { jb = __builtin_ctzll(Ur); Ur &= Ur - 1ull; }
;             __syncthreads();
;             load2(kb, vb, LDH, ja * 64, jb * 64, hasb, SEQ - 1);
;             __syncthreads();
; #pragma unroll
;             for (int sl = 0; sl < 2; ++sl) if (sl == 0 || hasb) {
;                 const int j = sl ? jb : ja; const LAS bf16_t* Ks = KV + sl * 9216; const LAS bf16_t* Vt = Ks + 4608;
;                 const bool far = t0 - (64 * j + 63) >= 790;
; #pragma unroll
;                 for (int sb = 0; sb < 2; ++sb) { const bool selj = (ms[sb] >> j) & 1ull; const int tqs = tq[sb];
;                     if (far) {
;                         if (__builtin_amdgcn_ballot_w64(selj) == 0ull) continue;
;                         attn_step<64>(qf[sb], Ks, Vt, o[sb], m[sb], lsum[sb], alpha, pf, pf1, lane,
;                             [&](int, float s) { return selj ? s * LOG2E + cfar : NEGBIG; });
;                     } else { const int kp0 = j * 64;
;                         attn_step<64>(qf[sb], Ks, Vt, o[sb], m[sb], lsum[sb], alpha, pf, pf1, lane,
;                             [&](int kk, float s) { const int dist = tqs - (kp0 + kk); return (selj && dist >= 0) ? s * LOG2E + lut[min((unsigned)dist, 1023u)] : NEGBIG; });
;                     }
;                 }
;             }
;         }
.Lsl3_skd_20:
.Lsl3_donex_7:
	s_add_i32 s40, s40, 1
	s_cmp_lt_u32 s40, s30
	s_cbranch_scc1 .Lsl3_slot_6
	s_cmp_lg_u32 s13, 0
	s_cbranch_scc1 .Lsl3_top
	s_nop 7

; __device__ __forceinline__ float bflo(unsigned w) { return __uint_as_float(w << 16); }
; __device__ __forceinline__ float bfhi(unsigned w) { return __uint_as_float(w & 0xffff0000u); }
; __device__ __forceinline__ void gmlp_unit(LAS unsigned char* lds, const Ctx& P, int l, int unit) {
;     ...
; #pragma unroll 2
;     for (int r = 0; r < 16; ++r) { const int t = wid * 16 + r; const bf16_t* row = H + (tok0 + t) * LDH + C_V;
;         const u32x4 a = *(const u32x4*)(row + lane * 8), bb = *(const u32x4*)(row + 512 + lane * 8);
;         const float x[16] = {bflo(a.x), bfhi(a.x), bflo(a.y), bfhi(a.y), bflo(a.z), bfhi(a.z), bflo(a.w), bfhi(a.w), bflo(bb.x), bfhi(bb.x), bflo(bb.y), bfhi(bb.y), bflo(bb.z), bfhi(bb.z), bflo(bb.w), bfhi(bb.w)};
;         float s = 0.f;
; #pragma unroll
;         for (int e = 0; e < 16; ++e) s += x[e];
;         const float mean = wave_sum(s) * (1.0f / 1024.0f); float q = 0.f;
; #pragma unroll
;         for (int e = 0; e < 16; ++e) q += (x[e] - mean) * (x[e] - mean);
;         const float var = wave_sum(q) * (1.0f / 1024.0f);
;         if (lane == 0) { stats[2 * t] = mean; stats[2 * t + 1] = rsqrtf(var + 1e-5f); } }
.LBB0_793:
	v_add_co_u32_e32 v8, vcc, 0xb203000, v6
	s_nop 1
	v_addc_co_u32_e32 v9, vcc, 0, v7, vcc
	s_mov_b64 s[4:5], 0
	v_lshl_add_u64 v[12:13], v[8:9], 0, s[4:5]
	global_load_dwordx4 v[16:19], v[12:13], off offset:2048
	global_load_dwordx4 v[20:23], v[12:13], off offset:3072
	s_add_u32 s4, s4, 0x5600
	s_addc_u32 s5, s5, 0
	v_lshl_add_u64 v[12:13], v[8:9], 0, s[4:5]
	global_load_dwordx4 v[24:27], v[12:13], off offset:2048
	global_load_dwordx4 v[28:31], v[12:13], off offset:3072
	s_add_u32 s4, s4, 0x5600
	s_addc_u32 s5, s5, 0
	v_lshl_add_u64 v[12:13], v[8:9], 0, s[4:5]
	global_load_dwordx4 v[32:35], v[12:13], off offset:2048
	global_load_dwordx4 v[36:39], v[12:13], off offset:3072
	s_add_u32 s4, s4, 0x5600
	s_addc_u32 s5, s5, 0
	v_lshl_add_u64 v[12:13], v[8:9], 0, s[4:5]
	global_load_dwordx4 v[40:43], v[12:13], off offset:2048
	global_load_dwordx4 v[44:47], v[12:13], off offset:3072
	s_add_u32 s4, s4, 0x5600
	s_addc_u32 s5, s5, 0
	v_lshl_add_u64 v[12:13], v[8:9], 0, s[4:5]
	global_load_dwordx4 v[48:51], v[12:13], off offset:2048
	global_load_dwordx4 v[52:55], v[12:13], off offset:3072
	s_add_u32 s4, s4, 0x5600
	s_addc_u32 s5, s5, 0
	v_lshl_add_u64 v[12:13], v[8:9], 0, s[4:5]
	global_load_dwordx4 v[56:59], v[12:13], off offset:2048
	global_load_dwordx4 v[60:63], v[12:13], off offset:3072
	s_add_u32 s4, s4, 0x5600
	s_addc_u32 s5, s5, 0
	v_lshl_add_u64 v[12:13], v[8:9], 0, s[4:5]
	global_load_dwordx4 v[114:117], v[12:13], off offset:2048
	global_load_dwordx4 v[118:121], v[12:13], off offset:3072
	s_add_u32 s4, s4, 0x5600
	s_addc_u32 s5, s5, 0
	v_lshl_add_u64 v[12:13], v[8:9], 0, s[4:5]
	global_load_dwordx4 v[122:125], v[12:13], off offset:2048
	global_load_dwordx4 v[126:129], v[12:13], off offset:3072
	s_add_u32 s4, s4, 0x5600
	s_addc_u32 s5, s5, 0
	v_lshl_add_u64 v[12:13], v[8:9], 0, s[4:5]
	global_load_dwordx4 v[130:133], v[12:13], off offset:2048
	global_load_dwordx4 v[134:137], v[12:13], off offset:3072
	s_add_u32 s4, s4, 0x5600
	s_addc_u32 s5, s5, 0
	v_lshl_add_u64 v[12:13], v[8:9], 0, s[4:5]
	global_load_dwordx4 v[138:141], v[12:13], off offset:2048
	global_load_dwordx4 v[142:145], v[12:13], off offset:3072
	s_add_u32 s4, s4, 0x5600
	s_addc_u32 s5, s5, 0
	v_lshl_add_u64 v[12:13], v[8:9], 0, s[4:5]
	global_load_dwordx4 v[146:149], v[12:13], off offset:2048
	global_load_dwordx4 v[150:153], v[12:13], off offset:3072
	s_add_u32 s4, s4, 0x5600
	s_addc_u32 s5, s5, 0
	v_lshl_add_u64 v[12:13], v[8:9], 0, s[4:5]
	global_load_dwordx4 v[154:157], v[12:13], off offset:2048
	global_load_dwordx4 v[158:161], v[12:13], off offset:3072
	s_add_u32 s4, s4, 0x5600
	s_addc_u32 s5, s5, 0
	v_lshl_add_u64 v[12:13], v[8:9], 0, s[4:5]
	global_load_dwordx4 v[170:173], v[12:13], off offset:2048
	global_load_dwordx4 v[174:177], v[12:13], off offset:3072
	s_add_u32 s4, s4, 0x5600
	s_addc_u32 s5, s5, 0
	v_lshl_add_u64 v[12:13], v[8:9], 0, s[4:5]
	global_load_dwordx4 v[178:181], v[12:13], off offset:2048
	global_load_dwordx4 v[182:185], v[12:13], off offset:3072
	s_add_u32 s4, s4, 0x5600
	s_addc_u32 s5, s5, 0
	v_lshl_add_u64 v[12:13], v[8:9], 0, s[4:5]
	global_load_dwordx4 v[186:189], v[12:13], off offset:2048
	global_load_dwordx4 v[190:193], v[12:13], off offset:3072
	s_add_u32 s4, s4, 0x5600
	s_addc_u32 s5, s5, 0
	v_lshl_add_u64 v[12:13], v[8:9], 0, s[4:5]
	global_load_dwordx4 v[194:197], v[12:13], off offset:2048
	global_load_dwordx4 v[198:201], v[12:13], off offset:3072
	s_waitcnt vmcnt(24)
	v_lshlrev_b32_e32 v80, 16, v16
	v_lshlrev_b32_e32 v86, 16, v24
	v_lshlrev_b32_e32 v92, 16, v32
	v_lshlrev_b32_e32 v232, 16, v40
	v_and_b32_e32 v81, 0xffff0000, v16
	v_and_b32_e32 v87, 0xffff0000, v24
	v_and_b32_e32 v93, 0xffff0000, v32
	v_and_b32_e32 v233, 0xffff0000, v40
	v_add_f32_e32 v78, 0, v80
	v_add_f32_e32 v84, 0, v86
	v_add_f32_e32 v90, 0, v92
	v_add_f32_e32 v230, 0, v232
	v_add_f32_e32 v78, v78, v81
	v_add_f32_e32 v84, v84, v87
	v_add_f32_e32 v90, v90, v93
	v_add_f32_e32 v230, v230, v233
	v_lshlrev_b32_e32 v80, 16, v17
	v_lshlrev_b32_e32 v86, 16, v25
	v_lshlrev_b32_e32 v92, 16, v33
	v_lshlrev_b32_e32 v232, 16, v41
	v_and_b32_e32 v81, 0xffff0000, v17
	v_and_b32_e32 v87, 0xffff0000, v25
	v_and_b32_e32 v93, 0xffff0000, v33
	v_and_b32_e32 v233, 0xffff0000, v41
	v_add_f32_e32 v78, v78, v80
	v_add_f32_e32 v84, v84, v86
	v_add_f32_e32 v90, v90, v92
	v_add_f32_e32 v230, v230, v232
	v_add_f32_e32 v78, v78, v81
	v_add_f32_e32 v84, v84, v87
	v_add_f32_e32 v90, v90, v93
	v_add_f32_e32 v230, v230, v233
	v_lshlrev_b32_e32 v80, 16, v18
	v_lshlrev_b32_e32 v86, 16, v26
	v_lshlrev_b32_e32 v92, 16, v34
	v_lshlrev_b32_e32 v232, 16, v42
	v_and_b32_e32 v81, 0xffff0000, v18
	v_and_b32_e32 v87, 0xffff0000, v26
	v_and_b32_e32 v93, 0xffff0000, v34
	v_and_b32_e32 v233, 0xffff0000, v42
	v_add_f32_e32 v78, v78, v80
	v_add_f32_e32 v84, v84, v86
	v_add_f32_e32 v90, v90, v92
	v_add_f32_e32 v230, v230, v232
	v_add_f32_e32 v78, v78, v81
	v_add_f32_e32 v84, v84, v87
	v_add_f32_e32 v90, v90, v93
	v_add_f32_e32 v230, v230, v233
	v_lshlrev_b32_e32 v80, 16, v19
	v_lshlrev_b32_e32 v86, 16, v27
	v_lshlrev_b32_e32 v92, 16, v35
	v_lshlrev_b32_e32 v232, 16, v43
	v_and_b32_e32 v81, 0xffff0000, v19
	v_and_b32_e32 v87, 0xffff0000, v27
	v_and_b32_e32 v93, 0xffff0000, v35
	v_and_b32_e32 v233, 0xffff0000, v43
	v_add_f32_e32 v78, v78, v80
	v_add_f32_e32 v84, v84, v86
	v_add_f32_e32 v90, v90, v92
	v_add_f32_e32 v230, v230, v232
	v_add_f32_e32 v78, v78, v81
	v_add_f32_e32 v84, v84, v87
	v_add_f32_e32 v90, v90, v93
	v_add_f32_e32 v230, v230, v233
	v_lshlrev_b32_e32 v80, 16, v20
	v_lshlrev_b32_e32 v86, 16, v28
	v_lshlrev_b32_e32 v92, 16, v36
	v_lshlrev_b32_e32 v232, 16, v44
	v_and_b32_e32 v81, 0xffff0000, v20
; __device__ __forceinline__ float bflo(unsigned w) { return __uint_as_float(w << 16); }
; __device__ __forceinline__ float bfhi(unsigned w) { return __uint_as_float(w & 0xffff0000u); }
; __device__ __forceinline__ void gmlp_unit(LAS unsigned char* lds, const Ctx& P, int l, int unit) {
;     ...
;         const float x[16] = {bflo(a.x), bfhi(a.x), bflo(a.y), bfhi(a.y), bflo(a.z), bfhi(a.z), bflo(a.w), bfhi(a.w), bflo(bb.x), bfhi(bb.x), bflo(bb.y), bfhi(bb.y), bflo(bb.z), bfhi(bb.z), bflo(bb.w), bfhi(bb.w)};
;         float s = 0.f;
; #pragma unroll
;         for (int e = 0; e < 16; ++e) s += x[e];
;         const float mean = wave_sum(s) * (1.0f / 1024.0f); float q = 0.f;
; #pragma unroll
;         for (int e = 0; e < 16; ++e) q += (x[e] - mean) * (x[e] - mean);
;         const float var = wave_sum(q) * (1.0f / 1024.0f);
	v_and_b32_e32 v87, 0xffff0000, v28
	v_and_b32_e32 v93, 0xffff0000, v36
	v_and_b32_e32 v233, 0xffff0000, v44
	v_add_f32_e32 v78, v78, v80
	v_add_f32_e32 v84, v84, v86
	v_add_f32_e32 v90, v90, v92
	v_add_f32_e32 v230, v230, v232
	v_add_f32_e32 v78, v78, v81
	v_add_f32_e32 v84, v84, v87
	v_add_f32_e32 v90, v90, v93
	v_add_f32_e32 v230, v230, v233
	v_lshlrev_b32_e32 v80, 16, v21
	v_lshlrev_b32_e32 v86, 16, v29
	v_lshlrev_b32_e32 v92, 16, v37
	v_lshlrev_b32_e32 v232, 16, v45
	v_and_b32_e32 v81, 0xffff0000, v21
	v_and_b32_e32 v87, 0xffff0000, v29
	v_and_b32_e32 v93, 0xffff0000, v37
	v_and_b32_e32 v233, 0xffff0000, v45
	v_add_f32_e32 v78, v78, v80
	v_add_f32_e32 v84, v84, v86
	v_add_f32_e32 v90, v90, v92
	v_add_f32_e32 v230, v230, v232
	v_add_f32_e32 v78, v78, v81
	v_add_f32_e32 v84, v84, v87
	v_add_f32_e32 v90, v90, v93
	v_add_f32_e32 v230, v230, v233
	v_lshlrev_b32_e32 v80, 16, v22
	v_lshlrev_b32_e32 v86, 16, v30
	v_lshlrev_b32_e32 v92, 16, v38
	v_lshlrev_b32_e32 v232, 16, v46
	v_and_b32_e32 v81, 0xffff0000, v22
	v_and_b32_e32 v87, 0xffff0000, v30
	v_and_b32_e32 v93, 0xffff0000, v38
	v_and_b32_e32 v233, 0xffff0000, v46
	v_add_f32_e32 v78, v78, v80
	v_add_f32_e32 v84, v84, v86
	v_add_f32_e32 v90, v90, v92
	v_add_f32_e32 v230, v230, v232
	v_add_f32_e32 v78, v78, v81
	v_add_f32_e32 v84, v84, v87
	v_add_f32_e32 v90, v90, v93
	v_add_f32_e32 v230, v230, v233
	v_lshlrev_b32_e32 v80, 16, v23
	v_lshlrev_b32_e32 v86, 16, v31
	v_lshlrev_b32_e32 v92, 16, v39
	v_lshlrev_b32_e32 v232, 16, v47
	v_and_b32_e32 v81, 0xffff0000, v23
	v_and_b32_e32 v87, 0xffff0000, v31
	v_and_b32_e32 v93, 0xffff0000, v39
	v_and_b32_e32 v233, 0xffff0000, v47
	v_add_f32_e32 v78, v78, v80
	v_add_f32_e32 v84, v84, v86
	v_add_f32_e32 v90, v90, v92
	v_add_f32_e32 v230, v230, v232
	v_add_f32_e32 v78, v78, v81
	v_add_f32_e32 v84, v84, v87
	v_add_f32_e32 v90, v90, v93
	v_add_f32_e32 v230, v230, v233
	v_add_f32_dpp v78, v78, v78 row_ror:8 row_mask:0xf bank_mask:0xf
	v_add_f32_dpp v84, v84, v84 row_ror:8 row_mask:0xf bank_mask:0xf
	v_add_f32_dpp v90, v90, v90 row_ror:8 row_mask:0xf bank_mask:0xf
	v_add_f32_dpp v230, v230, v230 row_ror:8 row_mask:0xf bank_mask:0xf
	v_add_f32_dpp v78, v78, v78 row_ror:4 row_mask:0xf bank_mask:0xf
	v_add_f32_dpp v84, v84, v84 row_ror:4 row_mask:0xf bank_mask:0xf
	v_add_f32_dpp v90, v90, v90 row_ror:4 row_mask:0xf bank_mask:0xf
	v_add_f32_dpp v230, v230, v230 row_ror:4 row_mask:0xf bank_mask:0xf
	v_add_f32_dpp v78, v78, v78 row_ror:2 row_mask:0xf bank_mask:0xf
	v_add_f32_dpp v84, v84, v84 row_ror:2 row_mask:0xf bank_mask:0xf
	v_add_f32_dpp v90, v90, v90 row_ror:2 row_mask:0xf bank_mask:0xf
	v_add_f32_dpp v230, v230, v230 row_ror:2 row_mask:0xf bank_mask:0xf
	v_add_f32_dpp v78, v78, v78 row_ror:1 row_mask:0xf bank_mask:0xf
	v_add_f32_dpp v84, v84, v84 row_ror:1 row_mask:0xf bank_mask:0xf
	v_add_f32_dpp v90, v90, v90 row_ror:1 row_mask:0xf bank_mask:0xf
	v_add_f32_dpp v230, v230, v230 row_ror:1 row_mask:0xf bank_mask:0xf
	v_mov_b32_e32 v80, v78
	v_mov_b32_e32 v86, v84
	v_mov_b32_e32 v92, v90
	v_mov_b32_e32 v232, v230
	v_permlane16_swap_b32_e32 v78, v80
	v_permlane16_swap_b32_e32 v84, v86
	v_permlane16_swap_b32_e32 v90, v92
	v_permlane16_swap_b32_e32 v230, v232
	v_add_f32_e32 v78, v78, v80
	v_add_f32_e32 v84, v84, v86
	v_add_f32_e32 v90, v90, v92
	v_add_f32_e32 v230, v230, v232
	v_mov_b32_e32 v80, v78
	v_mov_b32_e32 v86, v84
	v_mov_b32_e32 v92, v90
	v_mov_b32_e32 v232, v230
	v_permlane32_swap_b32_e32 v78, v80
	v_permlane32_swap_b32_e32 v84, v86
	v_permlane32_swap_b32_e32 v90, v92
	v_permlane32_swap_b32_e32 v230, v232
	v_add_f32_e32 v78, v78, v80
	v_add_f32_e32 v84, v84, v86
	v_add_f32_e32 v90, v90, v92
	v_add_f32_e32 v230, v230, v232
	v_lshlrev_b32_e32 v80, 16, v16
	v_lshlrev_b32_e32 v86, 16, v24
	v_lshlrev_b32_e32 v92, 16, v32
	v_lshlrev_b32_e32 v232, 16, v40
	v_and_b32_e32 v81, 0xffff0000, v16
	v_and_b32_e32 v87, 0xffff0000, v24
	v_and_b32_e32 v93, 0xffff0000, v32
	v_and_b32_e32 v233, 0xffff0000, v40
	v_fmac_f32_e32 v80, 0xba800000, v78
	v_fmac_f32_e32 v86, 0xba800000, v84
	v_fmac_f32_e32 v92, 0xba800000, v90
	v_fmac_f32_e32 v232, 0xba800000, v230
	v_fmac_f32_e32 v81, 0xba800000, v78
	v_fmac_f32_e32 v87, 0xba800000, v84
	v_fmac_f32_e32 v93, 0xba800000, v90
	v_fmac_f32_e32 v233, 0xba800000, v230
	v_mul_f32_e32 v79, v81, v81
	v_mul_f32_e32 v85, v87, v87
	v_mul_f32_e32 v91, v93, v93
	v_mul_f32_e32 v231, v233, v233
	v_fmac_f32_e32 v79, v80, v80
	v_fmac_f32_e32 v85, v86, v86
	v_fmac_f32_e32 v91, v92, v92
	v_fmac_f32_e32 v231, v232, v232
	v_lshlrev_b32_e32 v80, 16, v17
	v_lshlrev_b32_e32 v86, 16, v25
	v_lshlrev_b32_e32 v92, 16, v33
	v_lshlrev_b32_e32 v232, 16, v41
	v_and_b32_e32 v81, 0xffff0000, v17
	v_and_b32_e32 v87, 0xffff0000, v25
	v_and_b32_e32 v93, 0xffff0000, v33
	v_and_b32_e32 v233, 0xffff0000, v41
	v_fmac_f32_e32 v80, 0xba800000, v78
	v_fmac_f32_e32 v86, 0xba800000, v84
	v_fmac_f32_e32 v92, 0xba800000, v90
	v_fmac_f32_e32 v232, 0xba800000, v230
	v_fmac_f32_e32 v81, 0xba800000, v78
	v_fmac_f32_e32 v87, 0xba800000, v84
	v_fmac_f32_e32 v93, 0xba800000, v90
	v_fmac_f32_e32 v233, 0xba800000, v230
	v_fmac_f32_e32 v79, v80, v80
	v_fmac_f32_e32 v85, v86, v86
	v_fmac_f32_e32 v91, v92, v92
	v_fmac_f32_e32 v231, v232, v232
	v_fmac_f32_e32 v79, v81, v81
	v_fmac_f32_e32 v85, v87, v87
	v_fmac_f32_e32 v91, v93, v93
	v_fmac_f32_e32 v231, v233, v233
	v_lshlrev_b32_e32 v80, 16, v18
	v_lshlrev_b32_e32 v86, 16, v26
	v_lshlrev_b32_e32 v92, 16, v34
	v_lshlrev_b32_e32 v232, 16, v42
	v_and_b32_e32 v81, 0xffff0000, v18
	v_and_b32_e32 v87, 0xffff0000, v26
	v_and_b32_e32 v93, 0xffff0000, v34
	v_and_b32_e32 v233, 0xffff0000, v42
	v_fmac_f32_e32 v80, 0xba800000, v78
; __device__ __forceinline__ void gmlp_unit(LAS unsigned char* lds, const Ctx& P, int l, int unit) {
;     ...
; #pragma unroll
;         for (int e = 0; e < 16; ++e) q += (x[e] - mean) * (x[e] - mean);
;         const float var = wave_sum(q) * (1.0f / 1024.0f);
	v_fmac_f32_e32 v86, 0xba800000, v84
	v_fmac_f32_e32 v92, 0xba800000, v90
	v_fmac_f32_e32 v232, 0xba800000, v230
	v_fmac_f32_e32 v81, 0xba800000, v78
	v_fmac_f32_e32 v87, 0xba800000, v84
	v_fmac_f32_e32 v93, 0xba800000, v90
	v_fmac_f32_e32 v233, 0xba800000, v230
	v_fmac_f32_e32 v79, v80, v80
	v_fmac_f32_e32 v85, v86, v86
	v_fmac_f32_e32 v91, v92, v92
	v_fmac_f32_e32 v231, v232, v232
	v_fmac_f32_e32 v79, v81, v81
	v_fmac_f32_e32 v85, v87, v87
	v_fmac_f32_e32 v91, v93, v93
	v_fmac_f32_e32 v231, v233, v233
	v_lshlrev_b32_e32 v80, 16, v19
	v_lshlrev_b32_e32 v86, 16, v27
	v_lshlrev_b32_e32 v92, 16, v35
	v_lshlrev_b32_e32 v232, 16, v43
	v_and_b32_e32 v81, 0xffff0000, v19
	v_and_b32_e32 v87, 0xffff0000, v27
	v_and_b32_e32 v93, 0xffff0000, v35
	v_and_b32_e32 v233, 0xffff0000, v43
	v_fmac_f32_e32 v80, 0xba800000, v78
	v_fmac_f32_e32 v86, 0xba800000, v84
	v_fmac_f32_e32 v92, 0xba800000, v90
	v_fmac_f32_e32 v232, 0xba800000, v230
	v_fmac_f32_e32 v81, 0xba800000, v78
	v_fmac_f32_e32 v87, 0xba800000, v84
	v_fmac_f32_e32 v93, 0xba800000, v90
	v_fmac_f32_e32 v233, 0xba800000, v230
	v_fmac_f32_e32 v79, v80, v80
	v_fmac_f32_e32 v85, v86, v86
	v_fmac_f32_e32 v91, v92, v92
	v_fmac_f32_e32 v231, v232, v232
	v_fmac_f32_e32 v79, v81, v81
	v_fmac_f32_e32 v85, v87, v87
	v_fmac_f32_e32 v91, v93, v93
	v_fmac_f32_e32 v231, v233, v233
	v_lshlrev_b32_e32 v80, 16, v20
	v_lshlrev_b32_e32 v86, 16, v28
	v_lshlrev_b32_e32 v92, 16, v36
	v_lshlrev_b32_e32 v232, 16, v44
	v_and_b32_e32 v81, 0xffff0000, v20
	v_and_b32_e32 v87, 0xffff0000, v28
	v_and_b32_e32 v93, 0xffff0000, v36
	v_and_b32_e32 v233, 0xffff0000, v44
	v_fmac_f32_e32 v80, 0xba800000, v78
	v_fmac_f32_e32 v86, 0xba800000, v84
	v_fmac_f32_e32 v92, 0xba800000, v90
	v_fmac_f32_e32 v232, 0xba800000, v230
	v_fmac_f32_e32 v81, 0xba800000, v78
	v_fmac_f32_e32 v87, 0xba800000, v84
	v_fmac_f32_e32 v93, 0xba800000, v90
	v_fmac_f32_e32 v233, 0xba800000, v230
	v_fmac_f32_e32 v79, v80, v80
	v_fmac_f32_e32 v85, v86, v86
	v_fmac_f32_e32 v91, v92, v92
	v_fmac_f32_e32 v231, v232, v232
	v_fmac_f32_e32 v79, v81, v81
	v_fmac_f32_e32 v85, v87, v87
	v_fmac_f32_e32 v91, v93, v93
	v_fmac_f32_e32 v231, v233, v233
	v_lshlrev_b32_e32 v80, 16, v21
	v_lshlrev_b32_e32 v86, 16, v29
	v_lshlrev_b32_e32 v92, 16, v37
	v_lshlrev_b32_e32 v232, 16, v45
	v_and_b32_e32 v81, 0xffff0000, v21
	v_and_b32_e32 v87, 0xffff0000, v29
	v_and_b32_e32 v93, 0xffff0000, v37
	v_and_b32_e32 v233, 0xffff0000, v45
	v_fmac_f32_e32 v80, 0xba800000, v78
	v_fmac_f32_e32 v86, 0xba800000, v84
	v_fmac_f32_e32 v92, 0xba800000, v90
	v_fmac_f32_e32 v232, 0xba800000, v230
	v_fmac_f32_e32 v81, 0xba800000, v78
	v_fmac_f32_e32 v87, 0xba800000, v84
	v_fmac_f32_e32 v93, 0xba800000, v90
	v_fmac_f32_e32 v233, 0xba800000, v230
	v_fmac_f32_e32 v79, v80, v80
	v_fmac_f32_e32 v85, v86, v86
	v_fmac_f32_e32 v91, v92, v92
	v_fmac_f32_e32 v231, v232, v232
	v_fmac_f32_e32 v79, v81, v81
	v_fmac_f32_e32 v85, v87, v87
	v_fmac_f32_e32 v91, v93, v93
	v_fmac_f32_e32 v231, v233, v233
	v_lshlrev_b32_e32 v80, 16, v22
	v_lshlrev_b32_e32 v86, 16, v30
	v_lshlrev_b32_e32 v92, 16, v38
	v_lshlrev_b32_e32 v232, 16, v46
	v_and_b32_e32 v81, 0xffff0000, v22
	v_and_b32_e32 v87, 0xffff0000, v30
	v_and_b32_e32 v93, 0xffff0000, v38
	v_and_b32_e32 v233, 0xffff0000, v46
	v_fmac_f32_e32 v80, 0xba800000, v78
	v_fmac_f32_e32 v86, 0xba800000, v84
	v_fmac_f32_e32 v92, 0xba800000, v90
	v_fmac_f32_e32 v232, 0xba800000, v230
	v_fmac_f32_e32 v81, 0xba800000, v78
	v_fmac_f32_e32 v87, 0xba800000, v84
	v_fmac_f32_e32 v93, 0xba800000, v90
	v_fmac_f32_e32 v233, 0xba800000, v230
	v_fmac_f32_e32 v79, v80, v80
	v_fmac_f32_e32 v85, v86, v86
	v_fmac_f32_e32 v91, v92, v92
	v_fmac_f32_e32 v231, v232, v232
	v_fmac_f32_e32 v79, v81, v81
	v_fmac_f32_e32 v85, v87, v87
	v_fmac_f32_e32 v91, v93, v93
	v_fmac_f32_e32 v231, v233, v233
	v_lshlrev_b32_e32 v80, 16, v23
	v_lshlrev_b32_e32 v86, 16, v31
	v_lshlrev_b32_e32 v92, 16, v39
	v_lshlrev_b32_e32 v232, 16, v47
	v_and_b32_e32 v81, 0xffff0000, v23
	v_and_b32_e32 v87, 0xffff0000, v31
	v_and_b32_e32 v93, 0xffff0000, v39
	v_and_b32_e32 v233, 0xffff0000, v47
	v_fmac_f32_e32 v80, 0xba800000, v78
	v_fmac_f32_e32 v86, 0xba800000, v84
	v_fmac_f32_e32 v92, 0xba800000, v90
	v_fmac_f32_e32 v232, 0xba800000, v230
	v_fmac_f32_e32 v81, 0xba800000, v78
	v_fmac_f32_e32 v87, 0xba800000, v84
	v_fmac_f32_e32 v93, 0xba800000, v90
	v_fmac_f32_e32 v233, 0xba800000, v230
	v_fmac_f32_e32 v79, v80, v80
	v_fmac_f32_e32 v85, v86, v86
	v_fmac_f32_e32 v91, v92, v92
	v_fmac_f32_e32 v231, v232, v232
	v_fmac_f32_e32 v79, v81, v81
	v_fmac_f32_e32 v85, v87, v87
	v_fmac_f32_e32 v91, v93, v93
	v_fmac_f32_e32 v231, v233, v233
	v_add_f32_dpp v79, v79, v79 row_ror:8 row_mask:0xf bank_mask:0xf
	v_add_f32_dpp v85, v85, v85 row_ror:8 row_mask:0xf bank_mask:0xf
	v_add_f32_dpp v91, v91, v91 row_ror:8 row_mask:0xf bank_mask:0xf
	v_add_f32_dpp v231, v231, v231 row_ror:8 row_mask:0xf bank_mask:0xf
	v_add_f32_dpp v79, v79, v79 row_ror:4 row_mask:0xf bank_mask:0xf
	v_add_f32_dpp v85, v85, v85 row_ror:4 row_mask:0xf bank_mask:0xf
	v_add_f32_dpp v91, v91, v91 row_ror:4 row_mask:0xf bank_mask:0xf
	v_add_f32_dpp v231, v231, v231 row_ror:4 row_mask:0xf bank_mask:0xf
	v_add_f32_dpp v79, v79, v79 row_ror:2 row_mask:0xf bank_mask:0xf
	v_add_f32_dpp v85, v85, v85 row_ror:2 row_mask:0xf bank_mask:0xf
	v_add_f32_dpp v91, v91, v91 row_ror:2 row_mask:0xf bank_mask:0xf
	v_add_f32_dpp v231, v231, v231 row_ror:2 row_mask:0xf bank_mask:0xf
	v_add_f32_dpp v79, v79, v79 row_ror:1 row_mask:0xf bank_mask:0xf
	v_add_f32_dpp v85, v85, v85 row_ror:1 row_mask:0xf bank_mask:0xf
	v_add_f32_dpp v91, v91, v91 row_ror:1 row_mask:0xf bank_mask:0xf
; __device__ __forceinline__ void gmlp_unit(LAS unsigned char* lds, const Ctx& P, int l, int unit) {
;     ...
;         const float mean = wave_sum(s) * (1.0f / 1024.0f); float q = 0.f;
; #pragma unroll
;         for (int e = 0; e < 16; ++e) q += (x[e] - mean) * (x[e] - mean);
;         const float var = wave_sum(q) * (1.0f / 1024.0f);
;         if (lane == 0) { stats[2 * t] = mean; stats[2 * t + 1] = rsqrtf(var + 1e-5f); } }
	v_add_f32_dpp v231, v231, v231 row_ror:1 row_mask:0xf bank_mask:0xf
	v_mov_b32_e32 v80, v79
	v_mov_b32_e32 v86, v85
	v_mov_b32_e32 v92, v91
	v_mov_b32_e32 v232, v231
	v_permlane16_swap_b32_e32 v79, v80
	v_permlane16_swap_b32_e32 v85, v86
	v_permlane16_swap_b32_e32 v91, v92
	v_permlane16_swap_b32_e32 v231, v232
	v_add_f32_e32 v79, v79, v80
	v_add_f32_e32 v85, v85, v86
	v_add_f32_e32 v91, v91, v92
	v_add_f32_e32 v231, v231, v232
	v_mov_b32_e32 v80, v79
	v_mov_b32_e32 v86, v85
	v_mov_b32_e32 v92, v91
	v_mov_b32_e32 v232, v231
	v_permlane32_swap_b32_e32 v79, v80
	v_permlane32_swap_b32_e32 v85, v86
	v_permlane32_swap_b32_e32 v91, v92
	v_permlane32_swap_b32_e32 v231, v232
	v_add_f32_e32 v79, v79, v80
	v_add_f32_e32 v85, v85, v86
	v_add_f32_e32 v91, v91, v92
	v_add_f32_e32 v231, v231, v232
	v_fmamk_f32 v79, v79, 0x3a800000, v236
	v_mul_f32_e32 v80, 0x4b800000, v79
	v_cmp_gt_f32_e32 vcc, s81, v79
	v_mul_f32_e32 v78, 0x3a800000, v78
	s_nop 0
	v_cndmask_b32_e32 v79, v79, v80, vcc
	v_rsq_f32_e32 v79, v79
	s_nop 0
	v_mul_f32_e32 v80, 0x45800000, v79
	v_cndmask_b32_e32 v79, v79, v80, vcc
	v_fmamk_f32 v85, v85, 0x3a800000, v236
	v_mul_f32_e32 v86, 0x4b800000, v85
	v_cmp_gt_f32_e32 vcc, s81, v85
	v_mul_f32_e32 v84, 0x3a800000, v84
	s_nop 0
	v_cndmask_b32_e32 v85, v85, v86, vcc
	v_rsq_f32_e32 v85, v85
	s_nop 0
	v_mul_f32_e32 v86, 0x45800000, v85
	v_cndmask_b32_e32 v85, v85, v86, vcc
	v_fmamk_f32 v91, v91, 0x3a800000, v236
	v_mul_f32_e32 v92, 0x4b800000, v91
	v_cmp_gt_f32_e32 vcc, s81, v91
	v_mul_f32_e32 v90, 0x3a800000, v90
	s_nop 0
	v_cndmask_b32_e32 v91, v91, v92, vcc
	v_rsq_f32_e32 v91, v91
	s_nop 0
	v_mul_f32_e32 v92, 0x45800000, v91
	v_cndmask_b32_e32 v91, v91, v92, vcc
	v_fmamk_f32 v231, v231, 0x3a800000, v236
	v_mul_f32_e32 v232, 0x4b800000, v231
	v_cmp_gt_f32_e32 vcc, s81, v231
	v_mul_f32_e32 v230, 0x3a800000, v230
	s_nop 0
	v_cndmask_b32_e32 v231, v231, v232, vcc
	v_rsq_f32_e32 v231, v231
	s_nop 0
	v_mul_f32_e32 v232, 0x45800000, v231
	v_cndmask_b32_e32 v231, v231, v232, vcc
	s_and_saveexec_b64 s[14:15], s[6:7]
	ds_write_b64 v15, v[78:79]
	ds_write_b64 v15, v[84:85] offset:8
	ds_write_b64 v15, v[90:91] offset:16
	ds_write_b64 v15, v[230:231] offset:24
	s_or_b64 exec, exec, s[14:15]
	s_waitcnt vmcnt(16)
	v_lshlrev_b32_e32 v80, 16, v48
	v_lshlrev_b32_e32 v86, 16, v56
	v_lshlrev_b32_e32 v92, 16, v114
	v_lshlrev_b32_e32 v232, 16, v122
	v_and_b32_e32 v81, 0xffff0000, v48
	v_and_b32_e32 v87, 0xffff0000, v56
	v_and_b32_e32 v93, 0xffff0000, v114
	v_and_b32_e32 v233, 0xffff0000, v122
	v_add_f32_e32 v78, 0, v80
	v_add_f32_e32 v84, 0, v86
	v_add_f32_e32 v90, 0, v92
	v_add_f32_e32 v230, 0, v232
	v_add_f32_e32 v78, v78, v81
	v_add_f32_e32 v84, v84, v87
	v_add_f32_e32 v90, v90, v93
	v_add_f32_e32 v230, v230, v233
	v_lshlrev_b32_e32 v80, 16, v49
	v_lshlrev_b32_e32 v86, 16, v57
	v_lshlrev_b32_e32 v92, 16, v115
	v_lshlrev_b32_e32 v232, 16, v123
	v_and_b32_e32 v81, 0xffff0000, v49
	v_and_b32_e32 v87, 0xffff0000, v57
	v_and_b32_e32 v93, 0xffff0000, v115
	v_and_b32_e32 v233, 0xffff0000, v123
	v_add_f32_e32 v78, v78, v80
	v_add_f32_e32 v84, v84, v86
	v_add_f32_e32 v90, v90, v92
	v_add_f32_e32 v230, v230, v232
	v_add_f32_e32 v78, v78, v81
	v_add_f32_e32 v84, v84, v87
	v_add_f32_e32 v90, v90, v93
	v_add_f32_e32 v230, v230, v233
	v_lshlrev_b32_e32 v80, 16, v50
	v_lshlrev_b32_e32 v86, 16, v58
	v_lshlrev_b32_e32 v92, 16, v116
	v_lshlrev_b32_e32 v232, 16, v124
	v_and_b32_e32 v81, 0xffff0000, v50
	v_and_b32_e32 v87, 0xffff0000, v58
	v_and_b32_e32 v93, 0xffff0000, v116
	v_and_b32_e32 v233, 0xffff0000, v124
	v_add_f32_e32 v78, v78, v80
	v_add_f32_e32 v84, v84, v86
	v_add_f32_e32 v90, v90, v92
	v_add_f32_e32 v230, v230, v232
	v_add_f32_e32 v78, v78, v81
	v_add_f32_e32 v84, v84, v87
	v_add_f32_e32 v90, v90, v93
	v_add_f32_e32 v230, v230, v233
	v_lshlrev_b32_e32 v80, 16, v51
	v_lshlrev_b32_e32 v86, 16, v59
	v_lshlrev_b32_e32 v92, 16, v117
	v_lshlrev_b32_e32 v232, 16, v125
	v_and_b32_e32 v81, 0xffff0000, v51
	v_and_b32_e32 v87, 0xffff0000, v59
	v_and_b32_e32 v93, 0xffff0000, v117
	v_and_b32_e32 v233, 0xffff0000, v125
	v_add_f32_e32 v78, v78, v80
	v_add_f32_e32 v84, v84, v86
	v_add_f32_e32 v90, v90, v92
	v_add_f32_e32 v230, v230, v232
	v_add_f32_e32 v78, v78, v81
	v_add_f32_e32 v84, v84, v87
	v_add_f32_e32 v90, v90, v93
	v_add_f32_e32 v230, v230, v233
	v_lshlrev_b32_e32 v80, 16, v52
	v_lshlrev_b32_e32 v86, 16, v60
	v_lshlrev_b32_e32 v92, 16, v118
	v_lshlrev_b32_e32 v232, 16, v126
	v_and_b32_e32 v81, 0xffff0000, v52
	v_and_b32_e32 v87, 0xffff0000, v60
	v_and_b32_e32 v93, 0xffff0000, v118
	v_and_b32_e32 v233, 0xffff0000, v126
	v_add_f32_e32 v78, v78, v80
	v_add_f32_e32 v84, v84, v86
	v_add_f32_e32 v90, v90, v92
	v_add_f32_e32 v230, v230, v232
	v_add_f32_e32 v78, v78, v81
	v_add_f32_e32 v84, v84, v87
	v_add_f32_e32 v90, v90, v93
	v_add_f32_e32 v230, v230, v233
	v_lshlrev_b32_e32 v80, 16, v53
	v_lshlrev_b32_e32 v86, 16, v61
	v_lshlrev_b32_e32 v92, 16, v119
	v_lshlrev_b32_e32 v232, 16, v127
	v_and_b32_e32 v81, 0xffff0000, v53
	v_and_b32_e32 v87, 0xffff0000, v61
	v_and_b32_e32 v93, 0xffff0000, v119
	v_and_b32_e32 v233, 0xffff0000, v127
	v_add_f32_e32 v78, v78, v80
	v_add_f32_e32 v84, v84, v86
	v_add_f32_e32 v90, v90, v92
	v_add_f32_e32 v230, v230, v232
	v_add_f32_e32 v78, v78, v81
	v_add_f32_e32 v84, v84, v87
	v_add_f32_e32 v90, v90, v93
	v_add_f32_e32 v230, v230, v233
	v_lshlrev_b32_e32 v80, 16, v54
	v_lshlrev_b32_e32 v86, 16, v62
	v_lshlrev_b32_e32 v92, 16, v120
	v_lshlrev_b32_e32 v232, 16, v128
	v_and_b32_e32 v81, 0xffff0000, v54
	v_and_b32_e32 v87, 0xffff0000, v62
	v_and_b32_e32 v93, 0xffff0000, v120
	v_and_b32_e32 v233, 0xffff0000, v128
	v_add_f32_e32 v78, v78, v80
; __device__ __forceinline__ float bflo(unsigned w) { return __uint_as_float(w << 16); }
; __device__ __forceinline__ float bfhi(unsigned w) { return __uint_as_float(w & 0xffff0000u); }
; __device__ __forceinline__ void gmlp_unit(LAS unsigned char* lds, const Ctx& P, int l, int unit) {
;     ...
;         const float x[16] = {bflo(a.x), bfhi(a.x), bflo(a.y), bfhi(a.y), bflo(a.z), bfhi(a.z), bflo(a.w), bfhi(a.w), bflo(bb.x), bfhi(bb.x), bflo(bb.y), bfhi(bb.y), bflo(bb.z), bfhi(bb.z), bflo(bb.w), bfhi(bb.w)};
;         float s = 0.f;
; #pragma unroll
;         for (int e = 0; e < 16; ++e) s += x[e];
;         const float mean = wave_sum(s) * (1.0f / 1024.0f); float q = 0.f;
; #pragma unroll
;         for (int e = 0; e < 16; ++e) q += (x[e] - mean) * (x[e] - mean);
;         const float var = wave_sum(q) * (1.0f / 1024.0f);
	v_add_f32_e32 v84, v84, v86
	v_add_f32_e32 v90, v90, v92
	v_add_f32_e32 v230, v230, v232
	v_add_f32_e32 v78, v78, v81
	v_add_f32_e32 v84, v84, v87
	v_add_f32_e32 v90, v90, v93
	v_add_f32_e32 v230, v230, v233
	v_lshlrev_b32_e32 v80, 16, v55
	v_lshlrev_b32_e32 v86, 16, v63
	v_lshlrev_b32_e32 v92, 16, v121
	v_lshlrev_b32_e32 v232, 16, v129
	v_and_b32_e32 v81, 0xffff0000, v55
	v_and_b32_e32 v87, 0xffff0000, v63
	v_and_b32_e32 v93, 0xffff0000, v121
	v_and_b32_e32 v233, 0xffff0000, v129
	v_add_f32_e32 v78, v78, v80
	v_add_f32_e32 v84, v84, v86
	v_add_f32_e32 v90, v90, v92
	v_add_f32_e32 v230, v230, v232
	v_add_f32_e32 v78, v78, v81
	v_add_f32_e32 v84, v84, v87
	v_add_f32_e32 v90, v90, v93
	v_add_f32_e32 v230, v230, v233
	v_add_f32_dpp v78, v78, v78 row_ror:8 row_mask:0xf bank_mask:0xf
	v_add_f32_dpp v84, v84, v84 row_ror:8 row_mask:0xf bank_mask:0xf
	v_add_f32_dpp v90, v90, v90 row_ror:8 row_mask:0xf bank_mask:0xf
	v_add_f32_dpp v230, v230, v230 row_ror:8 row_mask:0xf bank_mask:0xf
	v_add_f32_dpp v78, v78, v78 row_ror:4 row_mask:0xf bank_mask:0xf
	v_add_f32_dpp v84, v84, v84 row_ror:4 row_mask:0xf bank_mask:0xf
	v_add_f32_dpp v90, v90, v90 row_ror:4 row_mask:0xf bank_mask:0xf
	v_add_f32_dpp v230, v230, v230 row_ror:4 row_mask:0xf bank_mask:0xf
	v_add_f32_dpp v78, v78, v78 row_ror:2 row_mask:0xf bank_mask:0xf
	v_add_f32_dpp v84, v84, v84 row_ror:2 row_mask:0xf bank_mask:0xf
	v_add_f32_dpp v90, v90, v90 row_ror:2 row_mask:0xf bank_mask:0xf
	v_add_f32_dpp v230, v230, v230 row_ror:2 row_mask:0xf bank_mask:0xf
	v_add_f32_dpp v78, v78, v78 row_ror:1 row_mask:0xf bank_mask:0xf
	v_add_f32_dpp v84, v84, v84 row_ror:1 row_mask:0xf bank_mask:0xf
	v_add_f32_dpp v90, v90, v90 row_ror:1 row_mask:0xf bank_mask:0xf
	v_add_f32_dpp v230, v230, v230 row_ror:1 row_mask:0xf bank_mask:0xf
	v_mov_b32_e32 v80, v78
	v_mov_b32_e32 v86, v84
	v_mov_b32_e32 v92, v90
	v_mov_b32_e32 v232, v230
	v_permlane16_swap_b32_e32 v78, v80
	v_permlane16_swap_b32_e32 v84, v86
	v_permlane16_swap_b32_e32 v90, v92
	v_permlane16_swap_b32_e32 v230, v232
	v_add_f32_e32 v78, v78, v80
	v_add_f32_e32 v84, v84, v86
	v_add_f32_e32 v90, v90, v92
	v_add_f32_e32 v230, v230, v232
	v_mov_b32_e32 v80, v78
	v_mov_b32_e32 v86, v84
	v_mov_b32_e32 v92, v90
	v_mov_b32_e32 v232, v230
	v_permlane32_swap_b32_e32 v78, v80
	v_permlane32_swap_b32_e32 v84, v86
	v_permlane32_swap_b32_e32 v90, v92
	v_permlane32_swap_b32_e32 v230, v232
	v_add_f32_e32 v78, v78, v80
	v_add_f32_e32 v84, v84, v86
	v_add_f32_e32 v90, v90, v92
	v_add_f32_e32 v230, v230, v232
	v_lshlrev_b32_e32 v80, 16, v48
	v_lshlrev_b32_e32 v86, 16, v56
	v_lshlrev_b32_e32 v92, 16, v114
	v_lshlrev_b32_e32 v232, 16, v122
	v_and_b32_e32 v81, 0xffff0000, v48
	v_and_b32_e32 v87, 0xffff0000, v56
	v_and_b32_e32 v93, 0xffff0000, v114
	v_and_b32_e32 v233, 0xffff0000, v122
	v_fmac_f32_e32 v80, 0xba800000, v78
	v_fmac_f32_e32 v86, 0xba800000, v84
	v_fmac_f32_e32 v92, 0xba800000, v90
	v_fmac_f32_e32 v232, 0xba800000, v230
	v_fmac_f32_e32 v81, 0xba800000, v78
	v_fmac_f32_e32 v87, 0xba800000, v84
	v_fmac_f32_e32 v93, 0xba800000, v90
	v_fmac_f32_e32 v233, 0xba800000, v230
	v_mul_f32_e32 v79, v81, v81
	v_mul_f32_e32 v85, v87, v87
	v_mul_f32_e32 v91, v93, v93
	v_mul_f32_e32 v231, v233, v233
	v_fmac_f32_e32 v79, v80, v80
	v_fmac_f32_e32 v85, v86, v86
	v_fmac_f32_e32 v91, v92, v92
	v_fmac_f32_e32 v231, v232, v232
	v_lshlrev_b32_e32 v80, 16, v49
	v_lshlrev_b32_e32 v86, 16, v57
	v_lshlrev_b32_e32 v92, 16, v115
	v_lshlrev_b32_e32 v232, 16, v123
	v_and_b32_e32 v81, 0xffff0000, v49
	v_and_b32_e32 v87, 0xffff0000, v57
	v_and_b32_e32 v93, 0xffff0000, v115
	v_and_b32_e32 v233, 0xffff0000, v123
	v_fmac_f32_e32 v80, 0xba800000, v78
	v_fmac_f32_e32 v86, 0xba800000, v84
	v_fmac_f32_e32 v92, 0xba800000, v90
	v_fmac_f32_e32 v232, 0xba800000, v230
	v_fmac_f32_e32 v81, 0xba800000, v78
	v_fmac_f32_e32 v87, 0xba800000, v84
	v_fmac_f32_e32 v93, 0xba800000, v90
	v_fmac_f32_e32 v233, 0xba800000, v230
	v_fmac_f32_e32 v79, v80, v80
	v_fmac_f32_e32 v85, v86, v86
	v_fmac_f32_e32 v91, v92, v92
	v_fmac_f32_e32 v231, v232, v232
	v_fmac_f32_e32 v79, v81, v81
	v_fmac_f32_e32 v85, v87, v87
	v_fmac_f32_e32 v91, v93, v93
	v_fmac_f32_e32 v231, v233, v233
	v_lshlrev_b32_e32 v80, 16, v50
	v_lshlrev_b32_e32 v86, 16, v58
	v_lshlrev_b32_e32 v92, 16, v116
	v_lshlrev_b32_e32 v232, 16, v124
	v_and_b32_e32 v81, 0xffff0000, v50
	v_and_b32_e32 v87, 0xffff0000, v58
	v_and_b32_e32 v93, 0xffff0000, v116
	v_and_b32_e32 v233, 0xffff0000, v124
	v_fmac_f32_e32 v80, 0xba800000, v78
	v_fmac_f32_e32 v86, 0xba800000, v84
	v_fmac_f32_e32 v92, 0xba800000, v90
	v_fmac_f32_e32 v232, 0xba800000, v230
	v_fmac_f32_e32 v81, 0xba800000, v78
	v_fmac_f32_e32 v87, 0xba800000, v84
	v_fmac_f32_e32 v93, 0xba800000, v90
	v_fmac_f32_e32 v233, 0xba800000, v230
	v_fmac_f32_e32 v79, v80, v80
	v_fmac_f32_e32 v85, v86, v86
	v_fmac_f32_e32 v91, v92, v92
	v_fmac_f32_e32 v231, v232, v232
	v_fmac_f32_e32 v79, v81, v81
	v_fmac_f32_e32 v85, v87, v87
	v_fmac_f32_e32 v91, v93, v93
	v_fmac_f32_e32 v231, v233, v233
	v_lshlrev_b32_e32 v80, 16, v51
	v_lshlrev_b32_e32 v86, 16, v59
	v_lshlrev_b32_e32 v92, 16, v117
	v_lshlrev_b32_e32 v232, 16, v125
	v_and_b32_e32 v81, 0xffff0000, v51
	v_and_b32_e32 v87, 0xffff0000, v59
	v_and_b32_e32 v93, 0xffff0000, v117
	v_and_b32_e32 v233, 0xffff0000, v125
	v_fmac_f32_e32 v80, 0xba800000, v78
	v_fmac_f32_e32 v86, 0xba800000, v84
	v_fmac_f32_e32 v92, 0xba800000, v90
	v_fmac_f32_e32 v232, 0xba800000, v230
	v_fmac_f32_e32 v81, 0xba800000, v78
	v_fmac_f32_e32 v87, 0xba800000, v84
	v_fmac_f32_e32 v93, 0xba800000, v90
	v_fmac_f32_e32 v233, 0xba800000, v230
	v_fmac_f32_e32 v79, v80, v80
	v_fmac_f32_e32 v85, v86, v86
; __device__ __forceinline__ void gmlp_unit(LAS unsigned char* lds, const Ctx& P, int l, int unit) {
;     ...
; #pragma unroll
;         for (int e = 0; e < 16; ++e) q += (x[e] - mean) * (x[e] - mean);
;         const float var = wave_sum(q) * (1.0f / 1024.0f);
;         if (lane == 0) { stats[2 * t] = mean; stats[2 * t + 1] = rsqrtf(var + 1e-5f); } }
	v_fmac_f32_e32 v91, v92, v92
	v_fmac_f32_e32 v231, v232, v232
	v_fmac_f32_e32 v79, v81, v81
	v_fmac_f32_e32 v85, v87, v87
	v_fmac_f32_e32 v91, v93, v93
	v_fmac_f32_e32 v231, v233, v233
	v_lshlrev_b32_e32 v80, 16, v52
	v_lshlrev_b32_e32 v86, 16, v60
	v_lshlrev_b32_e32 v92, 16, v118
	v_lshlrev_b32_e32 v232, 16, v126
	v_and_b32_e32 v81, 0xffff0000, v52
	v_and_b32_e32 v87, 0xffff0000, v60
	v_and_b32_e32 v93, 0xffff0000, v118
	v_and_b32_e32 v233, 0xffff0000, v126
	v_fmac_f32_e32 v80, 0xba800000, v78
	v_fmac_f32_e32 v86, 0xba800000, v84
	v_fmac_f32_e32 v92, 0xba800000, v90
	v_fmac_f32_e32 v232, 0xba800000, v230
	v_fmac_f32_e32 v81, 0xba800000, v78
	v_fmac_f32_e32 v87, 0xba800000, v84
	v_fmac_f32_e32 v93, 0xba800000, v90
	v_fmac_f32_e32 v233, 0xba800000, v230
	v_fmac_f32_e32 v79, v80, v80
	v_fmac_f32_e32 v85, v86, v86
	v_fmac_f32_e32 v91, v92, v92
	v_fmac_f32_e32 v231, v232, v232
	v_fmac_f32_e32 v79, v81, v81
	v_fmac_f32_e32 v85, v87, v87
	v_fmac_f32_e32 v91, v93, v93
	v_fmac_f32_e32 v231, v233, v233
	v_lshlrev_b32_e32 v80, 16, v53
	v_lshlrev_b32_e32 v86, 16, v61
	v_lshlrev_b32_e32 v92, 16, v119
	v_lshlrev_b32_e32 v232, 16, v127
	v_and_b32_e32 v81, 0xffff0000, v53
	v_and_b32_e32 v87, 0xffff0000, v61
	v_and_b32_e32 v93, 0xffff0000, v119
	v_and_b32_e32 v233, 0xffff0000, v127
	v_fmac_f32_e32 v80, 0xba800000, v78
	v_fmac_f32_e32 v86, 0xba800000, v84
	v_fmac_f32_e32 v92, 0xba800000, v90
	v_fmac_f32_e32 v232, 0xba800000, v230
	v_fmac_f32_e32 v81, 0xba800000, v78
	v_fmac_f32_e32 v87, 0xba800000, v84
	v_fmac_f32_e32 v93, 0xba800000, v90
	v_fmac_f32_e32 v233, 0xba800000, v230
	v_fmac_f32_e32 v79, v80, v80
	v_fmac_f32_e32 v85, v86, v86
	v_fmac_f32_e32 v91, v92, v92
	v_fmac_f32_e32 v231, v232, v232
	v_fmac_f32_e32 v79, v81, v81
	v_fmac_f32_e32 v85, v87, v87
	v_fmac_f32_e32 v91, v93, v93
	v_fmac_f32_e32 v231, v233, v233
	v_lshlrev_b32_e32 v80, 16, v54
	v_lshlrev_b32_e32 v86, 16, v62
	v_lshlrev_b32_e32 v92, 16, v120
	v_lshlrev_b32_e32 v232, 16, v128
	v_and_b32_e32 v81, 0xffff0000, v54
	v_and_b32_e32 v87, 0xffff0000, v62
	v_and_b32_e32 v93, 0xffff0000, v120
	v_and_b32_e32 v233, 0xffff0000, v128
	v_fmac_f32_e32 v80, 0xba800000, v78
	v_fmac_f32_e32 v86, 0xba800000, v84
	v_fmac_f32_e32 v92, 0xba800000, v90
	v_fmac_f32_e32 v232, 0xba800000, v230
	v_fmac_f32_e32 v81, 0xba800000, v78
	v_fmac_f32_e32 v87, 0xba800000, v84
	v_fmac_f32_e32 v93, 0xba800000, v90
	v_fmac_f32_e32 v233, 0xba800000, v230
	v_fmac_f32_e32 v79, v80, v80
	v_fmac_f32_e32 v85, v86, v86
	v_fmac_f32_e32 v91, v92, v92
	v_fmac_f32_e32 v231, v232, v232
	v_fmac_f32_e32 v79, v81, v81
	v_fmac_f32_e32 v85, v87, v87
	v_fmac_f32_e32 v91, v93, v93
	v_fmac_f32_e32 v231, v233, v233
	v_lshlrev_b32_e32 v80, 16, v55
	v_lshlrev_b32_e32 v86, 16, v63
	v_lshlrev_b32_e32 v92, 16, v121
	v_lshlrev_b32_e32 v232, 16, v129
	v_and_b32_e32 v81, 0xffff0000, v55
	v_and_b32_e32 v87, 0xffff0000, v63
	v_and_b32_e32 v93, 0xffff0000, v121
	v_and_b32_e32 v233, 0xffff0000, v129
	v_fmac_f32_e32 v80, 0xba800000, v78
	v_fmac_f32_e32 v86, 0xba800000, v84
	v_fmac_f32_e32 v92, 0xba800000, v90
	v_fmac_f32_e32 v232, 0xba800000, v230
	v_fmac_f32_e32 v81, 0xba800000, v78
	v_fmac_f32_e32 v87, 0xba800000, v84
	v_fmac_f32_e32 v93, 0xba800000, v90
	v_fmac_f32_e32 v233, 0xba800000, v230
	v_fmac_f32_e32 v79, v80, v80
	v_fmac_f32_e32 v85, v86, v86
	v_fmac_f32_e32 v91, v92, v92
	v_fmac_f32_e32 v231, v232, v232
	v_fmac_f32_e32 v79, v81, v81
	v_fmac_f32_e32 v85, v87, v87
	v_fmac_f32_e32 v91, v93, v93
	v_fmac_f32_e32 v231, v233, v233
	v_add_f32_dpp v79, v79, v79 row_ror:8 row_mask:0xf bank_mask:0xf
	v_add_f32_dpp v85, v85, v85 row_ror:8 row_mask:0xf bank_mask:0xf
	v_add_f32_dpp v91, v91, v91 row_ror:8 row_mask:0xf bank_mask:0xf
	v_add_f32_dpp v231, v231, v231 row_ror:8 row_mask:0xf bank_mask:0xf
	v_add_f32_dpp v79, v79, v79 row_ror:4 row_mask:0xf bank_mask:0xf
	v_add_f32_dpp v85, v85, v85 row_ror:4 row_mask:0xf bank_mask:0xf
	v_add_f32_dpp v91, v91, v91 row_ror:4 row_mask:0xf bank_mask:0xf
	v_add_f32_dpp v231, v231, v231 row_ror:4 row_mask:0xf bank_mask:0xf
	v_add_f32_dpp v79, v79, v79 row_ror:2 row_mask:0xf bank_mask:0xf
	v_add_f32_dpp v85, v85, v85 row_ror:2 row_mask:0xf bank_mask:0xf
	v_add_f32_dpp v91, v91, v91 row_ror:2 row_mask:0xf bank_mask:0xf
	v_add_f32_dpp v231, v231, v231 row_ror:2 row_mask:0xf bank_mask:0xf
	v_add_f32_dpp v79, v79, v79 row_ror:1 row_mask:0xf bank_mask:0xf
	v_add_f32_dpp v85, v85, v85 row_ror:1 row_mask:0xf bank_mask:0xf
	v_add_f32_dpp v91, v91, v91 row_ror:1 row_mask:0xf bank_mask:0xf
	v_add_f32_dpp v231, v231, v231 row_ror:1 row_mask:0xf bank_mask:0xf
	v_mov_b32_e32 v80, v79
	v_mov_b32_e32 v86, v85
	v_mov_b32_e32 v92, v91
	v_mov_b32_e32 v232, v231
	v_permlane16_swap_b32_e32 v79, v80
	v_permlane16_swap_b32_e32 v85, v86
	v_permlane16_swap_b32_e32 v91, v92
	v_permlane16_swap_b32_e32 v231, v232
	v_add_f32_e32 v79, v79, v80
	v_add_f32_e32 v85, v85, v86
	v_add_f32_e32 v91, v91, v92
	v_add_f32_e32 v231, v231, v232
	v_mov_b32_e32 v80, v79
	v_mov_b32_e32 v86, v85
	v_mov_b32_e32 v92, v91
	v_mov_b32_e32 v232, v231
	v_permlane32_swap_b32_e32 v79, v80
	v_permlane32_swap_b32_e32 v85, v86
	v_permlane32_swap_b32_e32 v91, v92
	v_permlane32_swap_b32_e32 v231, v232
	v_add_f32_e32 v79, v79, v80
	v_add_f32_e32 v85, v85, v86
	v_add_f32_e32 v91, v91, v92
	v_add_f32_e32 v231, v231, v232
	v_fmamk_f32 v79, v79, 0x3a800000, v236
	v_mul_f32_e32 v80, 0x4b800000, v79
	v_cmp_gt_f32_e32 vcc, s81, v79
	v_mul_f32_e32 v78, 0x3a800000, v78
	s_nop 0
	v_cndmask_b32_e32 v79, v79, v80, vcc
	v_rsq_f32_e32 v79, v79
	s_nop 0
	v_mul_f32_e32 v80, 0x45800000, v79
	v_cndmask_b32_e32 v79, v79, v80, vcc
	v_fmamk_f32 v85, v85, 0x3a800000, v236
	v_mul_f32_e32 v86, 0x4b800000, v85
	v_cmp_gt_f32_e32 vcc, s81, v85
	v_mul_f32_e32 v84, 0x3a800000, v84
	s_nop 0
	v_cndmask_b32_e32 v85, v85, v86, vcc
	v_rsq_f32_e32 v85, v85
	s_nop 0
	v_mul_f32_e32 v86, 0x45800000, v85
	v_cndmask_b32_e32 v85, v85, v86, vcc
	v_fmamk_f32 v91, v91, 0x3a800000, v236
	v_mul_f32_e32 v92, 0x4b800000, v91
	v_cmp_gt_f32_e32 vcc, s81, v91
	v_mul_f32_e32 v90, 0x3a800000, v90
	s_nop 0
	v_cndmask_b32_e32 v91, v91, v92, vcc
	v_rsq_f32_e32 v91, v91
	s_nop 0
	v_mul_f32_e32 v92, 0x45800000, v91
	v_cndmask_b32_e32 v91, v91, v92, vcc
	v_fmamk_f32 v231, v231, 0x3a800000, v236
	v_mul_f32_e32 v232, 0x4b800000, v231
	v_cmp_gt_f32_e32 vcc, s81, v231
	v_mul_f32_e32 v230, 0x3a800000, v230
	s_nop 0
	v_cndmask_b32_e32 v231, v231, v232, vcc
	v_rsq_f32_e32 v231, v231
	s_nop 0
	v_mul_f32_e32 v232, 0x45800000, v231
	v_cndmask_b32_e32 v231, v231, v232, vcc
	s_and_saveexec_b64 s[14:15], s[6:7]
	ds_write_b64 v15, v[78:79] offset:32
	ds_write_b64 v15, v[84:85] offset:40
	ds_write_b64 v15, v[90:91] offset:48
	ds_write_b64 v15, v[230:231] offset:56
	s_or_b64 exec, exec, s[14:15]
	s_waitcnt vmcnt(8)
; __device__ __forceinline__ float bflo(unsigned w) { return __uint_as_float(w << 16); }
; __device__ __forceinline__ float bfhi(unsigned w) { return __uint_as_float(w & 0xffff0000u); }
; __device__ __forceinline__ void gmlp_unit(LAS unsigned char* lds, const Ctx& P, int l, int unit) {
;     ...
;         const float x[16] = {bflo(a.x), bfhi(a.x), bflo(a.y), bfhi(a.y), bflo(a.z), bfhi(a.z), bflo(a.w), bfhi(a.w), bflo(bb.x), bfhi(bb.x), bflo(bb.y), bfhi(bb.y), bflo(bb.z), bfhi(bb.z), bflo(bb.w), bfhi(bb.w)};
;         float s = 0.f;
; #pragma unroll
;         for (int e = 0; e < 16; ++e) s += x[e];
;         const float mean = wave_sum(s) * (1.0f / 1024.0f); float q = 0.f;
	v_lshlrev_b32_e32 v80, 16, v130
	v_lshlrev_b32_e32 v86, 16, v138
	v_lshlrev_b32_e32 v92, 16, v146
	v_lshlrev_b32_e32 v232, 16, v154
	v_and_b32_e32 v81, 0xffff0000, v130
	v_and_b32_e32 v87, 0xffff0000, v138
	v_and_b32_e32 v93, 0xffff0000, v146
	v_and_b32_e32 v233, 0xffff0000, v154
	v_add_f32_e32 v78, 0, v80
	v_add_f32_e32 v84, 0, v86
	v_add_f32_e32 v90, 0, v92
	v_add_f32_e32 v230, 0, v232
	v_add_f32_e32 v78, v78, v81
	v_add_f32_e32 v84, v84, v87
	v_add_f32_e32 v90, v90, v93
	v_add_f32_e32 v230, v230, v233
	v_lshlrev_b32_e32 v80, 16, v131
	v_lshlrev_b32_e32 v86, 16, v139
	v_lshlrev_b32_e32 v92, 16, v147
	v_lshlrev_b32_e32 v232, 16, v155
	v_and_b32_e32 v81, 0xffff0000, v131
	v_and_b32_e32 v87, 0xffff0000, v139
	v_and_b32_e32 v93, 0xffff0000, v147
	v_and_b32_e32 v233, 0xffff0000, v155
	v_add_f32_e32 v78, v78, v80
	v_add_f32_e32 v84, v84, v86
	v_add_f32_e32 v90, v90, v92
	v_add_f32_e32 v230, v230, v232
	v_add_f32_e32 v78, v78, v81
	v_add_f32_e32 v84, v84, v87
	v_add_f32_e32 v90, v90, v93
	v_add_f32_e32 v230, v230, v233
	v_lshlrev_b32_e32 v80, 16, v132
	v_lshlrev_b32_e32 v86, 16, v140
	v_lshlrev_b32_e32 v92, 16, v148
	v_lshlrev_b32_e32 v232, 16, v156
	v_and_b32_e32 v81, 0xffff0000, v132
	v_and_b32_e32 v87, 0xffff0000, v140
	v_and_b32_e32 v93, 0xffff0000, v148
	v_and_b32_e32 v233, 0xffff0000, v156
	v_add_f32_e32 v78, v78, v80
	v_add_f32_e32 v84, v84, v86
	v_add_f32_e32 v90, v90, v92
	v_add_f32_e32 v230, v230, v232
	v_add_f32_e32 v78, v78, v81
	v_add_f32_e32 v84, v84, v87
	v_add_f32_e32 v90, v90, v93
	v_add_f32_e32 v230, v230, v233
	v_lshlrev_b32_e32 v80, 16, v133
	v_lshlrev_b32_e32 v86, 16, v141
	v_lshlrev_b32_e32 v92, 16, v149
	v_lshlrev_b32_e32 v232, 16, v157
	v_and_b32_e32 v81, 0xffff0000, v133
	v_and_b32_e32 v87, 0xffff0000, v141
	v_and_b32_e32 v93, 0xffff0000, v149
	v_and_b32_e32 v233, 0xffff0000, v157
	v_add_f32_e32 v78, v78, v80
	v_add_f32_e32 v84, v84, v86
	v_add_f32_e32 v90, v90, v92
	v_add_f32_e32 v230, v230, v232
	v_add_f32_e32 v78, v78, v81
	v_add_f32_e32 v84, v84, v87
	v_add_f32_e32 v90, v90, v93
	v_add_f32_e32 v230, v230, v233
	v_lshlrev_b32_e32 v80, 16, v134
	v_lshlrev_b32_e32 v86, 16, v142
	v_lshlrev_b32_e32 v92, 16, v150
	v_lshlrev_b32_e32 v232, 16, v158
	v_and_b32_e32 v81, 0xffff0000, v134
	v_and_b32_e32 v87, 0xffff0000, v142
	v_and_b32_e32 v93, 0xffff0000, v150
	v_and_b32_e32 v233, 0xffff0000, v158
	v_add_f32_e32 v78, v78, v80
	v_add_f32_e32 v84, v84, v86
	v_add_f32_e32 v90, v90, v92
	v_add_f32_e32 v230, v230, v232
	v_add_f32_e32 v78, v78, v81
	v_add_f32_e32 v84, v84, v87
	v_add_f32_e32 v90, v90, v93
	v_add_f32_e32 v230, v230, v233
	v_lshlrev_b32_e32 v80, 16, v135
	v_lshlrev_b32_e32 v86, 16, v143
	v_lshlrev_b32_e32 v92, 16, v151
	v_lshlrev_b32_e32 v232, 16, v159
	v_and_b32_e32 v81, 0xffff0000, v135
	v_and_b32_e32 v87, 0xffff0000, v143
	v_and_b32_e32 v93, 0xffff0000, v151
	v_and_b32_e32 v233, 0xffff0000, v159
	v_add_f32_e32 v78, v78, v80
	v_add_f32_e32 v84, v84, v86
	v_add_f32_e32 v90, v90, v92
	v_add_f32_e32 v230, v230, v232
	v_add_f32_e32 v78, v78, v81
	v_add_f32_e32 v84, v84, v87
	v_add_f32_e32 v90, v90, v93
	v_add_f32_e32 v230, v230, v233
	v_lshlrev_b32_e32 v80, 16, v136
	v_lshlrev_b32_e32 v86, 16, v144
	v_lshlrev_b32_e32 v92, 16, v152
	v_lshlrev_b32_e32 v232, 16, v160
	v_and_b32_e32 v81, 0xffff0000, v136
	v_and_b32_e32 v87, 0xffff0000, v144
	v_and_b32_e32 v93, 0xffff0000, v152
	v_and_b32_e32 v233, 0xffff0000, v160
	v_add_f32_e32 v78, v78, v80
	v_add_f32_e32 v84, v84, v86
	v_add_f32_e32 v90, v90, v92
	v_add_f32_e32 v230, v230, v232
	v_add_f32_e32 v78, v78, v81
	v_add_f32_e32 v84, v84, v87
	v_add_f32_e32 v90, v90, v93
	v_add_f32_e32 v230, v230, v233
	v_lshlrev_b32_e32 v80, 16, v137
	v_lshlrev_b32_e32 v86, 16, v145
	v_lshlrev_b32_e32 v92, 16, v153
	v_lshlrev_b32_e32 v232, 16, v161
	v_and_b32_e32 v81, 0xffff0000, v137
	v_and_b32_e32 v87, 0xffff0000, v145
	v_and_b32_e32 v93, 0xffff0000, v153
	v_and_b32_e32 v233, 0xffff0000, v161
	v_add_f32_e32 v78, v78, v80
	v_add_f32_e32 v84, v84, v86
	v_add_f32_e32 v90, v90, v92
	v_add_f32_e32 v230, v230, v232
	v_add_f32_e32 v78, v78, v81
	v_add_f32_e32 v84, v84, v87
	v_add_f32_e32 v90, v90, v93
	v_add_f32_e32 v230, v230, v233
	v_add_f32_dpp v78, v78, v78 row_ror:8 row_mask:0xf bank_mask:0xf
	v_add_f32_dpp v84, v84, v84 row_ror:8 row_mask:0xf bank_mask:0xf
	v_add_f32_dpp v90, v90, v90 row_ror:8 row_mask:0xf bank_mask:0xf
	v_add_f32_dpp v230, v230, v230 row_ror:8 row_mask:0xf bank_mask:0xf
	v_add_f32_dpp v78, v78, v78 row_ror:4 row_mask:0xf bank_mask:0xf
	v_add_f32_dpp v84, v84, v84 row_ror:4 row_mask:0xf bank_mask:0xf
	v_add_f32_dpp v90, v90, v90 row_ror:4 row_mask:0xf bank_mask:0xf
	v_add_f32_dpp v230, v230, v230 row_ror:4 row_mask:0xf bank_mask:0xf
	v_add_f32_dpp v78, v78, v78 row_ror:2 row_mask:0xf bank_mask:0xf
	v_add_f32_dpp v84, v84, v84 row_ror:2 row_mask:0xf bank_mask:0xf
	v_add_f32_dpp v90, v90, v90 row_ror:2 row_mask:0xf bank_mask:0xf
	v_add_f32_dpp v230, v230, v230 row_ror:2 row_mask:0xf bank_mask:0xf
	v_add_f32_dpp v78, v78, v78 row_ror:1 row_mask:0xf bank_mask:0xf
	v_add_f32_dpp v84, v84, v84 row_ror:1 row_mask:0xf bank_mask:0xf
	v_add_f32_dpp v90, v90, v90 row_ror:1 row_mask:0xf bank_mask:0xf
	v_add_f32_dpp v230, v230, v230 row_ror:1 row_mask:0xf bank_mask:0xf
	v_mov_b32_e32 v80, v78
	v_mov_b32_e32 v86, v84
	v_mov_b32_e32 v92, v90
	v_mov_b32_e32 v232, v230
	v_permlane16_swap_b32_e32 v78, v80
	v_permlane16_swap_b32_e32 v84, v86
	v_permlane16_swap_b32_e32 v90, v92
	v_permlane16_swap_b32_e32 v230, v232
	v_add_f32_e32 v78, v78, v80
	v_add_f32_e32 v84, v84, v86
	v_add_f32_e32 v90, v90, v92
	v_add_f32_e32 v230, v230, v232
	v_mov_b32_e32 v80, v78
	v_mov_b32_e32 v86, v84
; __device__ __forceinline__ void gmlp_unit(LAS unsigned char* lds, const Ctx& P, int l, int unit) {
;     ...
;         const float mean = wave_sum(s) * (1.0f / 1024.0f); float q = 0.f;
; #pragma unroll
;         for (int e = 0; e < 16; ++e) q += (x[e] - mean) * (x[e] - mean);
;         const float var = wave_sum(q) * (1.0f / 1024.0f);
	v_mov_b32_e32 v92, v90
	v_mov_b32_e32 v232, v230
	v_permlane32_swap_b32_e32 v78, v80
	v_permlane32_swap_b32_e32 v84, v86
	v_permlane32_swap_b32_e32 v90, v92
	v_permlane32_swap_b32_e32 v230, v232
	v_add_f32_e32 v78, v78, v80
	v_add_f32_e32 v84, v84, v86
	v_add_f32_e32 v90, v90, v92
	v_add_f32_e32 v230, v230, v232
	v_lshlrev_b32_e32 v80, 16, v130
	v_lshlrev_b32_e32 v86, 16, v138
	v_lshlrev_b32_e32 v92, 16, v146
	v_lshlrev_b32_e32 v232, 16, v154
	v_and_b32_e32 v81, 0xffff0000, v130
	v_and_b32_e32 v87, 0xffff0000, v138
	v_and_b32_e32 v93, 0xffff0000, v146
	v_and_b32_e32 v233, 0xffff0000, v154
	v_fmac_f32_e32 v80, 0xba800000, v78
	v_fmac_f32_e32 v86, 0xba800000, v84
	v_fmac_f32_e32 v92, 0xba800000, v90
	v_fmac_f32_e32 v232, 0xba800000, v230
	v_fmac_f32_e32 v81, 0xba800000, v78
	v_fmac_f32_e32 v87, 0xba800000, v84
	v_fmac_f32_e32 v93, 0xba800000, v90
	v_fmac_f32_e32 v233, 0xba800000, v230
	v_mul_f32_e32 v79, v81, v81
	v_mul_f32_e32 v85, v87, v87
	v_mul_f32_e32 v91, v93, v93
	v_mul_f32_e32 v231, v233, v233
	v_fmac_f32_e32 v79, v80, v80
	v_fmac_f32_e32 v85, v86, v86
	v_fmac_f32_e32 v91, v92, v92
	v_fmac_f32_e32 v231, v232, v232
	v_lshlrev_b32_e32 v80, 16, v131
	v_lshlrev_b32_e32 v86, 16, v139
	v_lshlrev_b32_e32 v92, 16, v147
	v_lshlrev_b32_e32 v232, 16, v155
	v_and_b32_e32 v81, 0xffff0000, v131
	v_and_b32_e32 v87, 0xffff0000, v139
	v_and_b32_e32 v93, 0xffff0000, v147
	v_and_b32_e32 v233, 0xffff0000, v155
	v_fmac_f32_e32 v80, 0xba800000, v78
	v_fmac_f32_e32 v86, 0xba800000, v84
	v_fmac_f32_e32 v92, 0xba800000, v90
	v_fmac_f32_e32 v232, 0xba800000, v230
	v_fmac_f32_e32 v81, 0xba800000, v78
	v_fmac_f32_e32 v87, 0xba800000, v84
	v_fmac_f32_e32 v93, 0xba800000, v90
	v_fmac_f32_e32 v233, 0xba800000, v230
	v_fmac_f32_e32 v79, v80, v80
	v_fmac_f32_e32 v85, v86, v86
	v_fmac_f32_e32 v91, v92, v92
	v_fmac_f32_e32 v231, v232, v232
	v_fmac_f32_e32 v79, v81, v81
	v_fmac_f32_e32 v85, v87, v87
	v_fmac_f32_e32 v91, v93, v93
	v_fmac_f32_e32 v231, v233, v233
	v_lshlrev_b32_e32 v80, 16, v132
	v_lshlrev_b32_e32 v86, 16, v140
	v_lshlrev_b32_e32 v92, 16, v148
	v_lshlrev_b32_e32 v232, 16, v156
	v_and_b32_e32 v81, 0xffff0000, v132
	v_and_b32_e32 v87, 0xffff0000, v140
	v_and_b32_e32 v93, 0xffff0000, v148
	v_and_b32_e32 v233, 0xffff0000, v156
	v_fmac_f32_e32 v80, 0xba800000, v78
	v_fmac_f32_e32 v86, 0xba800000, v84
	v_fmac_f32_e32 v92, 0xba800000, v90
	v_fmac_f32_e32 v232, 0xba800000, v230
	v_fmac_f32_e32 v81, 0xba800000, v78
	v_fmac_f32_e32 v87, 0xba800000, v84
	v_fmac_f32_e32 v93, 0xba800000, v90
	v_fmac_f32_e32 v233, 0xba800000, v230
	v_fmac_f32_e32 v79, v80, v80
	v_fmac_f32_e32 v85, v86, v86
	v_fmac_f32_e32 v91, v92, v92
	v_fmac_f32_e32 v231, v232, v232
	v_fmac_f32_e32 v79, v81, v81
	v_fmac_f32_e32 v85, v87, v87
	v_fmac_f32_e32 v91, v93, v93
	v_fmac_f32_e32 v231, v233, v233
	v_lshlrev_b32_e32 v80, 16, v133
	v_lshlrev_b32_e32 v86, 16, v141
	v_lshlrev_b32_e32 v92, 16, v149
	v_lshlrev_b32_e32 v232, 16, v157
	v_and_b32_e32 v81, 0xffff0000, v133
	v_and_b32_e32 v87, 0xffff0000, v141
	v_and_b32_e32 v93, 0xffff0000, v149
	v_and_b32_e32 v233, 0xffff0000, v157
	v_fmac_f32_e32 v80, 0xba800000, v78
	v_fmac_f32_e32 v86, 0xba800000, v84
	v_fmac_f32_e32 v92, 0xba800000, v90
	v_fmac_f32_e32 v232, 0xba800000, v230
	v_fmac_f32_e32 v81, 0xba800000, v78
	v_fmac_f32_e32 v87, 0xba800000, v84
	v_fmac_f32_e32 v93, 0xba800000, v90
	v_fmac_f32_e32 v233, 0xba800000, v230
	v_fmac_f32_e32 v79, v80, v80
	v_fmac_f32_e32 v85, v86, v86
	v_fmac_f32_e32 v91, v92, v92
	v_fmac_f32_e32 v231, v232, v232
	v_fmac_f32_e32 v79, v81, v81
	v_fmac_f32_e32 v85, v87, v87
	v_fmac_f32_e32 v91, v93, v93
	v_fmac_f32_e32 v231, v233, v233
	v_lshlrev_b32_e32 v80, 16, v134
	v_lshlrev_b32_e32 v86, 16, v142
	v_lshlrev_b32_e32 v92, 16, v150
	v_lshlrev_b32_e32 v232, 16, v158
	v_and_b32_e32 v81, 0xffff0000, v134
	v_and_b32_e32 v87, 0xffff0000, v142
	v_and_b32_e32 v93, 0xffff0000, v150
	v_and_b32_e32 v233, 0xffff0000, v158
	v_fmac_f32_e32 v80, 0xba800000, v78
	v_fmac_f32_e32 v86, 0xba800000, v84
	v_fmac_f32_e32 v92, 0xba800000, v90
	v_fmac_f32_e32 v232, 0xba800000, v230
	v_fmac_f32_e32 v81, 0xba800000, v78
	v_fmac_f32_e32 v87, 0xba800000, v84
	v_fmac_f32_e32 v93, 0xba800000, v90
	v_fmac_f32_e32 v233, 0xba800000, v230
	v_fmac_f32_e32 v79, v80, v80
	v_fmac_f32_e32 v85, v86, v86
	v_fmac_f32_e32 v91, v92, v92
	v_fmac_f32_e32 v231, v232, v232
	v_fmac_f32_e32 v79, v81, v81
	v_fmac_f32_e32 v85, v87, v87
	v_fmac_f32_e32 v91, v93, v93
	v_fmac_f32_e32 v231, v233, v233
	v_lshlrev_b32_e32 v80, 16, v135
	v_lshlrev_b32_e32 v86, 16, v143
	v_lshlrev_b32_e32 v92, 16, v151
	v_lshlrev_b32_e32 v232, 16, v159
	v_and_b32_e32 v81, 0xffff0000, v135
	v_and_b32_e32 v87, 0xffff0000, v143
	v_and_b32_e32 v93, 0xffff0000, v151
	v_and_b32_e32 v233, 0xffff0000, v159
	v_fmac_f32_e32 v80, 0xba800000, v78
	v_fmac_f32_e32 v86, 0xba800000, v84
	v_fmac_f32_e32 v92, 0xba800000, v90
	v_fmac_f32_e32 v232, 0xba800000, v230
	v_fmac_f32_e32 v81, 0xba800000, v78
	v_fmac_f32_e32 v87, 0xba800000, v84
	v_fmac_f32_e32 v93, 0xba800000, v90
	v_fmac_f32_e32 v233, 0xba800000, v230
	v_fmac_f32_e32 v79, v80, v80
	v_fmac_f32_e32 v85, v86, v86
	v_fmac_f32_e32 v91, v92, v92
	v_fmac_f32_e32 v231, v232, v232
	v_fmac_f32_e32 v79, v81, v81
	v_fmac_f32_e32 v85, v87, v87
	v_fmac_f32_e32 v91, v93, v93
	v_fmac_f32_e32 v231, v233, v233
	v_lshlrev_b32_e32 v80, 16, v136
	v_lshlrev_b32_e32 v86, 16, v144
	v_lshlrev_b32_e32 v92, 16, v152
	v_lshlrev_b32_e32 v232, 16, v160
	v_and_b32_e32 v81, 0xffff0000, v136
	v_and_b32_e32 v87, 0xffff0000, v144
	v_and_b32_e32 v93, 0xffff0000, v152
	v_and_b32_e32 v233, 0xffff0000, v160
	v_fmac_f32_e32 v80, 0xba800000, v78
	v_fmac_f32_e32 v86, 0xba800000, v84
; __device__ __forceinline__ float bflo(unsigned w) { return __uint_as_float(w << 16); }
; __device__ __forceinline__ float bfhi(unsigned w) { return __uint_as_float(w & 0xffff0000u); }
; __device__ __forceinline__ void gmlp_unit(LAS unsigned char* lds, const Ctx& P, int l, int unit) {
;     ...
;     for (int r = 0; r < 16; ++r) { const int t = wid * 16 + r; const bf16_t* row = H + (tok0 + t) * LDH + C_V;
;         const u32x4 a = *(const u32x4*)(row + lane * 8), bb = *(const u32x4*)(row + 512 + lane * 8);
;         const float x[16] = {bflo(a.x), bfhi(a.x), bflo(a.y), bfhi(a.y), bflo(a.z), bfhi(a.z), bflo(a.w), bfhi(a.w), bflo(bb.x), bfhi(bb.x), bflo(bb.y), bfhi(bb.y), bflo(bb.z), bfhi(bb.z), bflo(bb.w), bfhi(bb.w)};
;         float s = 0.f;
; #pragma unroll
;         for (int e = 0; e < 16; ++e) s += x[e];
;         const float mean = wave_sum(s) * (1.0f / 1024.0f); float q = 0.f;
; #pragma unroll
;         for (int e = 0; e < 16; ++e) q += (x[e] - mean) * (x[e] - mean);
;         const float var = wave_sum(q) * (1.0f / 1024.0f);
;         if (lane == 0) { stats[2 * t] = mean; stats[2 * t + 1] = rsqrtf(var + 1e-5f); } }
	v_fmac_f32_e32 v92, 0xba800000, v90
	v_fmac_f32_e32 v232, 0xba800000, v230
	v_fmac_f32_e32 v81, 0xba800000, v78
	v_fmac_f32_e32 v87, 0xba800000, v84
	v_fmac_f32_e32 v93, 0xba800000, v90
	v_fmac_f32_e32 v233, 0xba800000, v230
	v_fmac_f32_e32 v79, v80, v80
	v_fmac_f32_e32 v85, v86, v86
	v_fmac_f32_e32 v91, v92, v92
	v_fmac_f32_e32 v231, v232, v232
	v_fmac_f32_e32 v79, v81, v81
	v_fmac_f32_e32 v85, v87, v87
	v_fmac_f32_e32 v91, v93, v93
	v_fmac_f32_e32 v231, v233, v233
	v_lshlrev_b32_e32 v80, 16, v137
	v_lshlrev_b32_e32 v86, 16, v145
	v_lshlrev_b32_e32 v92, 16, v153
	v_lshlrev_b32_e32 v232, 16, v161
	v_and_b32_e32 v81, 0xffff0000, v137
	v_and_b32_e32 v87, 0xffff0000, v145
	v_and_b32_e32 v93, 0xffff0000, v153
	v_and_b32_e32 v233, 0xffff0000, v161
	v_fmac_f32_e32 v80, 0xba800000, v78
	v_fmac_f32_e32 v86, 0xba800000, v84
	v_fmac_f32_e32 v92, 0xba800000, v90
	v_fmac_f32_e32 v232, 0xba800000, v230
	v_fmac_f32_e32 v81, 0xba800000, v78
	v_fmac_f32_e32 v87, 0xba800000, v84
	v_fmac_f32_e32 v93, 0xba800000, v90
	v_fmac_f32_e32 v233, 0xba800000, v230
	v_fmac_f32_e32 v79, v80, v80
	v_fmac_f32_e32 v85, v86, v86
	v_fmac_f32_e32 v91, v92, v92
	v_fmac_f32_e32 v231, v232, v232
	v_fmac_f32_e32 v79, v81, v81
	v_fmac_f32_e32 v85, v87, v87
	v_fmac_f32_e32 v91, v93, v93
	v_fmac_f32_e32 v231, v233, v233
	v_add_f32_dpp v79, v79, v79 row_ror:8 row_mask:0xf bank_mask:0xf
	v_add_f32_dpp v85, v85, v85 row_ror:8 row_mask:0xf bank_mask:0xf
	v_add_f32_dpp v91, v91, v91 row_ror:8 row_mask:0xf bank_mask:0xf
	v_add_f32_dpp v231, v231, v231 row_ror:8 row_mask:0xf bank_mask:0xf
	v_add_f32_dpp v79, v79, v79 row_ror:4 row_mask:0xf bank_mask:0xf
	v_add_f32_dpp v85, v85, v85 row_ror:4 row_mask:0xf bank_mask:0xf
	v_add_f32_dpp v91, v91, v91 row_ror:4 row_mask:0xf bank_mask:0xf
	v_add_f32_dpp v231, v231, v231 row_ror:4 row_mask:0xf bank_mask:0xf
	v_add_f32_dpp v79, v79, v79 row_ror:2 row_mask:0xf bank_mask:0xf
	v_add_f32_dpp v85, v85, v85 row_ror:2 row_mask:0xf bank_mask:0xf
	v_add_f32_dpp v91, v91, v91 row_ror:2 row_mask:0xf bank_mask:0xf
	v_add_f32_dpp v231, v231, v231 row_ror:2 row_mask:0xf bank_mask:0xf
	v_add_f32_dpp v79, v79, v79 row_ror:1 row_mask:0xf bank_mask:0xf
	v_add_f32_dpp v85, v85, v85 row_ror:1 row_mask:0xf bank_mask:0xf
	v_add_f32_dpp v91, v91, v91 row_ror:1 row_mask:0xf bank_mask:0xf
	v_add_f32_dpp v231, v231, v231 row_ror:1 row_mask:0xf bank_mask:0xf
	v_mov_b32_e32 v80, v79
	v_mov_b32_e32 v86, v85
	v_mov_b32_e32 v92, v91
	v_mov_b32_e32 v232, v231
	v_permlane16_swap_b32_e32 v79, v80
	v_permlane16_swap_b32_e32 v85, v86
	v_permlane16_swap_b32_e32 v91, v92
	v_permlane16_swap_b32_e32 v231, v232
	v_add_f32_e32 v79, v79, v80
	v_add_f32_e32 v85, v85, v86
	v_add_f32_e32 v91, v91, v92
	v_add_f32_e32 v231, v231, v232
	v_mov_b32_e32 v80, v79
	v_mov_b32_e32 v86, v85
	v_mov_b32_e32 v92, v91
	v_mov_b32_e32 v232, v231
	v_permlane32_swap_b32_e32 v79, v80
	v_permlane32_swap_b32_e32 v85, v86
	v_permlane32_swap_b32_e32 v91, v92
	v_permlane32_swap_b32_e32 v231, v232
	v_add_f32_e32 v79, v79, v80
	v_add_f32_e32 v85, v85, v86
	v_add_f32_e32 v91, v91, v92
	v_add_f32_e32 v231, v231, v232
	v_fmamk_f32 v79, v79, 0x3a800000, v236
	v_mul_f32_e32 v80, 0x4b800000, v79
	v_cmp_gt_f32_e32 vcc, s81, v79
	v_mul_f32_e32 v78, 0x3a800000, v78
	s_nop 0
	v_cndmask_b32_e32 v79, v79, v80, vcc
	v_rsq_f32_e32 v79, v79
	s_nop 0
	v_mul_f32_e32 v80, 0x45800000, v79
	v_cndmask_b32_e32 v79, v79, v80, vcc
	v_fmamk_f32 v85, v85, 0x3a800000, v236
	v_mul_f32_e32 v86, 0x4b800000, v85
	v_cmp_gt_f32_e32 vcc, s81, v85
	v_mul_f32_e32 v84, 0x3a800000, v84
	s_nop 0
	v_cndmask_b32_e32 v85, v85, v86, vcc
	v_rsq_f32_e32 v85, v85
	s_nop 0
	v_mul_f32_e32 v86, 0x45800000, v85
	v_cndmask_b32_e32 v85, v85, v86, vcc
	v_fmamk_f32 v91, v91, 0x3a800000, v236
	v_mul_f32_e32 v92, 0x4b800000, v91
	v_cmp_gt_f32_e32 vcc, s81, v91
	v_mul_f32_e32 v90, 0x3a800000, v90
	s_nop 0
	v_cndmask_b32_e32 v91, v91, v92, vcc
	v_rsq_f32_e32 v91, v91
	s_nop 0
	v_mul_f32_e32 v92, 0x45800000, v91
	v_cndmask_b32_e32 v91, v91, v92, vcc
	v_fmamk_f32 v231, v231, 0x3a800000, v236
	v_mul_f32_e32 v232, 0x4b800000, v231
	v_cmp_gt_f32_e32 vcc, s81, v231
	v_mul_f32_e32 v230, 0x3a800000, v230
	s_nop 0
	v_cndmask_b32_e32 v231, v231, v232, vcc
	v_rsq_f32_e32 v231, v231
	s_nop 0
	v_mul_f32_e32 v232, 0x45800000, v231
	v_cndmask_b32_e32 v231, v231, v232, vcc
	s_and_saveexec_b64 s[14:15], s[6:7]
	ds_write_b64 v15, v[78:79] offset:64
	ds_write_b64 v15, v[84:85] offset:72
	ds_write_b64 v15, v[90:91] offset:80
	ds_write_b64 v15, v[230:231] offset:88
	s_or_b64 exec, exec, s[14:15]
	s_waitcnt vmcnt(0)
; __device__ __forceinline__ float bflo(unsigned w) { return __uint_as_float(w << 16); }
; __device__ __forceinline__ float bfhi(unsigned w) { return __uint_as_float(w & 0xffff0000u); }
; __device__ __forceinline__ void gmlp_unit(LAS unsigned char* lds, const Ctx& P, int l, int unit) {
;     ...
;     for (int r = 0; r < 16; ++r) { const int t = wid * 16 + r; const bf16_t* row = H + (tok0 + t) * LDH + C_V;
;         const u32x4 a = *(const u32x4*)(row + lane * 8), bb = *(const u32x4*)(row + 512 + lane * 8);
;         const float x[16] = {bflo(a.x), bfhi(a.x), bflo(a.y), bfhi(a.y), bflo(a.z), bfhi(a.z), bflo(a.w), bfhi(a.w), bflo(bb.x), bfhi(bb.x), bflo(bb.y), bfhi(bb.y), bflo(bb.z), bfhi(bb.z), bflo(bb.w), bfhi(bb.w)};
;         float s = 0.f;
; #pragma unroll
;         for (int e = 0; e < 16; ++e) s += x[e];
;         const float mean = wave_sum(s) * (1.0f / 1024.0f); float q = 0.f;
; #pragma unroll
;         for (int e = 0; e < 16; ++e) q += (x[e] - mean) * (x[e] - mean);
;         const float var = wave_sum(q) * (1.0f / 1024.0f);
;         if (lane == 0) { stats[2 * t] = mean; stats[2 * t + 1] = rsqrtf(var + 1e-5f); } }
	v_lshlrev_b32_e32 v80, 16, v170
	v_lshlrev_b32_e32 v86, 16, v178
	v_lshlrev_b32_e32 v92, 16, v186
	v_lshlrev_b32_e32 v232, 16, v194
	v_and_b32_e32 v81, 0xffff0000, v170
	v_and_b32_e32 v87, 0xffff0000, v178
	v_and_b32_e32 v93, 0xffff0000, v186
	v_and_b32_e32 v233, 0xffff0000, v194
	v_add_f32_e32 v78, 0, v80
	v_add_f32_e32 v84, 0, v86
	v_add_f32_e32 v90, 0, v92
	v_add_f32_e32 v230, 0, v232
	v_add_f32_e32 v78, v78, v81
	v_add_f32_e32 v84, v84, v87
	v_add_f32_e32 v90, v90, v93
	v_add_f32_e32 v230, v230, v233
	v_lshlrev_b32_e32 v80, 16, v171
	v_lshlrev_b32_e32 v86, 16, v179
	v_lshlrev_b32_e32 v92, 16, v187
	v_lshlrev_b32_e32 v232, 16, v195
	v_and_b32_e32 v81, 0xffff0000, v171
	v_and_b32_e32 v87, 0xffff0000, v179
	v_and_b32_e32 v93, 0xffff0000, v187
	v_and_b32_e32 v233, 0xffff0000, v195
	v_add_f32_e32 v78, v78, v80
	v_add_f32_e32 v84, v84, v86
	v_add_f32_e32 v90, v90, v92
	v_add_f32_e32 v230, v230, v232
	v_add_f32_e32 v78, v78, v81
	v_add_f32_e32 v84, v84, v87
	v_add_f32_e32 v90, v90, v93
	v_add_f32_e32 v230, v230, v233
	v_lshlrev_b32_e32 v80, 16, v172
	v_lshlrev_b32_e32 v86, 16, v180
	v_lshlrev_b32_e32 v92, 16, v188
	v_lshlrev_b32_e32 v232, 16, v196
	v_and_b32_e32 v81, 0xffff0000, v172
	v_and_b32_e32 v87, 0xffff0000, v180
	v_and_b32_e32 v93, 0xffff0000, v188
	v_and_b32_e32 v233, 0xffff0000, v196
	v_add_f32_e32 v78, v78, v80
	v_add_f32_e32 v84, v84, v86
	v_add_f32_e32 v90, v90, v92
	v_add_f32_e32 v230, v230, v232
	v_add_f32_e32 v78, v78, v81
	v_add_f32_e32 v84, v84, v87
	v_add_f32_e32 v90, v90, v93
	v_add_f32_e32 v230, v230, v233
	v_lshlrev_b32_e32 v80, 16, v173
	v_lshlrev_b32_e32 v86, 16, v181
	v_lshlrev_b32_e32 v92, 16, v189
	v_lshlrev_b32_e32 v232, 16, v197
	v_and_b32_e32 v81, 0xffff0000, v173
	v_and_b32_e32 v87, 0xffff0000, v181
	v_and_b32_e32 v93, 0xffff0000, v189
	v_and_b32_e32 v233, 0xffff0000, v197
	v_add_f32_e32 v78, v78, v80
	v_add_f32_e32 v84, v84, v86
	v_add_f32_e32 v90, v90, v92
	v_add_f32_e32 v230, v230, v232
	v_add_f32_e32 v78, v78, v81
	v_add_f32_e32 v84, v84, v87
	v_add_f32_e32 v90, v90, v93
	v_add_f32_e32 v230, v230, v233
	v_lshlrev_b32_e32 v80, 16, v174
	v_lshlrev_b32_e32 v86, 16, v182
	v_lshlrev_b32_e32 v92, 16, v190
	v_lshlrev_b32_e32 v232, 16, v198
	v_and_b32_e32 v81, 0xffff0000, v174
	v_and_b32_e32 v87, 0xffff0000, v182
	v_and_b32_e32 v93, 0xffff0000, v190
	v_and_b32_e32 v233, 0xffff0000, v198
	v_add_f32_e32 v78, v78, v80
	v_add_f32_e32 v84, v84, v86
	v_add_f32_e32 v90, v90, v92
	v_add_f32_e32 v230, v230, v232
	v_add_f32_e32 v78, v78, v81
	v_add_f32_e32 v84, v84, v87
	v_add_f32_e32 v90, v90, v93
	v_add_f32_e32 v230, v230, v233
	v_lshlrev_b32_e32 v80, 16, v175
	v_lshlrev_b32_e32 v86, 16, v183
	v_lshlrev_b32_e32 v92, 16, v191
	v_lshlrev_b32_e32 v232, 16, v199
	v_and_b32_e32 v81, 0xffff0000, v175
	v_and_b32_e32 v87, 0xffff0000, v183
	v_and_b32_e32 v93, 0xffff0000, v191
	v_and_b32_e32 v233, 0xffff0000, v199
	v_add_f32_e32 v78, v78, v80
	v_add_f32_e32 v84, v84, v86
	v_add_f32_e32 v90, v90, v92
	v_add_f32_e32 v230, v230, v232
	v_add_f32_e32 v78, v78, v81
	v_add_f32_e32 v84, v84, v87
	v_add_f32_e32 v90, v90, v93
	v_add_f32_e32 v230, v230, v233
	v_lshlrev_b32_e32 v80, 16, v176
	v_lshlrev_b32_e32 v86, 16, v184
	v_lshlrev_b32_e32 v92, 16, v192
	v_lshlrev_b32_e32 v232, 16, v200
	v_and_b32_e32 v81, 0xffff0000, v176
	v_and_b32_e32 v87, 0xffff0000, v184
	v_and_b32_e32 v93, 0xffff0000, v192
	v_and_b32_e32 v233, 0xffff0000, v200
	v_add_f32_e32 v78, v78, v80
	v_add_f32_e32 v84, v84, v86
	v_add_f32_e32 v90, v90, v92
	v_add_f32_e32 v230, v230, v232
	v_add_f32_e32 v78, v78, v81
	v_add_f32_e32 v84, v84, v87
	v_add_f32_e32 v90, v90, v93
	v_add_f32_e32 v230, v230, v233
	v_lshlrev_b32_e32 v80, 16, v177
	v_lshlrev_b32_e32 v86, 16, v185
	v_lshlrev_b32_e32 v92, 16, v193
	v_lshlrev_b32_e32 v232, 16, v201
	v_and_b32_e32 v81, 0xffff0000, v177
	v_and_b32_e32 v87, 0xffff0000, v185
	v_and_b32_e32 v93, 0xffff0000, v193
	v_and_b32_e32 v233, 0xffff0000, v201
	v_add_f32_e32 v78, v78, v80
	v_add_f32_e32 v84, v84, v86
	v_add_f32_e32 v90, v90, v92
	v_add_f32_e32 v230, v230, v232
	v_add_f32_e32 v78, v78, v81
	v_add_f32_e32 v84, v84, v87
	v_add_f32_e32 v90, v90, v93
	v_add_f32_e32 v230, v230, v233
	v_add_f32_dpp v78, v78, v78 row_ror:8 row_mask:0xf bank_mask:0xf
	v_add_f32_dpp v84, v84, v84 row_ror:8 row_mask:0xf bank_mask:0xf
	v_add_f32_dpp v90, v90, v90 row_ror:8 row_mask:0xf bank_mask:0xf
	v_add_f32_dpp v230, v230, v230 row_ror:8 row_mask:0xf bank_mask:0xf
	v_add_f32_dpp v78, v78, v78 row_ror:4 row_mask:0xf bank_mask:0xf
	v_add_f32_dpp v84, v84, v84 row_ror:4 row_mask:0xf bank_mask:0xf
	v_add_f32_dpp v90, v90, v90 row_ror:4 row_mask:0xf bank_mask:0xf
	v_add_f32_dpp v230, v230, v230 row_ror:4 row_mask:0xf bank_mask:0xf
	v_add_f32_dpp v78, v78, v78 row_ror:2 row_mask:0xf bank_mask:0xf
	v_add_f32_dpp v84, v84, v84 row_ror:2 row_mask:0xf bank_mask:0xf
	v_add_f32_dpp v90, v90, v90 row_ror:2 row_mask:0xf bank_mask:0xf
	v_add_f32_dpp v230, v230, v230 row_ror:2 row_mask:0xf bank_mask:0xf
	v_add_f32_dpp v78, v78, v78 row_ror:1 row_mask:0xf bank_mask:0xf
	v_add_f32_dpp v84, v84, v84 row_ror:1 row_mask:0xf bank_mask:0xf
	v_add_f32_dpp v90, v90, v90 row_ror:1 row_mask:0xf bank_mask:0xf
	v_add_f32_dpp v230, v230, v230 row_ror:1 row_mask:0xf bank_mask:0xf
	v_mov_b32_e32 v80, v78
	v_mov_b32_e32 v86, v84
	v_mov_b32_e32 v92, v90
	v_mov_b32_e32 v232, v230
	v_permlane16_swap_b32_e32 v78, v80
	v_permlane16_swap_b32_e32 v84, v86
	v_permlane16_swap_b32_e32 v90, v92
	v_permlane16_swap_b32_e32 v230, v232
	v_add_f32_e32 v78, v78, v80
	v_add_f32_e32 v84, v84, v86
	v_add_f32_e32 v90, v90, v92
	v_add_f32_e32 v230, v230, v232
	v_mov_b32_e32 v80, v78
	v_mov_b32_e32 v86, v84
; __device__ __forceinline__ void gmlp_unit(LAS unsigned char* lds, const Ctx& P, int l, int unit) {
;     ...
;         const float mean = wave_sum(s) * (1.0f / 1024.0f); float q = 0.f;
; #pragma unroll
;         for (int e = 0; e < 16; ++e) q += (x[e] - mean) * (x[e] - mean);
;         const float var = wave_sum(q) * (1.0f / 1024.0f);
;         if (lane == 0) { stats[2 * t] = mean; stats[2 * t + 1] = rsqrtf(var + 1e-5f); } }
	v_mov_b32_e32 v92, v90
	v_mov_b32_e32 v232, v230
	v_permlane32_swap_b32_e32 v78, v80
	v_permlane32_swap_b32_e32 v84, v86
	v_permlane32_swap_b32_e32 v90, v92
	v_permlane32_swap_b32_e32 v230, v232
	v_add_f32_e32 v78, v78, v80
	v_add_f32_e32 v84, v84, v86
	v_add_f32_e32 v90, v90, v92
	v_add_f32_e32 v230, v230, v232
	v_lshlrev_b32_e32 v80, 16, v170
	v_lshlrev_b32_e32 v86, 16, v178
	v_lshlrev_b32_e32 v92, 16, v186
	v_lshlrev_b32_e32 v232, 16, v194
	v_and_b32_e32 v81, 0xffff0000, v170
	v_and_b32_e32 v87, 0xffff0000, v178
	v_and_b32_e32 v93, 0xffff0000, v186
	v_and_b32_e32 v233, 0xffff0000, v194
	v_fmac_f32_e32 v80, 0xba800000, v78
	v_fmac_f32_e32 v86, 0xba800000, v84
	v_fmac_f32_e32 v92, 0xba800000, v90
	v_fmac_f32_e32 v232, 0xba800000, v230
	v_fmac_f32_e32 v81, 0xba800000, v78
	v_fmac_f32_e32 v87, 0xba800000, v84
	v_fmac_f32_e32 v93, 0xba800000, v90
	v_fmac_f32_e32 v233, 0xba800000, v230
	v_mul_f32_e32 v79, v81, v81
	v_mul_f32_e32 v85, v87, v87
	v_mul_f32_e32 v91, v93, v93
	v_mul_f32_e32 v231, v233, v233
	v_fmac_f32_e32 v79, v80, v80
	v_fmac_f32_e32 v85, v86, v86
	v_fmac_f32_e32 v91, v92, v92
	v_fmac_f32_e32 v231, v232, v232
	v_lshlrev_b32_e32 v80, 16, v171
	v_lshlrev_b32_e32 v86, 16, v179
	v_lshlrev_b32_e32 v92, 16, v187
	v_lshlrev_b32_e32 v232, 16, v195
	v_and_b32_e32 v81, 0xffff0000, v171
	v_and_b32_e32 v87, 0xffff0000, v179
	v_and_b32_e32 v93, 0xffff0000, v187
	v_and_b32_e32 v233, 0xffff0000, v195
	v_fmac_f32_e32 v80, 0xba800000, v78
	v_fmac_f32_e32 v86, 0xba800000, v84
	v_fmac_f32_e32 v92, 0xba800000, v90
	v_fmac_f32_e32 v232, 0xba800000, v230
	v_fmac_f32_e32 v81, 0xba800000, v78
	v_fmac_f32_e32 v87, 0xba800000, v84
	v_fmac_f32_e32 v93, 0xba800000, v90
	v_fmac_f32_e32 v233, 0xba800000, v230
	v_fmac_f32_e32 v79, v80, v80
	v_fmac_f32_e32 v85, v86, v86
	v_fmac_f32_e32 v91, v92, v92
	v_fmac_f32_e32 v231, v232, v232
	v_fmac_f32_e32 v79, v81, v81
	v_fmac_f32_e32 v85, v87, v87
	v_fmac_f32_e32 v91, v93, v93
	v_fmac_f32_e32 v231, v233, v233
	v_lshlrev_b32_e32 v80, 16, v172
	v_lshlrev_b32_e32 v86, 16, v180
	v_lshlrev_b32_e32 v92, 16, v188
	v_lshlrev_b32_e32 v232, 16, v196
	v_and_b32_e32 v81, 0xffff0000, v172
	v_and_b32_e32 v87, 0xffff0000, v180
	v_and_b32_e32 v93, 0xffff0000, v188
	v_and_b32_e32 v233, 0xffff0000, v196
	v_fmac_f32_e32 v80, 0xba800000, v78
	v_fmac_f32_e32 v86, 0xba800000, v84
	v_fmac_f32_e32 v92, 0xba800000, v90
	v_fmac_f32_e32 v232, 0xba800000, v230
	v_fmac_f32_e32 v81, 0xba800000, v78
	v_fmac_f32_e32 v87, 0xba800000, v84
	v_fmac_f32_e32 v93, 0xba800000, v90
	v_fmac_f32_e32 v233, 0xba800000, v230
	v_fmac_f32_e32 v79, v80, v80
	v_fmac_f32_e32 v85, v86, v86
	v_fmac_f32_e32 v91, v92, v92
	v_fmac_f32_e32 v231, v232, v232
	v_fmac_f32_e32 v79, v81, v81
	v_fmac_f32_e32 v85, v87, v87
	v_fmac_f32_e32 v91, v93, v93
	v_fmac_f32_e32 v231, v233, v233
	v_lshlrev_b32_e32 v80, 16, v173
	v_lshlrev_b32_e32 v86, 16, v181
	v_lshlrev_b32_e32 v92, 16, v189
	v_lshlrev_b32_e32 v232, 16, v197
	v_and_b32_e32 v81, 0xffff0000, v173
	v_and_b32_e32 v87, 0xffff0000, v181
	v_and_b32_e32 v93, 0xffff0000, v189
	v_and_b32_e32 v233, 0xffff0000, v197
	v_fmac_f32_e32 v80, 0xba800000, v78
	v_fmac_f32_e32 v86, 0xba800000, v84
	v_fmac_f32_e32 v92, 0xba800000, v90
	v_fmac_f32_e32 v232, 0xba800000, v230
	v_fmac_f32_e32 v81, 0xba800000, v78
	v_fmac_f32_e32 v87, 0xba800000, v84
	v_fmac_f32_e32 v93, 0xba800000, v90
	v_fmac_f32_e32 v233, 0xba800000, v230
	v_fmac_f32_e32 v79, v80, v80
	v_fmac_f32_e32 v85, v86, v86
	v_fmac_f32_e32 v91, v92, v92
	v_fmac_f32_e32 v231, v232, v232
	v_fmac_f32_e32 v79, v81, v81
	v_fmac_f32_e32 v85, v87, v87
	v_fmac_f32_e32 v91, v93, v93
	v_fmac_f32_e32 v231, v233, v233
	v_lshlrev_b32_e32 v80, 16, v174
	v_lshlrev_b32_e32 v86, 16, v182
	v_lshlrev_b32_e32 v92, 16, v190
	v_lshlrev_b32_e32 v232, 16, v198
	v_and_b32_e32 v81, 0xffff0000, v174
	v_and_b32_e32 v87, 0xffff0000, v182
	v_and_b32_e32 v93, 0xffff0000, v190
	v_and_b32_e32 v233, 0xffff0000, v198
	v_fmac_f32_e32 v80, 0xba800000, v78
	v_fmac_f32_e32 v86, 0xba800000, v84
	v_fmac_f32_e32 v92, 0xba800000, v90
	v_fmac_f32_e32 v232, 0xba800000, v230
	v_fmac_f32_e32 v81, 0xba800000, v78
	v_fmac_f32_e32 v87, 0xba800000, v84
	v_fmac_f32_e32 v93, 0xba800000, v90
	v_fmac_f32_e32 v233, 0xba800000, v230
	v_fmac_f32_e32 v79, v80, v80
	v_fmac_f32_e32 v85, v86, v86
	v_fmac_f32_e32 v91, v92, v92
	v_fmac_f32_e32 v231, v232, v232
	v_fmac_f32_e32 v79, v81, v81
	v_fmac_f32_e32 v85, v87, v87
	v_fmac_f32_e32 v91, v93, v93
	v_fmac_f32_e32 v231, v233, v233
	v_lshlrev_b32_e32 v80, 16, v175
	v_lshlrev_b32_e32 v86, 16, v183
	v_lshlrev_b32_e32 v92, 16, v191
	v_lshlrev_b32_e32 v232, 16, v199
	v_and_b32_e32 v81, 0xffff0000, v175
	v_and_b32_e32 v87, 0xffff0000, v183
	v_and_b32_e32 v93, 0xffff0000, v191
	v_and_b32_e32 v233, 0xffff0000, v199
	v_fmac_f32_e32 v80, 0xba800000, v78
	v_fmac_f32_e32 v86, 0xba800000, v84
	v_fmac_f32_e32 v92, 0xba800000, v90
	v_fmac_f32_e32 v232, 0xba800000, v230
	v_fmac_f32_e32 v81, 0xba800000, v78
	v_fmac_f32_e32 v87, 0xba800000, v84
	v_fmac_f32_e32 v93, 0xba800000, v90
	v_fmac_f32_e32 v233, 0xba800000, v230
	v_fmac_f32_e32 v79, v80, v80
	v_fmac_f32_e32 v85, v86, v86
; __device__ __forceinline__ float bflo(unsigned w) { return __uint_as_float(w << 16); }
; __device__ __forceinline__ float bfhi(unsigned w) { return __uint_as_float(w & 0xffff0000u); }
; __device__ __forceinline__ void gmlp_unit(LAS unsigned char* lds, const Ctx& P, int l, int unit) {
;     ...
;     for (int r = 0; r < 16; ++r) { const int t = wid * 16 + r; const bf16_t* row = H + (tok0 + t) * LDH + C_V;
;         const u32x4 a = *(const u32x4*)(row + lane * 8), bb = *(const u32x4*)(row + 512 + lane * 8);
;         const float x[16] = {bflo(a.x), bfhi(a.x), bflo(a.y), bfhi(a.y), bflo(a.z), bfhi(a.z), bflo(a.w), bfhi(a.w), bflo(bb.x), bfhi(bb.x), bflo(bb.y), bfhi(bb.y), bflo(bb.z), bfhi(bb.z), bflo(bb.w), bfhi(bb.w)};
;         float s = 0.f;
; #pragma unroll
;         for (int e = 0; e < 16; ++e) s += x[e];
;         const float mean = wave_sum(s) * (1.0f / 1024.0f); float q = 0.f;
; #pragma unroll
;         for (int e = 0; e < 16; ++e) q += (x[e] - mean) * (x[e] - mean);
;         const float var = wave_sum(q) * (1.0f / 1024.0f);
;         if (lane == 0) { stats[2 * t] = mean; stats[2 * t + 1] = rsqrtf(var + 1e-5f); } }
	v_fmac_f32_e32 v91, v92, v92
	v_fmac_f32_e32 v231, v232, v232
	v_fmac_f32_e32 v79, v81, v81
	v_fmac_f32_e32 v85, v87, v87
	v_fmac_f32_e32 v91, v93, v93
	v_fmac_f32_e32 v231, v233, v233
	v_lshlrev_b32_e32 v80, 16, v176
	v_lshlrev_b32_e32 v86, 16, v184
	v_lshlrev_b32_e32 v92, 16, v192
	v_lshlrev_b32_e32 v232, 16, v200
	v_and_b32_e32 v81, 0xffff0000, v176
	v_and_b32_e32 v87, 0xffff0000, v184
	v_and_b32_e32 v93, 0xffff0000, v192
	v_and_b32_e32 v233, 0xffff0000, v200
	v_fmac_f32_e32 v80, 0xba800000, v78
	v_fmac_f32_e32 v86, 0xba800000, v84
	v_fmac_f32_e32 v92, 0xba800000, v90
	v_fmac_f32_e32 v232, 0xba800000, v230
	v_fmac_f32_e32 v81, 0xba800000, v78
	v_fmac_f32_e32 v87, 0xba800000, v84
	v_fmac_f32_e32 v93, 0xba800000, v90
	v_fmac_f32_e32 v233, 0xba800000, v230
	v_fmac_f32_e32 v79, v80, v80
	v_fmac_f32_e32 v85, v86, v86
	v_fmac_f32_e32 v91, v92, v92
	v_fmac_f32_e32 v231, v232, v232
	v_fmac_f32_e32 v79, v81, v81
	v_fmac_f32_e32 v85, v87, v87
	v_fmac_f32_e32 v91, v93, v93
	v_fmac_f32_e32 v231, v233, v233
	v_lshlrev_b32_e32 v80, 16, v177
	v_lshlrev_b32_e32 v86, 16, v185
	v_lshlrev_b32_e32 v92, 16, v193
	v_lshlrev_b32_e32 v232, 16, v201
	v_and_b32_e32 v81, 0xffff0000, v177
	v_and_b32_e32 v87, 0xffff0000, v185
	v_and_b32_e32 v93, 0xffff0000, v193
	v_and_b32_e32 v233, 0xffff0000, v201
	v_fmac_f32_e32 v80, 0xba800000, v78
	v_fmac_f32_e32 v86, 0xba800000, v84
	v_fmac_f32_e32 v92, 0xba800000, v90
	v_fmac_f32_e32 v232, 0xba800000, v230
	v_fmac_f32_e32 v81, 0xba800000, v78
	v_fmac_f32_e32 v87, 0xba800000, v84
	v_fmac_f32_e32 v93, 0xba800000, v90
	v_fmac_f32_e32 v233, 0xba800000, v230
	v_fmac_f32_e32 v79, v80, v80
	v_fmac_f32_e32 v85, v86, v86
	v_fmac_f32_e32 v91, v92, v92
	v_fmac_f32_e32 v231, v232, v232
	v_fmac_f32_e32 v79, v81, v81
	v_fmac_f32_e32 v85, v87, v87
	v_fmac_f32_e32 v91, v93, v93
	v_fmac_f32_e32 v231, v233, v233
	v_add_f32_dpp v79, v79, v79 row_ror:8 row_mask:0xf bank_mask:0xf
	v_add_f32_dpp v85, v85, v85 row_ror:8 row_mask:0xf bank_mask:0xf
	v_add_f32_dpp v91, v91, v91 row_ror:8 row_mask:0xf bank_mask:0xf
	v_add_f32_dpp v231, v231, v231 row_ror:8 row_mask:0xf bank_mask:0xf
	v_add_f32_dpp v79, v79, v79 row_ror:4 row_mask:0xf bank_mask:0xf
	v_add_f32_dpp v85, v85, v85 row_ror:4 row_mask:0xf bank_mask:0xf
	v_add_f32_dpp v91, v91, v91 row_ror:4 row_mask:0xf bank_mask:0xf
	v_add_f32_dpp v231, v231, v231 row_ror:4 row_mask:0xf bank_mask:0xf
	v_add_f32_dpp v79, v79, v79 row_ror:2 row_mask:0xf bank_mask:0xf
	v_add_f32_dpp v85, v85, v85 row_ror:2 row_mask:0xf bank_mask:0xf
	v_add_f32_dpp v91, v91, v91 row_ror:2 row_mask:0xf bank_mask:0xf
	v_add_f32_dpp v231, v231, v231 row_ror:2 row_mask:0xf bank_mask:0xf
	v_add_f32_dpp v79, v79, v79 row_ror:1 row_mask:0xf bank_mask:0xf
	v_add_f32_dpp v85, v85, v85 row_ror:1 row_mask:0xf bank_mask:0xf
	v_add_f32_dpp v91, v91, v91 row_ror:1 row_mask:0xf bank_mask:0xf
	v_add_f32_dpp v231, v231, v231 row_ror:1 row_mask:0xf bank_mask:0xf
	v_mov_b32_e32 v80, v79
	v_mov_b32_e32 v86, v85
	v_mov_b32_e32 v92, v91
	v_mov_b32_e32 v232, v231
	v_permlane16_swap_b32_e32 v79, v80
	v_permlane16_swap_b32_e32 v85, v86
	v_permlane16_swap_b32_e32 v91, v92
	v_permlane16_swap_b32_e32 v231, v232
	v_add_f32_e32 v79, v79, v80
	v_add_f32_e32 v85, v85, v86
	v_add_f32_e32 v91, v91, v92
	v_add_f32_e32 v231, v231, v232
	v_mov_b32_e32 v80, v79
	v_mov_b32_e32 v86, v85
	v_mov_b32_e32 v92, v91
	v_mov_b32_e32 v232, v231
	v_permlane32_swap_b32_e32 v79, v80
	v_permlane32_swap_b32_e32 v85, v86
	v_permlane32_swap_b32_e32 v91, v92
	v_permlane32_swap_b32_e32 v231, v232
	v_add_f32_e32 v79, v79, v80
	v_add_f32_e32 v85, v85, v86
	v_add_f32_e32 v91, v91, v92
	v_add_f32_e32 v231, v231, v232
	v_fmamk_f32 v79, v79, 0x3a800000, v236
	v_mul_f32_e32 v80, 0x4b800000, v79
	v_cmp_gt_f32_e32 vcc, s81, v79
	v_mul_f32_e32 v78, 0x3a800000, v78
	s_nop 0
	v_cndmask_b32_e32 v79, v79, v80, vcc
	v_rsq_f32_e32 v79, v79
	s_nop 0
	v_mul_f32_e32 v80, 0x45800000, v79
	v_cndmask_b32_e32 v79, v79, v80, vcc
	v_fmamk_f32 v85, v85, 0x3a800000, v236
	v_mul_f32_e32 v86, 0x4b800000, v85
	v_cmp_gt_f32_e32 vcc, s81, v85
	v_mul_f32_e32 v84, 0x3a800000, v84
	s_nop 0
	v_cndmask_b32_e32 v85, v85, v86, vcc
	v_rsq_f32_e32 v85, v85
	s_nop 0
	v_mul_f32_e32 v86, 0x45800000, v85
	v_cndmask_b32_e32 v85, v85, v86, vcc
	v_fmamk_f32 v91, v91, 0x3a800000, v236
	v_mul_f32_e32 v92, 0x4b800000, v91
	v_cmp_gt_f32_e32 vcc, s81, v91
	v_mul_f32_e32 v90, 0x3a800000, v90
	s_nop 0
	v_cndmask_b32_e32 v91, v91, v92, vcc
	v_rsq_f32_e32 v91, v91
	s_nop 0
	v_mul_f32_e32 v92, 0x45800000, v91
	v_cndmask_b32_e32 v91, v91, v92, vcc
	v_fmamk_f32 v231, v231, 0x3a800000, v236
	v_mul_f32_e32 v232, 0x4b800000, v231
	v_cmp_gt_f32_e32 vcc, s81, v231
	v_mul_f32_e32 v230, 0x3a800000, v230
	s_nop 0
	v_cndmask_b32_e32 v231, v231, v232, vcc
	v_rsq_f32_e32 v231, v231
	s_nop 0
	v_mul_f32_e32 v232, 0x45800000, v231
	v_cndmask_b32_e32 v231, v231, v232, vcc
	s_and_saveexec_b64 s[14:15], s[6:7]
	ds_write_b64 v15, v[78:79] offset:96
	ds_write_b64 v15, v[84:85] offset:104
	ds_write_b64 v15, v[90:91] offset:112
	ds_write_b64 v15, v[230:231] offset:120
	s_or_b64 exec, exec, s[14:15]

; __device__ __forceinline__ unsigned cvt_pk_bf16(float lo, float hi) { unsigned r; asm("v_cvt_pk_bf16_f32 %0, %1, %2" : "=v"(r) : "v"(lo), "v"(hi)); return r; }
; __device__ __forceinline__ float bflo(unsigned w) { return __uint_as_float(w << 16); }
; __device__ __forceinline__ float bfhi(unsigned w) { return __uint_as_float(w & 0xffff0000u); }
; __device__ __forceinline__ void gmlp_unit(LAS unsigned char* lds, const Ctx& P, int l, int unit) {
;     ...
;         { const int t = 16 * wid + c; const size_t tok = tok0 + t; const float bs = sgb[g * 128 + t];
; #pragma unroll
;             for (int nt = 0; nt < 8; ++nt) { const int ch0 = g * 128 + 16 * nt + 4 * i;
;                 const u32x2 uu = *(const u32x2*)(H + tok * LDH + C_U + ch0), gg = *(const u32x2*)(H + tok * LDH + C_GA + ch0);
;                 u32x2 w; w.x = cvt_pk_bf16((acc[nt][0] + bs) * bflo(uu.x) * bflo(gg.x), (acc[nt][1] + bs) * bfhi(uu.x) * bfhi(gg.x));
;                 w.y = cvt_pk_bf16((acc[nt][2] + bs) * bflo(uu.y) * bflo(gg.y), (acc[nt][3] + bs) * bfhi(uu.y) * bfhi(gg.y));
;                 *(u32x2*)(O + tok * DBR + ch0) = w; } }
.LBB0_798:
	s_or_b64 exec, exec, s[16:17]
	v_or_b32_e32 v0, s26, v39
	v_lshl_add_u64 v[48:49], v[48:49], 2, s[14:15]
	v_lshlrev_b32_e32 v0, 1, v0
	global_load_dword v50, v[48:49], off
	v_lshl_add_u64 v[48:49], v[42:43], 0, v[0:1]
	global_load_dwordx2 v[56:57], v[48:49], off
	v_lshl_add_u64 v[58:59], v[44:45], 0, v[0:1]
	global_load_dwordx2 v[58:59], v[58:59], off
	v_lshl_add_u64 v[62:63], v[44:45], 0, v[0:1]
	global_load_dwordx2 v[64:65], v[48:49], off offset:32
	global_load_dwordx2 v[66:67], v[62:63], off offset:32
	global_load_dwordx2 v[68:69], v[48:49], off offset:64
	global_load_dwordx2 v[70:71], v[62:63], off offset:64
	global_load_dwordx2 v[72:73], v[48:49], off offset:96
	global_load_dwordx2 v[74:75], v[62:63], off offset:96
	global_load_dwordx2 v[76:77], v[48:49], off offset:128
	global_load_dwordx2 v[78:79], v[62:63], off offset:128
	global_load_dwordx2 v[80:81], v[48:49], off offset:160
	global_load_dwordx2 v[82:83], v[62:63], off offset:160
	global_load_dwordx2 v[84:85], v[48:49], off offset:192
	global_load_dwordx2 v[86:87], v[62:63], off offset:192
	global_load_dwordx2 v[88:89], v[48:49], off offset:224
	global_load_dwordx2 v[90:91], v[62:63], off offset:224
	s_add_i32 s25, s25, 1
	s_cmp_eq_u32 s25, 4
	s_waitcnt vmcnt(16)
	v_add_f32_e32 v30, v50, v30
	v_add_f32_e32 v31, v50, v31
	s_waitcnt vmcnt(15)
	v_lshlrev_b32_e32 v51, 16, v56
	v_mul_f32_e32 v30, v30, v51
	s_waitcnt vmcnt(14)
	v_lshlrev_b32_e32 v51, 16, v58
	v_mul_f32_e32 v30, v30, v51
	v_and_b32_e32 v51, 0xffff0000, v56
	v_mul_f32_e32 v31, v31, v51
	v_and_b32_e32 v51, 0xffff0000, v58
	v_mul_f32_e32 v31, v31, v51
	v_cvt_pk_bf16_f32 v56, v30, v31
	v_add_f32_e32 v30, v50, v32
	v_lshlrev_b32_e32 v31, 16, v57
	v_mul_f32_e32 v30, v30, v31
	v_lshlrev_b32_e32 v31, 16, v59
	v_mul_f32_e32 v30, v30, v31
	v_add_f32_e32 v31, v50, v33
	v_and_b32_e32 v32, 0xffff0000, v57
	v_mul_f32_e32 v31, v31, v32
	v_and_b32_e32 v32, 0xffff0000, v59
	v_mul_f32_e32 v31, v31, v32
	v_cvt_pk_bf16_f32 v57, v30, v31
	v_lshl_add_u64 v[30:31], v[46:47], 0, v[0:1]
	global_store_dwordx2 v[30:31], v[56:57], off
	v_or_b32_e32 v56, 32, v0
	v_mov_b32_e32 v57, v1
	s_waitcnt vmcnt(13)
	v_mov_b64_e32 v[32:33], v[64:65]
	v_lshl_add_u64 v[56:57], v[44:45], 0, v[56:57]
	v_mov_b64_e32 v[56:57], v[66:67]
	v_add_f32_e32 v26, v26, v50
	v_add_f32_e32 v27, v27, v50
	v_add_f32_e32 v22, v22, v50
	v_add_f32_e32 v23, v23, v50
	v_add_f32_e32 v18, v18, v50
	v_add_f32_e32 v19, v19, v50
	v_add_f32_e32 v14, v14, v50
	v_add_f32_e32 v15, v15, v50
	v_add_f32_e32 v10, v10, v50
	v_add_f32_e32 v11, v11, v50
	v_add_f32_e32 v6, v6, v50
	v_add_f32_e32 v7, v7, v50
	v_lshlrev_b32_e32 v51, 16, v32
	v_and_b32_e32 v32, 0xffff0000, v32
	v_mul_f32_e32 v26, v26, v51
	v_lshlrev_b32_e32 v51, 16, v56
	v_mul_f32_e32 v27, v27, v32
	v_and_b32_e32 v32, 0xffff0000, v56
	v_mul_f32_e32 v26, v26, v51
	v_mul_f32_e32 v27, v27, v32
	v_cvt_pk_bf16_f32 v26, v26, v27
	v_add_f32_e32 v27, v28, v50
	v_lshlrev_b32_e32 v28, 16, v33
	v_mul_f32_e32 v27, v27, v28
	v_lshlrev_b32_e32 v28, 16, v57
	v_mul_f32_e32 v27, v27, v28
	v_add_f32_e32 v28, v29, v50
	v_and_b32_e32 v29, 0xffff0000, v33
	v_mul_f32_e32 v28, v28, v29
	v_and_b32_e32 v29, 0xffff0000, v57
	v_mul_f32_e32 v28, v28, v29
	v_cvt_pk_bf16_f32 v27, v27, v28
	global_store_dwordx2 v[30:31], v[26:27], off offset:32
	v_or_b32_e32 v28, 64, v0
	v_mov_b32_e32 v29, v1
	s_waitcnt vmcnt(12)
	v_mov_b64_e32 v[26:27], v[68:69]
	v_lshl_add_u64 v[28:29], v[44:45], 0, v[28:29]
	v_mov_b64_e32 v[28:29], v[70:71]
	v_lshlrev_b32_e32 v32, 16, v26
	v_and_b32_e32 v26, 0xffff0000, v26
	v_mul_f32_e32 v22, v22, v32
	v_lshlrev_b32_e32 v32, 16, v28
	v_mul_f32_e32 v23, v23, v26
	v_and_b32_e32 v26, 0xffff0000, v28
	v_mul_f32_e32 v22, v22, v32
	v_mul_f32_e32 v23, v23, v26
	v_cvt_pk_bf16_f32 v22, v22, v23
	v_add_f32_e32 v23, v24, v50
	v_lshlrev_b32_e32 v24, 16, v27
	v_mul_f32_e32 v23, v23, v24
	v_lshlrev_b32_e32 v24, 16, v29
	v_mul_f32_e32 v23, v23, v24
	v_add_f32_e32 v24, v25, v50
	v_and_b32_e32 v25, 0xffff0000, v27
	v_mul_f32_e32 v24, v24, v25
	v_and_b32_e32 v25, 0xffff0000, v29
	v_mul_f32_e32 v24, v24, v25
	v_cvt_pk_bf16_f32 v23, v23, v24
	global_store_dwordx2 v[30:31], v[22:23], off offset:64
	v_or_b32_e32 v24, 0x60, v0
	v_mov_b32_e32 v25, v1
	s_waitcnt vmcnt(11)
; __device__ __forceinline__ unsigned cvt_pk_bf16(float lo, float hi) { unsigned r; asm("v_cvt_pk_bf16_f32 %0, %1, %2" : "=v"(r) : "v"(lo), "v"(hi)); return r; }
; __device__ __forceinline__ float bflo(unsigned w) { return __uint_as_float(w << 16); }
; __device__ __forceinline__ float bfhi(unsigned w) { return __uint_as_float(w & 0xffff0000u); }
; __device__ __forceinline__ void gmlp_unit(LAS unsigned char* lds, const Ctx& P, int l, int unit) {
;     ...
;         { const int t = 16 * wid + c; const size_t tok = tok0 + t; const float bs = sgb[g * 128 + t];
; #pragma unroll
;             for (int nt = 0; nt < 8; ++nt) { const int ch0 = g * 128 + 16 * nt + 4 * i;
;                 const u32x2 uu = *(const u32x2*)(H + tok * LDH + C_U + ch0), gg = *(const u32x2*)(H + tok * LDH + C_GA + ch0);
;                 u32x2 w; w.x = cvt_pk_bf16((acc[nt][0] + bs) * bflo(uu.x) * bflo(gg.x), (acc[nt][1] + bs) * bfhi(uu.x) * bfhi(gg.x));
;                 w.y = cvt_pk_bf16((acc[nt][2] + bs) * bflo(uu.y) * bflo(gg.y), (acc[nt][3] + bs) * bfhi(uu.y) * bfhi(gg.y));
;                 *(u32x2*)(O + tok * DBR + ch0) = w; } }
;         __syncthreads();
	v_mov_b64_e32 v[22:23], v[72:73]
	v_lshl_add_u64 v[24:25], v[44:45], 0, v[24:25]
	v_mov_b64_e32 v[24:25], v[74:75]
	v_lshlrev_b32_e32 v26, 16, v22
	v_and_b32_e32 v22, 0xffff0000, v22
	v_mul_f32_e32 v18, v18, v26
	v_lshlrev_b32_e32 v26, 16, v24
	v_mul_f32_e32 v19, v19, v22
	v_and_b32_e32 v22, 0xffff0000, v24
	v_mul_f32_e32 v18, v18, v26
	v_mul_f32_e32 v19, v19, v22
	v_cvt_pk_bf16_f32 v18, v18, v19
	v_add_f32_e32 v19, v20, v50
	v_lshlrev_b32_e32 v20, 16, v23
	v_mul_f32_e32 v19, v19, v20
	v_lshlrev_b32_e32 v20, 16, v25
	v_mul_f32_e32 v19, v19, v20
	v_add_f32_e32 v20, v21, v50
	v_and_b32_e32 v21, 0xffff0000, v23
	v_mul_f32_e32 v20, v20, v21
	v_and_b32_e32 v21, 0xffff0000, v25
	v_mul_f32_e32 v20, v20, v21
	v_cvt_pk_bf16_f32 v19, v19, v20
	global_store_dwordx2 v[30:31], v[18:19], off offset:96
	v_or_b32_e32 v20, 0x80, v0
	v_mov_b32_e32 v21, v1
	s_waitcnt vmcnt(10)
	v_mov_b64_e32 v[18:19], v[76:77]
	v_lshl_add_u64 v[20:21], v[44:45], 0, v[20:21]
	v_mov_b64_e32 v[20:21], v[78:79]
	v_lshlrev_b32_e32 v22, 16, v18
	v_and_b32_e32 v18, 0xffff0000, v18
	v_mul_f32_e32 v14, v14, v22
	v_lshlrev_b32_e32 v22, 16, v20
	v_mul_f32_e32 v15, v15, v18
	v_and_b32_e32 v18, 0xffff0000, v20
	v_mul_f32_e32 v14, v14, v22
	v_mul_f32_e32 v15, v15, v18
	v_cvt_pk_bf16_f32 v14, v14, v15
	v_add_f32_e32 v15, v16, v50
	v_lshlrev_b32_e32 v16, 16, v19
	v_mul_f32_e32 v15, v15, v16
	v_lshlrev_b32_e32 v16, 16, v21
	v_mul_f32_e32 v15, v15, v16
	v_add_f32_e32 v16, v17, v50
	v_and_b32_e32 v17, 0xffff0000, v19
	v_mul_f32_e32 v16, v16, v17
	v_and_b32_e32 v17, 0xffff0000, v21
	v_mul_f32_e32 v16, v16, v17
	v_cvt_pk_bf16_f32 v15, v15, v16
	global_store_dwordx2 v[30:31], v[14:15], off offset:128
	v_or_b32_e32 v16, 0xa0, v0
	v_mov_b32_e32 v17, v1
	s_waitcnt vmcnt(9)
	v_mov_b64_e32 v[14:15], v[80:81]
	v_lshl_add_u64 v[16:17], v[44:45], 0, v[16:17]
	v_mov_b64_e32 v[16:17], v[82:83]
	v_lshlrev_b32_e32 v18, 16, v14
	v_and_b32_e32 v14, 0xffff0000, v14
	v_mul_f32_e32 v10, v10, v18
	v_lshlrev_b32_e32 v18, 16, v16
	v_mul_f32_e32 v11, v11, v14
	v_and_b32_e32 v14, 0xffff0000, v16
	v_mul_f32_e32 v10, v10, v18
	v_mul_f32_e32 v11, v11, v14
	v_cvt_pk_bf16_f32 v10, v10, v11
	v_add_f32_e32 v11, v12, v50
	v_lshlrev_b32_e32 v12, 16, v15
	v_mul_f32_e32 v11, v11, v12
	v_lshlrev_b32_e32 v12, 16, v17
	v_mul_f32_e32 v11, v11, v12
	v_add_f32_e32 v12, v13, v50
	v_and_b32_e32 v13, 0xffff0000, v15
	v_mul_f32_e32 v12, v12, v13
	v_and_b32_e32 v13, 0xffff0000, v17
	v_mul_f32_e32 v12, v12, v13
	v_cvt_pk_bf16_f32 v11, v11, v12
	global_store_dwordx2 v[30:31], v[10:11], off offset:160
	v_or_b32_e32 v12, 0xc0, v0
	v_mov_b32_e32 v13, v1
	s_waitcnt vmcnt(8)
	v_mov_b64_e32 v[10:11], v[84:85]
	v_lshl_add_u64 v[12:13], v[44:45], 0, v[12:13]
	v_mov_b64_e32 v[12:13], v[86:87]
	v_or_b32_e32 v0, 0xe0, v0
	v_lshlrev_b32_e32 v14, 16, v10
	v_and_b32_e32 v10, 0xffff0000, v10
	v_mul_f32_e32 v6, v6, v14
	v_lshlrev_b32_e32 v14, 16, v12
	v_mul_f32_e32 v7, v7, v10
	v_and_b32_e32 v10, 0xffff0000, v12
	v_mul_f32_e32 v6, v6, v14
	v_mul_f32_e32 v7, v7, v10
	v_cvt_pk_bf16_f32 v6, v6, v7
	v_add_f32_e32 v7, v8, v50
	v_lshlrev_b32_e32 v8, 16, v11
	v_mul_f32_e32 v7, v7, v8
	v_lshlrev_b32_e32 v8, 16, v13
	v_mul_f32_e32 v7, v7, v8
	v_add_f32_e32 v8, v9, v50
	v_and_b32_e32 v9, 0xffff0000, v11
	v_mul_f32_e32 v8, v8, v9
	v_and_b32_e32 v9, 0xffff0000, v13
	v_mul_f32_e32 v8, v8, v9
	v_cvt_pk_bf16_f32 v7, v7, v8
	global_store_dwordx2 v[30:31], v[6:7], off offset:192
	s_waitcnt vmcnt(7)
	v_mov_b64_e32 v[6:7], v[88:89]
	v_lshl_add_u64 v[8:9], v[44:45], 0, v[0:1]
	v_mov_b64_e32 v[8:9], v[90:91]
	v_add_f32_e32 v0, v2, v50
	v_lshlrev_b32_e32 v2, 16, v6
	v_mul_f32_e32 v0, v0, v2
	v_lshlrev_b32_e32 v2, 16, v8
	v_mul_f32_e32 v0, v0, v2
	v_add_f32_e32 v2, v3, v50
	v_and_b32_e32 v3, 0xffff0000, v6
	v_mul_f32_e32 v2, v2, v3
	v_and_b32_e32 v3, 0xffff0000, v8
	v_mul_f32_e32 v2, v2, v3
	v_cvt_pk_bf16_f32 v2, v0, v2
	v_add_f32_e32 v0, v4, v50
	v_lshlrev_b32_e32 v3, 16, v7
	v_mul_f32_e32 v0, v0, v3
	v_lshlrev_b32_e32 v3, 16, v9
	v_mul_f32_e32 v0, v0, v3
	v_add_f32_e32 v3, v5, v50
	v_and_b32_e32 v4, 0xffff0000, v7
	v_mul_f32_e32 v3, v3, v4
	v_and_b32_e32 v4, 0xffff0000, v9
	v_mul_f32_e32 v3, v3, v4
	v_cvt_pk_bf16_f32 v3, v0, v3
	global_store_dwordx2 v[30:31], v[2:3], off offset:224
	s_barrier
	s_cbranch_scc1 .LBB0_790
